# GEMM compute-segment heads: removed the compiler's lgkmcnt(0) that duplicates the asm lgkmcnt(0) before the barrier (52 sites), one issue slot less between barrier release and first MFMA
# speedup vs baseline: 1.0088x; 1.0018x over previous
;     __device__ bool next(int i, Unit& u) const { if (!b.next(i >> 1, u)) return false; u.half = i & 1; u.koff = (i & 1) * kbytes; return true; }
; #define PG8_STAGE(bufoff, gbase, voff) do { _Pragma("unroll") for (int _i = 0; _i < 2; ++_i) \
;         __builtin_amdgcn_global_load_lds((const unsigned*)((const char*)(gbase) + (voff)[_i]), (LAS unsigned*)(lds + (bufoff) + ldsw + _i * 8192), 16, 0, 0); } while (0)
; #define PG8_LDA(dst, b, h) do { _Pragma("unroll") for (int m = 0; m < 4; ++m) _Pragma("unroll") for (int k = 0; k < 2; ++k) dst[m][k] = *(const LAS bf16x8*)(lds + PG8_SA(b, h) + aoff + m * 2048 + k * 1024); } while (0)
; #define PG8_LDB(dst, b, h) do { _Pragma("unroll") for (int n = 0; n < 2; ++n) _Pragma("unroll") for (int k = 0; k < 2; ++k) dst[n][k] = *(const LAS bf16x8*)(lds + PG8_SB(b, h) + boff + n * 2048 + k * 1024); } while (0)
; #define PG8_WAIT_V(n) asm volatile("s_waitcnt vmcnt(" #n ")" ::: "memory")
; #define PG8_WAIT_L(n) asm volatile("s_waitcnt lgkmcnt(" #n ")" ::: "memory")
; #define PG8_BAR __builtin_amdgcn_s_barrier()
; #define PG8_SCHED __builtin_amdgcn_sched_barrier(0)
; template <class Epi, class Sched>
; __device__ __forceinline__ void gemm_phase(LAS unsigned char* lds, const Gemm g, const Sched& S, const Epi& E, int tid_in) {
;     ...
;         const bool has_next = S.next(ui + 1, nxt);
;         const char* nA = has_next ? (const char*)g.A + (size_t)nxt.pm * tstep + nxt.koff : cA; const char* nB = has_next ? (const char*)g.Bt + (size_t)nxt.pn * tstep + nxt.koff : cB;
;         for (int t = 0; t < nt; t += 2) {
;             const bool last = (t == nt - 2);
;             const char* a1 = cA + (size_t)(t + 1) * kstep;
;             const char* a2 = last ? nA : cA + (size_t)(t + 2) * kstep; const char* b2 = last ? nB : cB + (size_t)(t + 2) * kstep;
;             const char* a3 = a2 + kstep; const char* b3 = b2 + kstep;
;             PG8_LDB(B0, 0, 0); PG8_LDB(B1, 0, 1); PG8_SCHED; PG8_LDA(At, 0, 0); PG8_STAGE(PG8_SA(1, 0), a1, voffA); PG8_STAGE(PG8_SA(1, 1), a1 + hstep, voffA);
;             PG8_WAIT_V(8); PG8_WAIT_L(0); PG8_BAR; PG8_MMA(0, 0, At, B0); PG8_MMA(0, 1, At, B1); PG8_BAR; PG8_SCHED;
;             PG8_LDA(At, 0, 1); PG8_STAGE(PG8_SB(0, 0), b2, voffB); PG8_STAGE(PG8_SB(0, 1), b2 + hstep, voffB);
;             PG8_WAIT_V(6); PG8_WAIT_L(0); PG8_BAR; PG8_MMA(1, 0, At, B0); PG8_MMA(1, 1, At, B1); PG8_BAR; PG8_SCHED;
.LBB0_101:
	s_ashr_i32 s31, s30, 31
	s_lshl_b64 s[34:35], s[30:31], 20
	s_add_u32 s34, s58, s34
	s_addc_u32 s35, s59, s35
	s_and_b64 s[36:37], s[0:1], exec
	s_cselect_b32 s31, s35, s43
	s_cselect_b32 s39, s34, s42
	s_ashr_i32 s29, s28, 31
	s_lshl_b64 s[36:37], s[28:29], 20
	s_add_u32 s36, s56, s36
	s_addc_u32 s37, s57, s37
	s_and_b64 s[46:47], s[0:1], exec
	s_cselect_b32 s29, s37, s45
	s_cselect_b32 s41, s36, s44
	s_add_u32 s94, s44, 0x100
	s_addc_u32 s95, s45, 0
	s_mov_b32 s96, -2
	s_mov_b64 s[44:45], 0
	v_lshl_add_u64 v[128:129], s[42:43], 0, v[158:159]
	v_lshl_add_u64 v[130:131], s[42:43], 0, v[160:161]
	ds_read_b128 v[132:135], v179
	ds_read_b128 v[136:139], v179 offset:1024
	ds_read_b128 v[140:143], v179 offset:2048
	ds_read_b128 v[172:175], v179 offset:3072
	ds_read_b128 v[188:191], v180
	ds_read_b128 v[192:195], v180 offset:1024
	ds_read_b128 v[196:199], v180 offset:2048
	ds_read_b128 v[200:203], v180 offset:3072
	s_add_u32 s46, s42, s44
	s_addc_u32 s47, s43, s45
	s_add_u32 s48, s46, 0x100
	s_addc_u32 s49, s47, 0
	s_add_u32 s46, s94, s44
	s_addc_u32 s47, s95, s45
	s_cmpk_eq_i32 s44, 0xf00
	s_cselect_b32 s47, s29, s47
	s_cselect_b32 s46, s41, s46
	s_cselect_b32 s49, s31, s49
	s_cselect_b32 s48, s39, s48
	v_lshl_add_u64 v[168:169], v[130:131], 0, s[44:45]
	v_lshl_add_u64 v[176:177], v[168:169], 0, s[10:11]
	s_add_i32 m0, s60, 0x8000
	ds_read_b128 v[204:207], v181
	ds_read_b128 v[208:211], v181 offset:1024
	ds_read_b128 v[212:215], v181 offset:2048
	ds_read_b128 v[216:219], v181 offset:3072
	ds_read_b128 v[220:223], v181 offset:4096
	ds_read_b128 v[224:227], v181 offset:5120
	ds_read_b128 v[228:231], v181 offset:6144
	ds_read_b128 v[232:235], v181 offset:7168
	global_load_lds_dwordx4 v[176:177], off
	v_lshl_add_u64 v[176:177], v[128:129], 0, s[44:45]
	v_lshl_add_u64 v[184:185], v[176:177], 0, s[10:11]
	s_add_i32 m0, s60, 0xa000
	v_lshl_add_u64 v[168:169], v[168:169], 0, s[12:13]
	global_load_lds_dwordx4 v[184:185], off
	s_add_i32 m0, s60, 0xc000
	s_nop 0
	global_load_lds_dwordx4 v[168:169], off
	v_lshl_add_u64 v[168:169], v[176:177], 0, s[12:13]
	s_add_i32 m0, s60, 0xe000
	s_nop 0
	global_load_lds_dwordx4 v[168:169], off
	s_waitcnt vmcnt(8)
	s_waitcnt lgkmcnt(0)
	s_barrier
	s_setprio 3
	v_mfma_f32_16x16x32_bf16 v[124:127], v[132:135], v[204:207], 0
	v_mfma_f32_16x16x32_bf16 v[120:123], v[140:143], v[204:207], 0
	v_mfma_f32_16x16x32_bf16 v[108:111], v[132:135], v[212:215], 0
	v_mfma_f32_16x16x32_bf16 v[104:107], v[140:143], v[212:215], 0
	v_mfma_f32_16x16x32_bf16 v[92:95], v[132:135], v[220:223], 0
	v_mfma_f32_16x16x32_bf16 v[88:91], v[140:143], v[220:223], 0
	v_mfma_f32_16x16x32_bf16 v[76:79], v[132:135], v[228:231], 0
	v_mfma_f32_16x16x32_bf16 v[72:75], v[140:143], v[228:231], 0
	v_mfma_f32_16x16x32_bf16 v[124:127], v[136:139], v[208:211], v[124:127]
	v_mfma_f32_16x16x32_bf16 v[120:123], v[172:175], v[208:211], v[120:123]
	v_mfma_f32_16x16x32_bf16 v[108:111], v[136:139], v[216:219], v[108:111]
	v_mfma_f32_16x16x32_bf16 v[104:107], v[172:175], v[216:219], v[104:107]
	v_mfma_f32_16x16x32_bf16 v[92:95], v[136:139], v[224:227], v[92:95]
	v_mfma_f32_16x16x32_bf16 v[88:91], v[172:175], v[224:227], v[88:91]
	v_mfma_f32_16x16x32_bf16 v[76:79], v[136:139], v[232:235], v[76:79]
	v_mfma_f32_16x16x32_bf16 v[72:75], v[172:175], v[232:235], v[72:75]
	s_setprio 0
	s_setprio 3
	v_mfma_f32_16x16x32_bf16 v[116:119], v[188:191], v[204:207], 0
	v_mfma_f32_16x16x32_bf16 v[112:115], v[196:199], v[204:207], 0
	v_mfma_f32_16x16x32_bf16 v[100:103], v[188:191], v[212:215], 0
	v_mfma_f32_16x16x32_bf16 v[96:99], v[196:199], v[212:215], 0
	v_mfma_f32_16x16x32_bf16 v[84:87], v[188:191], v[220:223], 0
	v_mfma_f32_16x16x32_bf16 v[80:83], v[196:199], v[220:223], 0
	v_mfma_f32_16x16x32_bf16 v[68:71], v[188:191], v[228:231], 0
	v_mfma_f32_16x16x32_bf16 v[64:67], v[196:199], v[228:231], 0
	v_mfma_f32_16x16x32_bf16 v[116:119], v[192:195], v[208:211], v[116:119]
	v_mfma_f32_16x16x32_bf16 v[112:115], v[200:203], v[208:211], v[112:115]
	v_mfma_f32_16x16x32_bf16 v[100:103], v[192:195], v[216:219], v[100:103]
	v_mfma_f32_16x16x32_bf16 v[96:99], v[200:203], v[216:219], v[96:99]
	v_mfma_f32_16x16x32_bf16 v[84:87], v[192:195], v[224:227], v[84:87]
	v_mfma_f32_16x16x32_bf16 v[80:83], v[200:203], v[224:227], v[80:83]
	v_mfma_f32_16x16x32_bf16 v[68:71], v[192:195], v[232:235], v[68:71]
	v_mfma_f32_16x16x32_bf16 v[64:67], v[200:203], v[232:235], v[64:67]
	s_setprio 0
	s_barrier
	s_add_i32 s97, s66, s2
	v_lshl_add_u64 v[168:169], s[46:47], 0, v[148:149]
	s_mov_b32 m0, s97
	ds_read_b128 v[204:207], v181 offset:16384
	ds_read_b128 v[208:211], v181 offset:17408
	ds_read_b128 v[212:215], v181 offset:18432
	ds_read_b128 v[216:219], v181 offset:19456
	ds_read_b128 v[220:223], v181 offset:20480
	ds_read_b128 v[224:227], v181 offset:21504
	ds_read_b128 v[228:231], v181 offset:22528
	ds_read_b128 v[232:235], v181 offset:23552
	global_load_lds_dwordx4 v[168:169], off
	s_add_i32 m0, s97, 0x2000
	s_add_u32 vcc_lo, s46, 0x80000
	v_lshl_add_u64 v[176:177], s[46:47], 0, v[144:145]
	s_addc_u32 vcc_hi, s47, 0
	s_add_i32 s97, s67, s2
	global_load_lds_dwordx4 v[176:177], off
	v_lshl_add_u64 v[184:185], vcc, 0, v[148:149]
	s_mov_b32 m0, s97
	s_nop 0
	global_load_lds_dwordx4 v[184:185], off
	v_lshl_add_u64 v[184:185], vcc, 0, v[144:145]
	s_add_i32 m0, s97, 0x2000
	s_nop 0
	global_load_lds_dwordx4 v[184:185], off
	s_waitcnt vmcnt(6)
	s_waitcnt lgkmcnt(0)
	s_barrier
; #define PG8_STAGE(bufoff, gbase, voff) do { _Pragma("unroll") for (int _i = 0; _i < 2; ++_i) \
;         __builtin_amdgcn_global_load_lds((const unsigned*)((const char*)(gbase) + (voff)[_i]), (LAS unsigned*)(lds + (bufoff) + ldsw + _i * 8192), 16, 0, 0); } while (0)
; #define PG8_LDA(dst, b, h) do { _Pragma("unroll") for (int m = 0; m < 4; ++m) _Pragma("unroll") for (int k = 0; k < 2; ++k) dst[m][k] = *(const LAS bf16x8*)(lds + PG8_SA(b, h) + aoff + m * 2048 + k * 1024); } while (0)
; #define PG8_LDB(dst, b, h) do { _Pragma("unroll") for (int n = 0; n < 2; ++n) _Pragma("unroll") for (int k = 0; k < 2; ++k) dst[n][k] = *(const LAS bf16x8*)(lds + PG8_SB(b, h) + boff + n * 2048 + k * 1024); } while (0)
; #define PG8_MMA(ai, bj, At, Bt) do { __builtin_amdgcn_s_setprio(3); _Pragma("unroll") for (int m = 0; m < 4; ++m) _Pragma("unroll") for (int n = 0; n < 2; ++n) _Pragma("unroll") for (int k = 0; k < 2; ++k) \
;         acc[ai][bj][m][n] = __builtin_amdgcn_mfma_f32_16x16x32_bf16(Bt[n][k], At[m][k], acc[ai][bj][m][n], 0, 0, 0); __builtin_amdgcn_s_setprio(0); } while (0)
; #define PG8_WAIT_V(n) asm volatile("s_waitcnt vmcnt(" #n ")" ::: "memory")
; #define PG8_WAIT_L(n) asm volatile("s_waitcnt lgkmcnt(" #n ")" ::: "memory")
; #define PG8_BAR __builtin_amdgcn_s_barrier()
; #define PG8_SCHED __builtin_amdgcn_sched_barrier(0)
; template <class Epi, class Sched>
; __device__ __forceinline__ void gemm_phase(LAS unsigned char* lds, const Gemm g, const Sched& S, const Epi& E, int tid_in) {
;     ...
;             PG8_WAIT_V(6); PG8_WAIT_L(0); PG8_BAR; PG8_MMA(1, 0, At, B0); PG8_MMA(1, 1, At, B1); PG8_BAR; PG8_SCHED;
;             PG8_LDB(B0, 1, 0); PG8_LDB(B1, 1, 1); PG8_SCHED; PG8_LDA(At, 1, 0); PG8_STAGE(PG8_SA(0, 0), a2, voffA); PG8_STAGE(PG8_SA(0, 1), a2 + hstep, voffA);
;             PG8_WAIT_V(8); PG8_WAIT_L(0); PG8_BAR; PG8_MMA(0, 0, At, B0); PG8_MMA(0, 1, At, B1); PG8_BAR; PG8_SCHED;
;             PG8_LDA(At, 1, 1); PG8_STAGE(PG8_SB(1, 0), b3, voffB); PG8_STAGE(PG8_SB(1, 1), b3 + hstep, voffB);
;             PG8_WAIT_V(6); PG8_WAIT_L(0); PG8_BAR; PG8_MMA(1, 0, At, B0); PG8_MMA(1, 1, At, B1); PG8_BAR; PG8_SCHED;
	s_setprio 3
	v_mfma_f32_16x16x32_bf16 v[60:63], v[132:135], v[204:207], 0
	v_mfma_f32_16x16x32_bf16 v[56:59], v[140:143], v[204:207], 0
	v_mfma_f32_16x16x32_bf16 v[44:47], v[132:135], v[212:215], 0
	v_mfma_f32_16x16x32_bf16 v[40:43], v[140:143], v[212:215], 0
	v_mfma_f32_16x16x32_bf16 v[28:31], v[132:135], v[220:223], 0
	v_mfma_f32_16x16x32_bf16 v[24:27], v[140:143], v[220:223], 0
	v_mfma_f32_16x16x32_bf16 v[12:15], v[132:135], v[228:231], 0
	v_mfma_f32_16x16x32_bf16 v[8:11], v[140:143], v[228:231], 0
	v_mfma_f32_16x16x32_bf16 v[60:63], v[136:139], v[208:211], v[60:63]
	v_mfma_f32_16x16x32_bf16 v[56:59], v[172:175], v[208:211], v[56:59]
	v_mfma_f32_16x16x32_bf16 v[44:47], v[136:139], v[216:219], v[44:47]
	v_mfma_f32_16x16x32_bf16 v[40:43], v[172:175], v[216:219], v[40:43]
	v_mfma_f32_16x16x32_bf16 v[28:31], v[136:139], v[224:227], v[28:31]
	v_mfma_f32_16x16x32_bf16 v[24:27], v[172:175], v[224:227], v[24:27]
	v_mfma_f32_16x16x32_bf16 v[12:15], v[136:139], v[232:235], v[12:15]
	v_mfma_f32_16x16x32_bf16 v[8:11], v[172:175], v[232:235], v[8:11]
	s_setprio 0
	s_setprio 3
	v_mfma_f32_16x16x32_bf16 v[52:55], v[188:191], v[204:207], 0
	v_mfma_f32_16x16x32_bf16 v[48:51], v[196:199], v[204:207], 0
	v_mfma_f32_16x16x32_bf16 v[36:39], v[188:191], v[212:215], 0
	v_mfma_f32_16x16x32_bf16 v[32:35], v[196:199], v[212:215], 0
	v_mfma_f32_16x16x32_bf16 v[20:23], v[188:191], v[220:223], 0
	v_mfma_f32_16x16x32_bf16 v[16:19], v[196:199], v[220:223], 0
	v_mfma_f32_16x16x32_bf16 v[4:7], v[188:191], v[228:231], 0
	v_mfma_f32_16x16x32_bf16 v[0:3], v[196:199], v[228:231], 0
	v_mfma_f32_16x16x32_bf16 v[52:55], v[192:195], v[208:211], v[52:55]
	v_mfma_f32_16x16x32_bf16 v[48:51], v[200:203], v[208:211], v[48:51]
	v_mfma_f32_16x16x32_bf16 v[36:39], v[192:195], v[216:219], v[36:39]
	v_mfma_f32_16x16x32_bf16 v[32:35], v[200:203], v[216:219], v[32:35]
	v_mfma_f32_16x16x32_bf16 v[20:23], v[192:195], v[224:227], v[20:23]
	v_mfma_f32_16x16x32_bf16 v[16:19], v[200:203], v[224:227], v[16:19]
	v_mfma_f32_16x16x32_bf16 v[4:7], v[192:195], v[232:235], v[4:7]
	v_mfma_f32_16x16x32_bf16 v[0:3], v[200:203], v[232:235], v[0:3]
	s_setprio 0
	s_barrier
	s_add_i32 s97, 0, 0x18000
	v_add_u32_e32 v152, s97, v171
	s_add_i32 vcc_lo, 0, 0x1c000
	ds_read_b128 v[132:135], v152
	ds_read_b128 v[136:139], v152 offset:1024
	ds_read_b128 v[140:143], v152 offset:2048
	ds_read_b128 v[172:175], v152 offset:3072
	v_add_u32_e32 v152, vcc_lo, v171
	ds_read_b128 v[188:191], v152
	ds_read_b128 v[192:195], v152 offset:1024
	ds_read_b128 v[196:199], v152 offset:2048
	ds_read_b128 v[200:203], v152 offset:3072
	s_mov_b32 m0, s60
	v_lshl_add_u64 v[184:185], s[48:49], 0, v[150:151]
	ds_read_b128 v[204:207], v181 offset:32768
	ds_read_b128 v[208:211], v181 offset:33792
	ds_read_b128 v[212:215], v181 offset:34816
	ds_read_b128 v[216:219], v181 offset:35840
	ds_read_b128 v[220:223], v181 offset:36864
	ds_read_b128 v[224:227], v181 offset:37888
	ds_read_b128 v[228:231], v181 offset:38912
	ds_read_b128 v[232:235], v181 offset:39936
	global_load_lds_dwordx4 v[184:185], off
	v_lshl_add_u64 v[184:185], s[48:49], 0, v[146:147]
	s_add_u32 s48, s48, 0x80000
	s_mov_b32 m0, s61
	s_addc_u32 s49, s49, 0
	global_load_lds_dwordx4 v[184:185], off
	v_lshl_add_u64 v[184:185], s[48:49], 0, v[150:151]
	s_mov_b32 m0, s62
	s_nop 0
	global_load_lds_dwordx4 v[184:185], off
	v_lshl_add_u64 v[184:185], s[48:49], 0, v[146:147]
	s_mov_b32 m0, s63
	s_nop 0
	global_load_lds_dwordx4 v[184:185], off
	s_waitcnt vmcnt(8)
	s_waitcnt lgkmcnt(0)
	s_barrier
	s_setprio 3
	v_mfma_f32_16x16x32_bf16 v[124:127], v[132:135], v[204:207], v[124:127]
	v_mfma_f32_16x16x32_bf16 v[120:123], v[140:143], v[204:207], v[120:123]
	v_mfma_f32_16x16x32_bf16 v[108:111], v[132:135], v[212:215], v[108:111]
	v_mfma_f32_16x16x32_bf16 v[104:107], v[140:143], v[212:215], v[104:107]
	v_mfma_f32_16x16x32_bf16 v[92:95], v[132:135], v[220:223], v[92:95]
	v_mfma_f32_16x16x32_bf16 v[88:91], v[140:143], v[220:223], v[88:91]
	v_mfma_f32_16x16x32_bf16 v[76:79], v[132:135], v[228:231], v[76:79]
	v_mfma_f32_16x16x32_bf16 v[72:75], v[140:143], v[228:231], v[72:75]
	v_mfma_f32_16x16x32_bf16 v[124:127], v[136:139], v[208:211], v[124:127]
	v_mfma_f32_16x16x32_bf16 v[120:123], v[172:175], v[208:211], v[120:123]
	v_mfma_f32_16x16x32_bf16 v[108:111], v[136:139], v[216:219], v[108:111]
	v_mfma_f32_16x16x32_bf16 v[104:107], v[172:175], v[216:219], v[104:107]
	v_mfma_f32_16x16x32_bf16 v[92:95], v[136:139], v[224:227], v[92:95]
	v_mfma_f32_16x16x32_bf16 v[88:91], v[172:175], v[224:227], v[88:91]
	v_mfma_f32_16x16x32_bf16 v[76:79], v[136:139], v[232:235], v[76:79]
	v_mfma_f32_16x16x32_bf16 v[72:75], v[172:175], v[232:235], v[72:75]
	s_setprio 0
	s_setprio 3
	v_mfma_f32_16x16x32_bf16 v[116:119], v[188:191], v[204:207], v[116:119]
	v_mfma_f32_16x16x32_bf16 v[112:115], v[196:199], v[204:207], v[112:115]
	v_mfma_f32_16x16x32_bf16 v[100:103], v[188:191], v[212:215], v[100:103]
	v_mfma_f32_16x16x32_bf16 v[96:99], v[196:199], v[212:215], v[96:99]
	v_mfma_f32_16x16x32_bf16 v[84:87], v[188:191], v[220:223], v[84:87]
	v_mfma_f32_16x16x32_bf16 v[80:83], v[196:199], v[220:223], v[80:83]
	v_mfma_f32_16x16x32_bf16 v[68:71], v[188:191], v[228:231], v[68:71]
	v_mfma_f32_16x16x32_bf16 v[64:67], v[196:199], v[228:231], v[64:67]
	v_mfma_f32_16x16x32_bf16 v[116:119], v[192:195], v[208:211], v[116:119]
	v_mfma_f32_16x16x32_bf16 v[112:115], v[200:203], v[208:211], v[112:115]
	v_mfma_f32_16x16x32_bf16 v[100:103], v[192:195], v[216:219], v[100:103]
	v_mfma_f32_16x16x32_bf16 v[96:99], v[200:203], v[216:219], v[96:99]
	v_mfma_f32_16x16x32_bf16 v[84:87], v[192:195], v[224:227], v[84:87]
	v_mfma_f32_16x16x32_bf16 v[80:83], v[200:203], v[224:227], v[80:83]
	v_mfma_f32_16x16x32_bf16 v[68:71], v[192:195], v[232:235], v[68:71]
	v_mfma_f32_16x16x32_bf16 v[64:67], v[200:203], v[232:235], v[64:67]
	s_setprio 0
	s_barrier
; #define PG8_STAGE(bufoff, gbase, voff) do { _Pragma("unroll") for (int _i = 0; _i < 2; ++_i) \
;         __builtin_amdgcn_global_load_lds((const unsigned*)((const char*)(gbase) + (voff)[_i]), (LAS unsigned*)(lds + (bufoff) + ldsw + _i * 8192), 16, 0, 0); } while (0)
; #define PG8_LDA(dst, b, h) do { _Pragma("unroll") for (int m = 0; m < 4; ++m) _Pragma("unroll") for (int k = 0; k < 2; ++k) dst[m][k] = *(const LAS bf16x8*)(lds + PG8_SA(b, h) + aoff + m * 2048 + k * 1024); } while (0)
; #define PG8_LDB(dst, b, h) do { _Pragma("unroll") for (int n = 0; n < 2; ++n) _Pragma("unroll") for (int k = 0; k < 2; ++k) dst[n][k] = *(const LAS bf16x8*)(lds + PG8_SB(b, h) + boff + n * 2048 + k * 1024); } while (0)
; #define PG8_MMA(ai, bj, At, Bt) do { __builtin_amdgcn_s_setprio(3); _Pragma("unroll") for (int m = 0; m < 4; ++m) _Pragma("unroll") for (int n = 0; n < 2; ++n) _Pragma("unroll") for (int k = 0; k < 2; ++k) \
;         acc[ai][bj][m][n] = __builtin_amdgcn_mfma_f32_16x16x32_bf16(Bt[n][k], At[m][k], acc[ai][bj][m][n], 0, 0, 0); __builtin_amdgcn_s_setprio(0); } while (0)
; #define PG8_WAIT_V(n) asm volatile("s_waitcnt vmcnt(" #n ")" ::: "memory")
; #define PG8_WAIT_L(n) asm volatile("s_waitcnt lgkmcnt(" #n ")" ::: "memory")
; #define PG8_BAR __builtin_amdgcn_s_barrier()
; #define PG8_SCHED __builtin_amdgcn_sched_barrier(0)
; template <class Epi, class Sched>
; __device__ __forceinline__ void gemm_phase(LAS unsigned char* lds, const Gemm g, const Sched& S, const Epi& E, int tid_in) {
;     ...
;             PG8_LDB(B0, 0, 0); PG8_LDB(B1, 0, 1); PG8_SCHED; PG8_LDA(At, 0, 0); PG8_STAGE(PG8_SA(1, 0), a1, voffA); PG8_STAGE(PG8_SA(1, 1), a1 + hstep, voffA);
;             PG8_WAIT_V(8); PG8_WAIT_L(0); PG8_BAR; PG8_MMA(0, 0, At, B0); PG8_MMA(0, 1, At, B1); PG8_BAR; PG8_SCHED;
;     ...
;             PG8_LDB(B0, 1, 0); PG8_LDB(B1, 1, 1); PG8_SCHED; PG8_LDA(At, 1, 0); PG8_STAGE(PG8_SA(0, 0), a2, voffA); PG8_STAGE(PG8_SA(0, 1), a2 + hstep, voffA);
;             PG8_WAIT_V(8); PG8_WAIT_L(0); PG8_BAR; PG8_MMA(0, 0, At, B0); PG8_MMA(0, 1, At, B1); PG8_BAR; PG8_SCHED;
;             PG8_LDA(At, 1, 1); PG8_STAGE(PG8_SB(1, 0), b3, voffB); PG8_STAGE(PG8_SB(1, 1), b3 + hstep, voffB);
;             PG8_WAIT_V(6); PG8_WAIT_L(0); PG8_BAR; PG8_MMA(1, 0, At, B0); PG8_MMA(1, 1, At, B1); PG8_BAR; PG8_SCHED;
;         }
	s_add_i32 s48, s97, s2
	v_lshl_add_u64 v[168:169], v[168:169], 0, s[10:11]
	s_mov_b32 m0, s48
	ds_read_b128 v[204:207], v181 offset:49152
	ds_read_b128 v[208:211], v181 offset:50176
	ds_read_b128 v[212:215], v181 offset:51200
	ds_read_b128 v[216:219], v181 offset:52224
	ds_read_b128 v[220:223], v181 offset:53248
	ds_read_b128 v[224:227], v181 offset:54272
	ds_read_b128 v[228:231], v181 offset:55296
	ds_read_b128 v[232:235], v181 offset:56320
	global_load_lds_dwordx4 v[168:169], off
	s_add_i32 m0, s48, 0x2000
	s_add_u32 s46, s46, 0x80080
	v_lshl_add_u64 v[168:169], v[176:177], 0, s[10:11]
	s_addc_u32 s47, s47, 0
	s_add_i32 s48, vcc_lo, s2
	global_load_lds_dwordx4 v[168:169], off
	v_lshl_add_u64 v[168:169], s[46:47], 0, v[148:149]
	s_mov_b32 m0, s48
	s_nop 0
	global_load_lds_dwordx4 v[168:169], off
	v_lshl_add_u64 v[168:169], s[46:47], 0, v[144:145]
	s_add_i32 m0, s48, 0x2000
	s_nop 0
	global_load_lds_dwordx4 v[168:169], off
	s_waitcnt vmcnt(6)
	s_waitcnt lgkmcnt(0)
	s_barrier
	s_setprio 3
	v_mfma_f32_16x16x32_bf16 v[60:63], v[132:135], v[204:207], v[60:63]
	v_mfma_f32_16x16x32_bf16 v[56:59], v[140:143], v[204:207], v[56:59]
	v_mfma_f32_16x16x32_bf16 v[44:47], v[132:135], v[212:215], v[44:47]
	v_mfma_f32_16x16x32_bf16 v[40:43], v[140:143], v[212:215], v[40:43]
	v_mfma_f32_16x16x32_bf16 v[28:31], v[132:135], v[220:223], v[28:31]
	v_mfma_f32_16x16x32_bf16 v[24:27], v[140:143], v[220:223], v[24:27]
	v_mfma_f32_16x16x32_bf16 v[12:15], v[132:135], v[228:231], v[12:15]
	v_mfma_f32_16x16x32_bf16 v[8:11], v[140:143], v[228:231], v[8:11]
	v_mfma_f32_16x16x32_bf16 v[60:63], v[136:139], v[208:211], v[60:63]
	v_mfma_f32_16x16x32_bf16 v[56:59], v[172:175], v[208:211], v[56:59]
	v_mfma_f32_16x16x32_bf16 v[44:47], v[136:139], v[216:219], v[44:47]
	v_mfma_f32_16x16x32_bf16 v[40:43], v[172:175], v[216:219], v[40:43]
	v_mfma_f32_16x16x32_bf16 v[28:31], v[136:139], v[224:227], v[28:31]
	v_mfma_f32_16x16x32_bf16 v[24:27], v[172:175], v[224:227], v[24:27]
	v_mfma_f32_16x16x32_bf16 v[12:15], v[136:139], v[232:235], v[12:15]
	v_mfma_f32_16x16x32_bf16 v[8:11], v[172:175], v[232:235], v[8:11]
	s_setprio 0
	s_setprio 3
	v_mfma_f32_16x16x32_bf16 v[52:55], v[188:191], v[204:207], v[52:55]
	v_mfma_f32_16x16x32_bf16 v[48:51], v[196:199], v[204:207], v[48:51]
	v_mfma_f32_16x16x32_bf16 v[36:39], v[188:191], v[212:215], v[36:39]
	v_mfma_f32_16x16x32_bf16 v[32:35], v[196:199], v[212:215], v[32:35]
	v_mfma_f32_16x16x32_bf16 v[20:23], v[188:191], v[220:223], v[20:23]
	v_mfma_f32_16x16x32_bf16 v[16:19], v[196:199], v[220:223], v[16:19]
	v_mfma_f32_16x16x32_bf16 v[4:7], v[188:191], v[228:231], v[4:7]
	v_mfma_f32_16x16x32_bf16 v[0:3], v[196:199], v[228:231], v[0:3]
	v_mfma_f32_16x16x32_bf16 v[52:55], v[192:195], v[208:211], v[52:55]
	v_mfma_f32_16x16x32_bf16 v[48:51], v[200:203], v[208:211], v[48:51]
	v_mfma_f32_16x16x32_bf16 v[36:39], v[192:195], v[216:219], v[36:39]
	v_mfma_f32_16x16x32_bf16 v[32:35], v[200:203], v[216:219], v[32:35]
	v_mfma_f32_16x16x32_bf16 v[20:23], v[192:195], v[224:227], v[20:23]
	v_mfma_f32_16x16x32_bf16 v[16:19], v[200:203], v[224:227], v[16:19]
	v_mfma_f32_16x16x32_bf16 v[4:7], v[192:195], v[232:235], v[4:7]
	v_mfma_f32_16x16x32_bf16 v[0:3], v[200:203], v[232:235], v[0:3]
	s_setprio 0
	s_barrier
	s_add_i32 s96, s96, 2
	s_add_u32 s44, s44, 0x100
	s_addc_u32 s45, s45, 0
	s_cmp_gt_u32 s96, 29
	s_cbranch_scc0 .LBB0_102
	s_branch .Lpeel_exit_0
.LBB0_102:
	ds_read_b128 v[132:135], v179
	ds_read_b128 v[136:139], v179 offset:1024
	ds_read_b128 v[140:143], v179 offset:2048
	ds_read_b128 v[172:175], v179 offset:3072
	ds_read_b128 v[188:191], v180
	ds_read_b128 v[192:195], v180 offset:1024
	ds_read_b128 v[196:199], v180 offset:2048
	ds_read_b128 v[200:203], v180 offset:3072
	s_add_u32 s46, s42, s44
	s_addc_u32 s47, s43, s45
	s_add_u32 s48, s46, 0x100
	s_addc_u32 s49, s47, 0
	s_add_u32 s46, s94, s44
	s_addc_u32 s47, s95, s45
	s_cmpk_eq_i32 s44, 0xf00
	s_cselect_b32 s47, s29, s47
	s_cselect_b32 s46, s41, s46
	s_cselect_b32 s49, s31, s49
	s_cselect_b32 s48, s39, s48
	v_lshl_add_u64 v[168:169], v[130:131], 0, s[44:45]
	v_lshl_add_u64 v[176:177], v[168:169], 0, s[10:11]
	s_add_i32 m0, s60, 0x8000
	ds_read_b128 v[204:207], v181
	ds_read_b128 v[208:211], v181 offset:1024
	ds_read_b128 v[212:215], v181 offset:2048
	ds_read_b128 v[216:219], v181 offset:3072
	ds_read_b128 v[220:223], v181 offset:4096
	ds_read_b128 v[224:227], v181 offset:5120
	ds_read_b128 v[228:231], v181 offset:6144
	ds_read_b128 v[232:235], v181 offset:7168
	global_load_lds_dwordx4 v[176:177], off
	v_lshl_add_u64 v[176:177], v[128:129], 0, s[44:45]
	v_lshl_add_u64 v[184:185], v[176:177], 0, s[10:11]
	s_add_i32 m0, s60, 0xa000
	v_lshl_add_u64 v[168:169], v[168:169], 0, s[12:13]
	global_load_lds_dwordx4 v[184:185], off
	s_add_i32 m0, s60, 0xc000
	s_nop 0
	global_load_lds_dwordx4 v[168:169], off
	v_lshl_add_u64 v[168:169], v[176:177], 0, s[12:13]
	s_add_i32 m0, s60, 0xe000
	s_nop 0
	global_load_lds_dwordx4 v[168:169], off
	s_waitcnt vmcnt(8)
	s_waitcnt lgkmcnt(0)
	s_barrier
; #define PG8_STAGE(bufoff, gbase, voff) do { _Pragma("unroll") for (int _i = 0; _i < 2; ++_i) \
;         __builtin_amdgcn_global_load_lds((const unsigned*)((const char*)(gbase) + (voff)[_i]), (LAS unsigned*)(lds + (bufoff) + ldsw + _i * 8192), 16, 0, 0); } while (0)
; #define PG8_LDA(dst, b, h) do { _Pragma("unroll") for (int m = 0; m < 4; ++m) _Pragma("unroll") for (int k = 0; k < 2; ++k) dst[m][k] = *(const LAS bf16x8*)(lds + PG8_SA(b, h) + aoff + m * 2048 + k * 1024); } while (0)
; #define PG8_LDB(dst, b, h) do { _Pragma("unroll") for (int n = 0; n < 2; ++n) _Pragma("unroll") for (int k = 0; k < 2; ++k) dst[n][k] = *(const LAS bf16x8*)(lds + PG8_SB(b, h) + boff + n * 2048 + k * 1024); } while (0)
; #define PG8_MMA(ai, bj, At, Bt) do { __builtin_amdgcn_s_setprio(3); _Pragma("unroll") for (int m = 0; m < 4; ++m) _Pragma("unroll") for (int n = 0; n < 2; ++n) _Pragma("unroll") for (int k = 0; k < 2; ++k) \
;         acc[ai][bj][m][n] = __builtin_amdgcn_mfma_f32_16x16x32_bf16(Bt[n][k], At[m][k], acc[ai][bj][m][n], 0, 0, 0); __builtin_amdgcn_s_setprio(0); } while (0)
; #define PG8_WAIT_V(n) asm volatile("s_waitcnt vmcnt(" #n ")" ::: "memory")
; #define PG8_WAIT_L(n) asm volatile("s_waitcnt lgkmcnt(" #n ")" ::: "memory")
; #define PG8_BAR __builtin_amdgcn_s_barrier()
; #define PG8_SCHED __builtin_amdgcn_sched_barrier(0)
; template <class Epi, class Sched>
; __device__ __forceinline__ void gemm_phase(LAS unsigned char* lds, const Gemm g, const Sched& S, const Epi& E, int tid_in) {
;     ...
;             PG8_WAIT_V(8); PG8_WAIT_L(0); PG8_BAR; PG8_MMA(0, 0, At, B0); PG8_MMA(0, 1, At, B1); PG8_BAR; PG8_SCHED;
;             PG8_LDA(At, 0, 1); PG8_STAGE(PG8_SB(0, 0), b2, voffB); PG8_STAGE(PG8_SB(0, 1), b2 + hstep, voffB);
;             PG8_WAIT_V(6); PG8_WAIT_L(0); PG8_BAR; PG8_MMA(1, 0, At, B0); PG8_MMA(1, 1, At, B1); PG8_BAR; PG8_SCHED;
;             PG8_LDB(B0, 1, 0); PG8_LDB(B1, 1, 1); PG8_SCHED; PG8_LDA(At, 1, 0); PG8_STAGE(PG8_SA(0, 0), a2, voffA); PG8_STAGE(PG8_SA(0, 1), a2 + hstep, voffA);
;             PG8_WAIT_V(8); PG8_WAIT_L(0); PG8_BAR; PG8_MMA(0, 0, At, B0); PG8_MMA(0, 1, At, B1); PG8_BAR; PG8_SCHED;
	s_setprio 3
	v_mfma_f32_16x16x32_bf16 v[124:127], v[132:135], v[204:207], v[124:127]
	v_mfma_f32_16x16x32_bf16 v[120:123], v[140:143], v[204:207], v[120:123]
	v_mfma_f32_16x16x32_bf16 v[108:111], v[132:135], v[212:215], v[108:111]
	v_mfma_f32_16x16x32_bf16 v[104:107], v[140:143], v[212:215], v[104:107]
	v_mfma_f32_16x16x32_bf16 v[92:95], v[132:135], v[220:223], v[92:95]
	v_mfma_f32_16x16x32_bf16 v[88:91], v[140:143], v[220:223], v[88:91]
	v_mfma_f32_16x16x32_bf16 v[76:79], v[132:135], v[228:231], v[76:79]
	v_mfma_f32_16x16x32_bf16 v[72:75], v[140:143], v[228:231], v[72:75]
	v_mfma_f32_16x16x32_bf16 v[124:127], v[136:139], v[208:211], v[124:127]
	v_mfma_f32_16x16x32_bf16 v[120:123], v[172:175], v[208:211], v[120:123]
	v_mfma_f32_16x16x32_bf16 v[108:111], v[136:139], v[216:219], v[108:111]
	v_mfma_f32_16x16x32_bf16 v[104:107], v[172:175], v[216:219], v[104:107]
	v_mfma_f32_16x16x32_bf16 v[92:95], v[136:139], v[224:227], v[92:95]
	v_mfma_f32_16x16x32_bf16 v[88:91], v[172:175], v[224:227], v[88:91]
	v_mfma_f32_16x16x32_bf16 v[76:79], v[136:139], v[232:235], v[76:79]
	v_mfma_f32_16x16x32_bf16 v[72:75], v[172:175], v[232:235], v[72:75]
	s_setprio 0
	s_setprio 3
	v_mfma_f32_16x16x32_bf16 v[116:119], v[188:191], v[204:207], v[116:119]
	v_mfma_f32_16x16x32_bf16 v[112:115], v[196:199], v[204:207], v[112:115]
	v_mfma_f32_16x16x32_bf16 v[100:103], v[188:191], v[212:215], v[100:103]
	v_mfma_f32_16x16x32_bf16 v[96:99], v[196:199], v[212:215], v[96:99]
	v_mfma_f32_16x16x32_bf16 v[84:87], v[188:191], v[220:223], v[84:87]
	v_mfma_f32_16x16x32_bf16 v[80:83], v[196:199], v[220:223], v[80:83]
	v_mfma_f32_16x16x32_bf16 v[68:71], v[188:191], v[228:231], v[68:71]
	v_mfma_f32_16x16x32_bf16 v[64:67], v[196:199], v[228:231], v[64:67]
	v_mfma_f32_16x16x32_bf16 v[116:119], v[192:195], v[208:211], v[116:119]
	v_mfma_f32_16x16x32_bf16 v[112:115], v[200:203], v[208:211], v[112:115]
	v_mfma_f32_16x16x32_bf16 v[100:103], v[192:195], v[216:219], v[100:103]
	v_mfma_f32_16x16x32_bf16 v[96:99], v[200:203], v[216:219], v[96:99]
	v_mfma_f32_16x16x32_bf16 v[84:87], v[192:195], v[224:227], v[84:87]
	v_mfma_f32_16x16x32_bf16 v[80:83], v[200:203], v[224:227], v[80:83]
	v_mfma_f32_16x16x32_bf16 v[68:71], v[192:195], v[232:235], v[68:71]
	v_mfma_f32_16x16x32_bf16 v[64:67], v[200:203], v[232:235], v[64:67]
	s_setprio 0
	s_barrier
	s_add_i32 s97, s66, s2
	v_lshl_add_u64 v[168:169], s[46:47], 0, v[148:149]
	s_mov_b32 m0, s97
	ds_read_b128 v[204:207], v181 offset:16384
	ds_read_b128 v[208:211], v181 offset:17408
	ds_read_b128 v[212:215], v181 offset:18432
	ds_read_b128 v[216:219], v181 offset:19456
	ds_read_b128 v[220:223], v181 offset:20480
	ds_read_b128 v[224:227], v181 offset:21504
	ds_read_b128 v[228:231], v181 offset:22528
	ds_read_b128 v[232:235], v181 offset:23552
	global_load_lds_dwordx4 v[168:169], off
	s_add_i32 m0, s97, 0x2000
	s_add_u32 vcc_lo, s46, 0x80000
	v_lshl_add_u64 v[176:177], s[46:47], 0, v[144:145]
	s_addc_u32 vcc_hi, s47, 0
	s_add_i32 s97, s67, s2
	global_load_lds_dwordx4 v[176:177], off
	v_lshl_add_u64 v[184:185], vcc, 0, v[148:149]
	s_mov_b32 m0, s97
	s_nop 0
	global_load_lds_dwordx4 v[184:185], off
	v_lshl_add_u64 v[184:185], vcc, 0, v[144:145]
	s_add_i32 m0, s97, 0x2000
	s_nop 0
	global_load_lds_dwordx4 v[184:185], off
	s_waitcnt vmcnt(6)
	s_waitcnt lgkmcnt(0)
	s_barrier
	s_setprio 3
	v_mfma_f32_16x16x32_bf16 v[60:63], v[132:135], v[204:207], v[60:63]
	v_mfma_f32_16x16x32_bf16 v[56:59], v[140:143], v[204:207], v[56:59]
	v_mfma_f32_16x16x32_bf16 v[44:47], v[132:135], v[212:215], v[44:47]
	v_mfma_f32_16x16x32_bf16 v[40:43], v[140:143], v[212:215], v[40:43]
	v_mfma_f32_16x16x32_bf16 v[28:31], v[132:135], v[220:223], v[28:31]
	v_mfma_f32_16x16x32_bf16 v[24:27], v[140:143], v[220:223], v[24:27]
	v_mfma_f32_16x16x32_bf16 v[12:15], v[132:135], v[228:231], v[12:15]
	v_mfma_f32_16x16x32_bf16 v[8:11], v[140:143], v[228:231], v[8:11]
	v_mfma_f32_16x16x32_bf16 v[60:63], v[136:139], v[208:211], v[60:63]
	v_mfma_f32_16x16x32_bf16 v[56:59], v[172:175], v[208:211], v[56:59]
	v_mfma_f32_16x16x32_bf16 v[44:47], v[136:139], v[216:219], v[44:47]
	v_mfma_f32_16x16x32_bf16 v[40:43], v[172:175], v[216:219], v[40:43]
	v_mfma_f32_16x16x32_bf16 v[28:31], v[136:139], v[224:227], v[28:31]
	v_mfma_f32_16x16x32_bf16 v[24:27], v[172:175], v[224:227], v[24:27]
	v_mfma_f32_16x16x32_bf16 v[12:15], v[136:139], v[232:235], v[12:15]
	v_mfma_f32_16x16x32_bf16 v[8:11], v[172:175], v[232:235], v[8:11]
	s_setprio 0
	s_setprio 3
	v_mfma_f32_16x16x32_bf16 v[52:55], v[188:191], v[204:207], v[52:55]
	v_mfma_f32_16x16x32_bf16 v[48:51], v[196:199], v[204:207], v[48:51]
	v_mfma_f32_16x16x32_bf16 v[36:39], v[188:191], v[212:215], v[36:39]
	v_mfma_f32_16x16x32_bf16 v[32:35], v[196:199], v[212:215], v[32:35]
	v_mfma_f32_16x16x32_bf16 v[20:23], v[188:191], v[220:223], v[20:23]
	v_mfma_f32_16x16x32_bf16 v[16:19], v[196:199], v[220:223], v[16:19]
	v_mfma_f32_16x16x32_bf16 v[4:7], v[188:191], v[228:231], v[4:7]
	v_mfma_f32_16x16x32_bf16 v[0:3], v[196:199], v[228:231], v[0:3]
	v_mfma_f32_16x16x32_bf16 v[52:55], v[192:195], v[208:211], v[52:55]
	v_mfma_f32_16x16x32_bf16 v[48:51], v[200:203], v[208:211], v[48:51]
	v_mfma_f32_16x16x32_bf16 v[36:39], v[192:195], v[216:219], v[36:39]
	v_mfma_f32_16x16x32_bf16 v[32:35], v[200:203], v[216:219], v[32:35]
	v_mfma_f32_16x16x32_bf16 v[20:23], v[192:195], v[224:227], v[20:23]
	v_mfma_f32_16x16x32_bf16 v[16:19], v[200:203], v[224:227], v[16:19]
	v_mfma_f32_16x16x32_bf16 v[4:7], v[192:195], v[232:235], v[4:7]
	v_mfma_f32_16x16x32_bf16 v[0:3], v[200:203], v[232:235], v[0:3]
	s_setprio 0
	s_barrier
; #define PG8_STAGE(bufoff, gbase, voff) do { _Pragma("unroll") for (int _i = 0; _i < 2; ++_i) \
;         __builtin_amdgcn_global_load_lds((const unsigned*)((const char*)(gbase) + (voff)[_i]), (LAS unsigned*)(lds + (bufoff) + ldsw + _i * 8192), 16, 0, 0); } while (0)
; #define PG8_LDA(dst, b, h) do { _Pragma("unroll") for (int m = 0; m < 4; ++m) _Pragma("unroll") for (int k = 0; k < 2; ++k) dst[m][k] = *(const LAS bf16x8*)(lds + PG8_SA(b, h) + aoff + m * 2048 + k * 1024); } while (0)
; #define PG8_MMA(ai, bj, At, Bt) do { __builtin_amdgcn_s_setprio(3); _Pragma("unroll") for (int m = 0; m < 4; ++m) _Pragma("unroll") for (int n = 0; n < 2; ++n) _Pragma("unroll") for (int k = 0; k < 2; ++k) \
;         acc[ai][bj][m][n] = __builtin_amdgcn_mfma_f32_16x16x32_bf16(Bt[n][k], At[m][k], acc[ai][bj][m][n], 0, 0, 0); __builtin_amdgcn_s_setprio(0); } while (0)
; #define PG8_WAIT_V(n) asm volatile("s_waitcnt vmcnt(" #n ")" ::: "memory")
; #define PG8_WAIT_L(n) asm volatile("s_waitcnt lgkmcnt(" #n ")" ::: "memory")
; #define PG8_BAR __builtin_amdgcn_s_barrier()
; #define PG8_SCHED __builtin_amdgcn_sched_barrier(0)
; template <class Epi, class Sched>
; __device__ __forceinline__ void gemm_phase(LAS unsigned char* lds, const Gemm g, const Sched& S, const Epi& E, int tid_in) {
;     ...
;             PG8_LDA(At, 1, 1); PG8_STAGE(PG8_SB(1, 0), b3, voffB); PG8_STAGE(PG8_SB(1, 1), b3 + hstep, voffB);
;             PG8_WAIT_V(6); PG8_WAIT_L(0); PG8_BAR; PG8_MMA(1, 0, At, B0); PG8_MMA(1, 1, At, B1); PG8_BAR; PG8_SCHED;
	s_add_i32 s97, 0, 0x18000
	v_add_u32_e32 v152, s97, v171
	s_add_i32 vcc_lo, 0, 0x1c000
	ds_read_b128 v[132:135], v152
	ds_read_b128 v[136:139], v152 offset:1024
	ds_read_b128 v[140:143], v152 offset:2048
	ds_read_b128 v[172:175], v152 offset:3072
	v_add_u32_e32 v152, vcc_lo, v171
	ds_read_b128 v[188:191], v152
	ds_read_b128 v[192:195], v152 offset:1024
	ds_read_b128 v[196:199], v152 offset:2048
	ds_read_b128 v[200:203], v152 offset:3072
	s_mov_b32 m0, s60
	v_lshl_add_u64 v[184:185], s[48:49], 0, v[150:151]
	ds_read_b128 v[204:207], v181 offset:32768
	ds_read_b128 v[208:211], v181 offset:33792
	ds_read_b128 v[212:215], v181 offset:34816
	ds_read_b128 v[216:219], v181 offset:35840
	ds_read_b128 v[220:223], v181 offset:36864
	ds_read_b128 v[224:227], v181 offset:37888
	ds_read_b128 v[228:231], v181 offset:38912
	ds_read_b128 v[232:235], v181 offset:39936
	global_load_lds_dwordx4 v[184:185], off
	v_lshl_add_u64 v[184:185], s[48:49], 0, v[146:147]
	s_add_u32 s48, s48, 0x80000
	s_mov_b32 m0, s61
	s_addc_u32 s49, s49, 0
	global_load_lds_dwordx4 v[184:185], off
	v_lshl_add_u64 v[184:185], s[48:49], 0, v[150:151]
	s_mov_b32 m0, s62
	s_nop 0
	global_load_lds_dwordx4 v[184:185], off
	v_lshl_add_u64 v[184:185], s[48:49], 0, v[146:147]
	s_mov_b32 m0, s63
	s_nop 0
	global_load_lds_dwordx4 v[184:185], off
	s_waitcnt vmcnt(8)
	s_waitcnt lgkmcnt(0)
	s_barrier
	s_setprio 3
	v_mfma_f32_16x16x32_bf16 v[124:127], v[132:135], v[204:207], v[124:127]
	v_mfma_f32_16x16x32_bf16 v[120:123], v[140:143], v[204:207], v[120:123]
	v_mfma_f32_16x16x32_bf16 v[108:111], v[132:135], v[212:215], v[108:111]
	v_mfma_f32_16x16x32_bf16 v[104:107], v[140:143], v[212:215], v[104:107]
	v_mfma_f32_16x16x32_bf16 v[92:95], v[132:135], v[220:223], v[92:95]
	v_mfma_f32_16x16x32_bf16 v[88:91], v[140:143], v[220:223], v[88:91]
	v_mfma_f32_16x16x32_bf16 v[76:79], v[132:135], v[228:231], v[76:79]
	v_mfma_f32_16x16x32_bf16 v[72:75], v[140:143], v[228:231], v[72:75]
	v_mfma_f32_16x16x32_bf16 v[124:127], v[136:139], v[208:211], v[124:127]
	v_mfma_f32_16x16x32_bf16 v[120:123], v[172:175], v[208:211], v[120:123]
	v_mfma_f32_16x16x32_bf16 v[108:111], v[136:139], v[216:219], v[108:111]
	v_mfma_f32_16x16x32_bf16 v[104:107], v[172:175], v[216:219], v[104:107]
	v_mfma_f32_16x16x32_bf16 v[92:95], v[136:139], v[224:227], v[92:95]
	v_mfma_f32_16x16x32_bf16 v[88:91], v[172:175], v[224:227], v[88:91]
	v_mfma_f32_16x16x32_bf16 v[76:79], v[136:139], v[232:235], v[76:79]
	v_mfma_f32_16x16x32_bf16 v[72:75], v[172:175], v[232:235], v[72:75]
	s_setprio 0
	s_setprio 3
	v_mfma_f32_16x16x32_bf16 v[116:119], v[188:191], v[204:207], v[116:119]
	v_mfma_f32_16x16x32_bf16 v[112:115], v[196:199], v[204:207], v[112:115]
	v_mfma_f32_16x16x32_bf16 v[100:103], v[188:191], v[212:215], v[100:103]
	v_mfma_f32_16x16x32_bf16 v[96:99], v[196:199], v[212:215], v[96:99]
	v_mfma_f32_16x16x32_bf16 v[84:87], v[188:191], v[220:223], v[84:87]
	v_mfma_f32_16x16x32_bf16 v[80:83], v[196:199], v[220:223], v[80:83]
	v_mfma_f32_16x16x32_bf16 v[68:71], v[188:191], v[228:231], v[68:71]
	v_mfma_f32_16x16x32_bf16 v[64:67], v[196:199], v[228:231], v[64:67]
	v_mfma_f32_16x16x32_bf16 v[116:119], v[192:195], v[208:211], v[116:119]
	v_mfma_f32_16x16x32_bf16 v[112:115], v[200:203], v[208:211], v[112:115]
	v_mfma_f32_16x16x32_bf16 v[100:103], v[192:195], v[216:219], v[100:103]
	v_mfma_f32_16x16x32_bf16 v[96:99], v[200:203], v[216:219], v[96:99]
	v_mfma_f32_16x16x32_bf16 v[84:87], v[192:195], v[224:227], v[84:87]
	v_mfma_f32_16x16x32_bf16 v[80:83], v[200:203], v[224:227], v[80:83]
	v_mfma_f32_16x16x32_bf16 v[68:71], v[192:195], v[232:235], v[68:71]
	v_mfma_f32_16x16x32_bf16 v[64:67], v[200:203], v[232:235], v[64:67]
	s_setprio 0
	s_barrier
; #define PG8_STAGE(bufoff, gbase, voff) do { _Pragma("unroll") for (int _i = 0; _i < 2; ++_i) \
;         __builtin_amdgcn_global_load_lds((const unsigned*)((const char*)(gbase) + (voff)[_i]), (LAS unsigned*)(lds + (bufoff) + ldsw + _i * 8192), 16, 0, 0); } while (0)
; #define PG8_LDA(dst, b, h) do { _Pragma("unroll") for (int m = 0; m < 4; ++m) _Pragma("unroll") for (int k = 0; k < 2; ++k) dst[m][k] = *(const LAS bf16x8*)(lds + PG8_SA(b, h) + aoff + m * 2048 + k * 1024); } while (0)
; #define PG8_LDB(dst, b, h) do { _Pragma("unroll") for (int n = 0; n < 2; ++n) _Pragma("unroll") for (int k = 0; k < 2; ++k) dst[n][k] = *(const LAS bf16x8*)(lds + PG8_SB(b, h) + boff + n * 2048 + k * 1024); } while (0)
; #define PG8_MMA(ai, bj, At, Bt) do { __builtin_amdgcn_s_setprio(3); _Pragma("unroll") for (int m = 0; m < 4; ++m) _Pragma("unroll") for (int n = 0; n < 2; ++n) _Pragma("unroll") for (int k = 0; k < 2; ++k) \
;         acc[ai][bj][m][n] = __builtin_amdgcn_mfma_f32_16x16x32_bf16(Bt[n][k], At[m][k], acc[ai][bj][m][n], 0, 0, 0); __builtin_amdgcn_s_setprio(0); } while (0)
; #define PG8_WAIT_V(n) asm volatile("s_waitcnt vmcnt(" #n ")" ::: "memory")
; #define PG8_WAIT_L(n) asm volatile("s_waitcnt lgkmcnt(" #n ")" ::: "memory")
; #define PG8_BAR __builtin_amdgcn_s_barrier()
; #define PG8_SCHED __builtin_amdgcn_sched_barrier(0)
; template <class Epi, class Sched>
; __device__ __forceinline__ void gemm_phase(LAS unsigned char* lds, const Gemm g, const Sched& S, const Epi& E, int tid_in) {
;     ...
;             PG8_LDB(B0, 1, 0); PG8_LDB(B1, 1, 1); PG8_SCHED; PG8_LDA(At, 1, 0); PG8_STAGE(PG8_SA(0, 0), a2, voffA); PG8_STAGE(PG8_SA(0, 1), a2 + hstep, voffA);
;             PG8_WAIT_V(8); PG8_WAIT_L(0); PG8_BAR; PG8_MMA(0, 0, At, B0); PG8_MMA(0, 1, At, B1); PG8_BAR; PG8_SCHED;
;             PG8_LDA(At, 1, 1); PG8_STAGE(PG8_SB(1, 0), b3, voffB); PG8_STAGE(PG8_SB(1, 1), b3 + hstep, voffB);
;             PG8_WAIT_V(6); PG8_WAIT_L(0); PG8_BAR; PG8_MMA(1, 0, At, B0); PG8_MMA(1, 1, At, B1); PG8_BAR; PG8_SCHED;
;         }
	s_add_i32 s48, s97, s2
	v_lshl_add_u64 v[168:169], v[168:169], 0, s[10:11]
	s_mov_b32 m0, s48
	ds_read_b128 v[204:207], v181 offset:49152
	ds_read_b128 v[208:211], v181 offset:50176
	ds_read_b128 v[212:215], v181 offset:51200
	ds_read_b128 v[216:219], v181 offset:52224
	ds_read_b128 v[220:223], v181 offset:53248
	ds_read_b128 v[224:227], v181 offset:54272
	ds_read_b128 v[228:231], v181 offset:55296
	ds_read_b128 v[232:235], v181 offset:56320
	global_load_lds_dwordx4 v[168:169], off
	s_add_i32 m0, s48, 0x2000
	s_add_u32 s46, s46, 0x80080
	v_lshl_add_u64 v[168:169], v[176:177], 0, s[10:11]
	s_addc_u32 s47, s47, 0
	s_add_i32 s48, vcc_lo, s2
	global_load_lds_dwordx4 v[168:169], off
	v_lshl_add_u64 v[168:169], s[46:47], 0, v[148:149]
	s_mov_b32 m0, s48
	s_nop 0
	global_load_lds_dwordx4 v[168:169], off
	v_lshl_add_u64 v[168:169], s[46:47], 0, v[144:145]
	s_add_i32 m0, s48, 0x2000
	s_nop 0
	global_load_lds_dwordx4 v[168:169], off
	s_waitcnt vmcnt(6)
	s_waitcnt lgkmcnt(0)
	s_barrier
	s_setprio 3
	v_mfma_f32_16x16x32_bf16 v[60:63], v[132:135], v[204:207], v[60:63]
	v_mfma_f32_16x16x32_bf16 v[56:59], v[140:143], v[204:207], v[56:59]
	v_mfma_f32_16x16x32_bf16 v[44:47], v[132:135], v[212:215], v[44:47]
	v_mfma_f32_16x16x32_bf16 v[40:43], v[140:143], v[212:215], v[40:43]
	v_mfma_f32_16x16x32_bf16 v[28:31], v[132:135], v[220:223], v[28:31]
	v_mfma_f32_16x16x32_bf16 v[24:27], v[140:143], v[220:223], v[24:27]
	v_mfma_f32_16x16x32_bf16 v[12:15], v[132:135], v[228:231], v[12:15]
	v_mfma_f32_16x16x32_bf16 v[8:11], v[140:143], v[228:231], v[8:11]
	v_mfma_f32_16x16x32_bf16 v[60:63], v[136:139], v[208:211], v[60:63]
	v_mfma_f32_16x16x32_bf16 v[56:59], v[172:175], v[208:211], v[56:59]
	v_mfma_f32_16x16x32_bf16 v[44:47], v[136:139], v[216:219], v[44:47]
	v_mfma_f32_16x16x32_bf16 v[40:43], v[172:175], v[216:219], v[40:43]
	v_mfma_f32_16x16x32_bf16 v[28:31], v[136:139], v[224:227], v[28:31]
	v_mfma_f32_16x16x32_bf16 v[24:27], v[172:175], v[224:227], v[24:27]
	v_mfma_f32_16x16x32_bf16 v[12:15], v[136:139], v[232:235], v[12:15]
	v_mfma_f32_16x16x32_bf16 v[8:11], v[172:175], v[232:235], v[8:11]
	s_setprio 0
	s_setprio 3
	v_mfma_f32_16x16x32_bf16 v[52:55], v[188:191], v[204:207], v[52:55]
	v_mfma_f32_16x16x32_bf16 v[48:51], v[196:199], v[204:207], v[48:51]
	v_mfma_f32_16x16x32_bf16 v[36:39], v[188:191], v[212:215], v[36:39]
	v_mfma_f32_16x16x32_bf16 v[32:35], v[196:199], v[212:215], v[32:35]
	v_mfma_f32_16x16x32_bf16 v[20:23], v[188:191], v[220:223], v[20:23]
	v_mfma_f32_16x16x32_bf16 v[16:19], v[196:199], v[220:223], v[16:19]
	v_mfma_f32_16x16x32_bf16 v[4:7], v[188:191], v[228:231], v[4:7]
	v_mfma_f32_16x16x32_bf16 v[0:3], v[196:199], v[228:231], v[0:3]
	v_mfma_f32_16x16x32_bf16 v[52:55], v[192:195], v[208:211], v[52:55]
	v_mfma_f32_16x16x32_bf16 v[48:51], v[200:203], v[208:211], v[48:51]
	v_mfma_f32_16x16x32_bf16 v[36:39], v[192:195], v[216:219], v[36:39]
	v_mfma_f32_16x16x32_bf16 v[32:35], v[200:203], v[216:219], v[32:35]
	v_mfma_f32_16x16x32_bf16 v[20:23], v[192:195], v[224:227], v[20:23]
	v_mfma_f32_16x16x32_bf16 v[16:19], v[200:203], v[224:227], v[16:19]
	v_mfma_f32_16x16x32_bf16 v[4:7], v[192:195], v[232:235], v[4:7]
	v_mfma_f32_16x16x32_bf16 v[0:3], v[200:203], v[232:235], v[0:3]
	s_setprio 0
	s_barrier
	s_add_i32 s96, s96, 2
	s_add_u32 s44, s44, 0x100
	s_addc_u32 s45, s45, 0
	s_cmp_gt_u32 s96, 29
	s_cbranch_scc0 .LBB0_102

; #define PG8_STAGE(bufoff, gbase, voff) do { _Pragma("unroll") for (int _i = 0; _i < 2; ++_i) \
;         __builtin_amdgcn_global_load_lds((const unsigned*)((const char*)(gbase) + (voff)[_i]), (LAS unsigned*)(lds + (bufoff) + ldsw + _i * 8192), 16, 0, 0); } while (0)
; #define PG8_LDA(dst, b, h) do { _Pragma("unroll") for (int m = 0; m < 4; ++m) _Pragma("unroll") for (int k = 0; k < 2; ++k) dst[m][k] = *(const LAS bf16x8*)(lds + PG8_SA(b, h) + aoff + m * 2048 + k * 1024); } while (0)
; #define PG8_LDB(dst, b, h) do { _Pragma("unroll") for (int n = 0; n < 2; ++n) _Pragma("unroll") for (int k = 0; k < 2; ++k) dst[n][k] = *(const LAS bf16x8*)(lds + PG8_SB(b, h) + boff + n * 2048 + k * 1024); } while (0)
; #define PG8_MMA(ai, bj, At, Bt) do { __builtin_amdgcn_s_setprio(3); _Pragma("unroll") for (int m = 0; m < 4; ++m) _Pragma("unroll") for (int n = 0; n < 2; ++n) _Pragma("unroll") for (int k = 0; k < 2; ++k) \
;         acc[ai][bj][m][n] = __builtin_amdgcn_mfma_f32_16x16x32_bf16(Bt[n][k], At[m][k], acc[ai][bj][m][n], 0, 0, 0); __builtin_amdgcn_s_setprio(0); } while (0)
; #define PG8_WAIT_V(n) asm volatile("s_waitcnt vmcnt(" #n ")" ::: "memory")
; #define PG8_WAIT_L(n) asm volatile("s_waitcnt lgkmcnt(" #n ")" ::: "memory")
; #define PG8_BAR __builtin_amdgcn_s_barrier()
; #define PG8_SCHED __builtin_amdgcn_sched_barrier(0)
; template <class Epi, class Sched>
; __device__ __forceinline__ void gemm_phase(LAS unsigned char* lds, const Gemm g, const Sched& S, const Epi& E, int tid_in) {
;     ...
;             PG8_LDB(B0, 0, 0); PG8_LDB(B1, 0, 1); PG8_SCHED; PG8_LDA(At, 0, 0); PG8_STAGE(PG8_SA(1, 0), a1, voffA); PG8_STAGE(PG8_SA(1, 1), a1 + hstep, voffA);
;             PG8_WAIT_V(8); PG8_WAIT_L(0); PG8_BAR; PG8_MMA(0, 0, At, B0); PG8_MMA(0, 1, At, B1); PG8_BAR; PG8_SCHED;
;             PG8_LDA(At, 0, 1); PG8_STAGE(PG8_SB(0, 0), b2, voffB); PG8_STAGE(PG8_SB(0, 1), b2 + hstep, voffB);
;             PG8_WAIT_V(6); PG8_WAIT_L(0); PG8_BAR; PG8_MMA(1, 0, At, B0); PG8_MMA(1, 1, At, B1); PG8_BAR; PG8_SCHED;
.LBB0_511:
	v_add_u32_e32 v144, s49, v188
	v_add_u32_e32 v176, s51, v188
	s_add_u32 s42, s38, s40
	ds_read_b128 v[132:135], v144
	ds_read_b128 v[136:139], v144 offset:1024
	ds_read_b128 v[140:143], v144 offset:2048
	ds_read_b128 v[144:147], v144 offset:3072
	ds_read_b128 v[148:151], v176
	ds_read_b128 v[152:155], v176 offset:1024
	ds_read_b128 v[172:175], v176 offset:2048
	ds_read_b128 v[176:179], v176 offset:3072
	s_addc_u32 s43, s39, s41
	s_add_u32 s44, s42, 0x100
	s_addc_u32 s45, s43, 0
	s_add_u32 s42, s77, s40
	s_addc_u32 s43, s78, s41
	s_cmpk_eq_i32 s40, 0x700
	s_cselect_b32 s43, s27, s43
	s_cselect_b32 s42, s76, s42
	s_cselect_b32 s45, s29, s45
	s_cselect_b32 s44, s37, s44
	v_lshl_add_u64 v[184:185], v[130:131], 0, s[40:41]
	v_lshl_add_u64 v[220:221], v[184:185], 0, s[14:15]
	s_add_i32 m0, s3, 0x8000
	ds_read_b128 v[180:183], v190
	ds_read_b128 v[192:195], v190 offset:1024
	ds_read_b128 v[196:199], v190 offset:2048
	ds_read_b128 v[200:203], v190 offset:3072
	ds_read_b128 v[204:207], v190 offset:4096
	ds_read_b128 v[208:211], v190 offset:5120
	ds_read_b128 v[212:215], v190 offset:6144
	ds_read_b128 v[216:219], v190 offset:7168
	global_load_lds_dwordx4 v[220:221], off
	v_lshl_add_u64 v[220:221], v[128:129], 0, s[40:41]
	v_lshl_add_u64 v[222:223], v[220:221], 0, s[14:15]
	s_add_i32 m0, s3, 0xa000
	v_lshl_add_u64 v[184:185], v[184:185], 0, s[16:17]
	global_load_lds_dwordx4 v[222:223], off
	s_add_i32 m0, s3, 0xc000
	s_nop 0
	global_load_lds_dwordx4 v[184:185], off
	v_lshl_add_u64 v[184:185], v[220:221], 0, s[16:17]
	s_add_i32 m0, s3, 0xe000
	s_nop 0
	global_load_lds_dwordx4 v[184:185], off
	s_waitcnt vmcnt(8)
	s_waitcnt lgkmcnt(0)
	s_barrier
	s_setprio 3
	v_mfma_f32_16x16x32_bf16 v[124:127], v[132:135], v[180:183], v[124:127]
	v_mfma_f32_16x16x32_bf16 v[120:123], v[140:143], v[180:183], v[120:123]
	v_mfma_f32_16x16x32_bf16 v[116:119], v[132:135], v[196:199], v[116:119]
	v_mfma_f32_16x16x32_bf16 v[112:115], v[140:143], v[196:199], v[112:115]
	v_mfma_f32_16x16x32_bf16 v[108:111], v[132:135], v[204:207], v[108:111]
	v_mfma_f32_16x16x32_bf16 v[104:107], v[140:143], v[204:207], v[104:107]
	v_mfma_f32_16x16x32_bf16 v[100:103], v[132:135], v[212:215], v[100:103]
	v_mfma_f32_16x16x32_bf16 v[96:99], v[140:143], v[212:215], v[96:99]
	v_mfma_f32_16x16x32_bf16 v[124:127], v[136:139], v[192:195], v[124:127]
	v_mfma_f32_16x16x32_bf16 v[120:123], v[144:147], v[192:195], v[120:123]
	v_mfma_f32_16x16x32_bf16 v[116:119], v[136:139], v[200:203], v[116:119]
	v_mfma_f32_16x16x32_bf16 v[112:115], v[144:147], v[200:203], v[112:115]
	v_mfma_f32_16x16x32_bf16 v[108:111], v[136:139], v[208:211], v[108:111]
	v_mfma_f32_16x16x32_bf16 v[104:107], v[144:147], v[208:211], v[104:107]
	v_mfma_f32_16x16x32_bf16 v[100:103], v[136:139], v[216:219], v[100:103]
	v_mfma_f32_16x16x32_bf16 v[96:99], v[144:147], v[216:219], v[96:99]
	s_setprio 0
	s_setprio 3
	v_mfma_f32_16x16x32_bf16 v[92:95], v[148:151], v[180:183], v[92:95]
	v_mfma_f32_16x16x32_bf16 v[88:91], v[172:175], v[180:183], v[88:91]
	v_mfma_f32_16x16x32_bf16 v[84:87], v[148:151], v[196:199], v[84:87]
	v_mfma_f32_16x16x32_bf16 v[80:83], v[172:175], v[196:199], v[80:83]
	v_mfma_f32_16x16x32_bf16 v[76:79], v[148:151], v[204:207], v[76:79]
	v_mfma_f32_16x16x32_bf16 v[72:75], v[172:175], v[204:207], v[72:75]
	v_mfma_f32_16x16x32_bf16 v[68:71], v[148:151], v[212:215], v[68:71]
	v_mfma_f32_16x16x32_bf16 v[64:67], v[172:175], v[212:215], v[64:67]
	v_mfma_f32_16x16x32_bf16 v[92:95], v[152:155], v[192:195], v[92:95]
	v_mfma_f32_16x16x32_bf16 v[88:91], v[176:179], v[192:195], v[88:91]
	v_mfma_f32_16x16x32_bf16 v[84:87], v[152:155], v[200:203], v[84:87]
	v_mfma_f32_16x16x32_bf16 v[80:83], v[176:179], v[200:203], v[80:83]
	v_mfma_f32_16x16x32_bf16 v[76:79], v[152:155], v[208:211], v[76:79]
	v_mfma_f32_16x16x32_bf16 v[72:75], v[176:179], v[208:211], v[72:75]
	v_mfma_f32_16x16x32_bf16 v[68:71], v[152:155], v[216:219], v[68:71]
	v_mfma_f32_16x16x32_bf16 v[64:67], v[176:179], v[216:219], v[64:67]
	s_setprio 0
	s_barrier
	s_add_i32 s80, s49, s2
	v_lshl_add_u64 v[184:185], s[42:43], 0, v[158:159]
	s_mov_b32 m0, s80
	ds_read_b128 v[180:183], v190 offset:16384
	ds_read_b128 v[192:195], v190 offset:17408
	ds_read_b128 v[196:199], v190 offset:18432
	ds_read_b128 v[200:203], v190 offset:19456
	ds_read_b128 v[204:207], v190 offset:20480
	ds_read_b128 v[208:211], v190 offset:21504
	ds_read_b128 v[212:215], v190 offset:22528
	ds_read_b128 v[216:219], v190 offset:23552
	global_load_lds_dwordx4 v[184:185], off
	s_add_i32 m0, s80, 0x2000
	s_add_u32 s80, s42, 0x80000
	v_lshl_add_u64 v[220:221], s[42:43], 0, v[162:163]
	s_addc_u32 s81, s43, 0
	s_add_i32 s82, s51, s2
	global_load_lds_dwordx4 v[220:221], off
	v_lshl_add_u64 v[222:223], s[80:81], 0, v[158:159]
	s_mov_b32 m0, s82
	s_nop 0
	global_load_lds_dwordx4 v[222:223], off
	v_lshl_add_u64 v[222:223], s[80:81], 0, v[162:163]
	s_add_i32 m0, s82, 0x2000
	s_nop 0
	global_load_lds_dwordx4 v[222:223], off
	s_waitcnt vmcnt(6)
	s_waitcnt lgkmcnt(0)
	s_barrier
; #define PG8_STAGE(bufoff, gbase, voff) do { _Pragma("unroll") for (int _i = 0; _i < 2; ++_i) \
;         __builtin_amdgcn_global_load_lds((const unsigned*)((const char*)(gbase) + (voff)[_i]), (LAS unsigned*)(lds + (bufoff) + ldsw + _i * 8192), 16, 0, 0); } while (0)
; #define PG8_LDA(dst, b, h) do { _Pragma("unroll") for (int m = 0; m < 4; ++m) _Pragma("unroll") for (int k = 0; k < 2; ++k) dst[m][k] = *(const LAS bf16x8*)(lds + PG8_SA(b, h) + aoff + m * 2048 + k * 1024); } while (0)
; #define PG8_LDB(dst, b, h) do { _Pragma("unroll") for (int n = 0; n < 2; ++n) _Pragma("unroll") for (int k = 0; k < 2; ++k) dst[n][k] = *(const LAS bf16x8*)(lds + PG8_SB(b, h) + boff + n * 2048 + k * 1024); } while (0)
; #define PG8_MMA(ai, bj, At, Bt) do { __builtin_amdgcn_s_setprio(3); _Pragma("unroll") for (int m = 0; m < 4; ++m) _Pragma("unroll") for (int n = 0; n < 2; ++n) _Pragma("unroll") for (int k = 0; k < 2; ++k) \
;         acc[ai][bj][m][n] = __builtin_amdgcn_mfma_f32_16x16x32_bf16(Bt[n][k], At[m][k], acc[ai][bj][m][n], 0, 0, 0); __builtin_amdgcn_s_setprio(0); } while (0)
; #define PG8_WAIT_V(n) asm volatile("s_waitcnt vmcnt(" #n ")" ::: "memory")
; #define PG8_WAIT_L(n) asm volatile("s_waitcnt lgkmcnt(" #n ")" ::: "memory")
; #define PG8_BAR __builtin_amdgcn_s_barrier()
; #define PG8_SCHED __builtin_amdgcn_sched_barrier(0)
; template <class Epi, class Sched>
; __device__ __forceinline__ void gemm_phase(LAS unsigned char* lds, const Gemm g, const Sched& S, const Epi& E, int tid_in) {
;     ...
;             PG8_WAIT_V(6); PG8_WAIT_L(0); PG8_BAR; PG8_MMA(1, 0, At, B0); PG8_MMA(1, 1, At, B1); PG8_BAR; PG8_SCHED;
;             PG8_LDB(B0, 1, 0); PG8_LDB(B1, 1, 1); PG8_SCHED; PG8_LDA(At, 1, 0); PG8_STAGE(PG8_SA(0, 0), a2, voffA); PG8_STAGE(PG8_SA(0, 1), a2 + hstep, voffA);
;             PG8_WAIT_V(8); PG8_WAIT_L(0); PG8_BAR; PG8_MMA(0, 0, At, B0); PG8_MMA(0, 1, At, B1); PG8_BAR; PG8_SCHED;
	s_setprio 3
	v_mfma_f32_16x16x32_bf16 v[60:63], v[132:135], v[180:183], v[60:63]
	v_mfma_f32_16x16x32_bf16 v[56:59], v[140:143], v[180:183], v[56:59]
	v_mfma_f32_16x16x32_bf16 v[52:55], v[132:135], v[196:199], v[52:55]
	v_mfma_f32_16x16x32_bf16 v[48:51], v[140:143], v[196:199], v[48:51]
	v_mfma_f32_16x16x32_bf16 v[44:47], v[132:135], v[204:207], v[44:47]
	v_mfma_f32_16x16x32_bf16 v[40:43], v[140:143], v[204:207], v[40:43]
	v_mfma_f32_16x16x32_bf16 v[36:39], v[132:135], v[212:215], v[36:39]
	v_mfma_f32_16x16x32_bf16 v[32:35], v[140:143], v[212:215], v[32:35]
	v_mfma_f32_16x16x32_bf16 v[60:63], v[136:139], v[192:195], v[60:63]
	v_mfma_f32_16x16x32_bf16 v[56:59], v[144:147], v[192:195], v[56:59]
	v_mfma_f32_16x16x32_bf16 v[52:55], v[136:139], v[200:203], v[52:55]
	v_mfma_f32_16x16x32_bf16 v[48:51], v[144:147], v[200:203], v[48:51]
	v_mfma_f32_16x16x32_bf16 v[44:47], v[136:139], v[208:211], v[44:47]
	v_mfma_f32_16x16x32_bf16 v[40:43], v[144:147], v[208:211], v[40:43]
	v_mfma_f32_16x16x32_bf16 v[36:39], v[136:139], v[216:219], v[36:39]
	v_mfma_f32_16x16x32_bf16 v[32:35], v[144:147], v[216:219], v[32:35]
	s_setprio 0
	s_setprio 3
	v_mfma_f32_16x16x32_bf16 v[28:31], v[148:151], v[180:183], v[28:31]
	v_mfma_f32_16x16x32_bf16 v[24:27], v[172:175], v[180:183], v[24:27]
	v_mfma_f32_16x16x32_bf16 v[20:23], v[148:151], v[196:199], v[20:23]
	v_mfma_f32_16x16x32_bf16 v[16:19], v[172:175], v[196:199], v[16:19]
	v_mfma_f32_16x16x32_bf16 v[12:15], v[148:151], v[204:207], v[12:15]
	v_mfma_f32_16x16x32_bf16 v[8:11], v[172:175], v[204:207], v[8:11]
	v_mfma_f32_16x16x32_bf16 v[4:7], v[148:151], v[212:215], v[4:7]
	v_mfma_f32_16x16x32_bf16 v[0:3], v[172:175], v[212:215], v[0:3]
	v_mfma_f32_16x16x32_bf16 v[28:31], v[152:155], v[192:195], v[28:31]
	v_mfma_f32_16x16x32_bf16 v[24:27], v[176:179], v[192:195], v[24:27]
	v_mfma_f32_16x16x32_bf16 v[20:23], v[152:155], v[200:203], v[20:23]
	v_mfma_f32_16x16x32_bf16 v[16:19], v[176:179], v[200:203], v[16:19]
	v_mfma_f32_16x16x32_bf16 v[12:15], v[152:155], v[208:211], v[12:15]
	v_mfma_f32_16x16x32_bf16 v[8:11], v[176:179], v[208:211], v[8:11]
	v_mfma_f32_16x16x32_bf16 v[4:7], v[152:155], v[216:219], v[4:7]
	v_mfma_f32_16x16x32_bf16 v[0:3], v[176:179], v[216:219], v[0:3]
	s_setprio 0
	s_barrier
	s_add_i32 s80, 0, 0x18000
	s_add_i32 s81, 0, 0x1c000
	v_add_u32_e32 v144, s80, v188
	v_add_u32_e32 v176, s81, v188
	ds_read_b128 v[132:135], v144
	ds_read_b128 v[136:139], v144 offset:1024
	ds_read_b128 v[140:143], v144 offset:2048
	ds_read_b128 v[144:147], v144 offset:3072
	ds_read_b128 v[148:151], v176
	ds_read_b128 v[152:155], v176 offset:1024
	ds_read_b128 v[172:175], v176 offset:2048
	ds_read_b128 v[176:179], v176 offset:3072
	s_mov_b32 m0, s3
	v_lshl_add_u64 v[222:223], s[44:45], 0, v[156:157]
	ds_read_b128 v[180:183], v190 offset:32768
	ds_read_b128 v[192:195], v190 offset:33792
	ds_read_b128 v[196:199], v190 offset:34816
	ds_read_b128 v[200:203], v190 offset:35840
	ds_read_b128 v[204:207], v190 offset:36864
	ds_read_b128 v[208:211], v190 offset:37888
	ds_read_b128 v[212:215], v190 offset:38912
	ds_read_b128 v[216:219], v190 offset:39936
	global_load_lds_dwordx4 v[222:223], off
	v_lshl_add_u64 v[222:223], s[44:45], 0, v[160:161]
	s_add_u32 s44, s44, 0x80000
	s_mov_b32 m0, s46
	s_addc_u32 s45, s45, 0
	global_load_lds_dwordx4 v[222:223], off
	v_lshl_add_u64 v[222:223], s[44:45], 0, v[156:157]
	s_mov_b32 m0, s47
	s_nop 0
	global_load_lds_dwordx4 v[222:223], off
	v_lshl_add_u64 v[222:223], s[44:45], 0, v[160:161]
	s_mov_b32 m0, s48
	s_nop 0
	global_load_lds_dwordx4 v[222:223], off
	s_waitcnt vmcnt(8)
	s_waitcnt lgkmcnt(0)
	s_barrier
; #define PG8_STAGE(bufoff, gbase, voff) do { _Pragma("unroll") for (int _i = 0; _i < 2; ++_i) \
;         __builtin_amdgcn_global_load_lds((const unsigned*)((const char*)(gbase) + (voff)[_i]), (LAS unsigned*)(lds + (bufoff) + ldsw + _i * 8192), 16, 0, 0); } while (0)
; #define PG8_LDA(dst, b, h) do { _Pragma("unroll") for (int m = 0; m < 4; ++m) _Pragma("unroll") for (int k = 0; k < 2; ++k) dst[m][k] = *(const LAS bf16x8*)(lds + PG8_SA(b, h) + aoff + m * 2048 + k * 1024); } while (0)
; #define PG8_MMA(ai, bj, At, Bt) do { __builtin_amdgcn_s_setprio(3); _Pragma("unroll") for (int m = 0; m < 4; ++m) _Pragma("unroll") for (int n = 0; n < 2; ++n) _Pragma("unroll") for (int k = 0; k < 2; ++k) \
;         acc[ai][bj][m][n] = __builtin_amdgcn_mfma_f32_16x16x32_bf16(Bt[n][k], At[m][k], acc[ai][bj][m][n], 0, 0, 0); __builtin_amdgcn_s_setprio(0); } while (0)
; #define PG8_WAIT_V(n) asm volatile("s_waitcnt vmcnt(" #n ")" ::: "memory")
; #define PG8_WAIT_L(n) asm volatile("s_waitcnt lgkmcnt(" #n ")" ::: "memory")
; #define PG8_BAR __builtin_amdgcn_s_barrier()
; #define PG8_SCHED __builtin_amdgcn_sched_barrier(0)
; template <class Epi, class Sched>
; __device__ __forceinline__ void gemm_phase(LAS unsigned char* lds, const Gemm g, const Sched& S, const Epi& E, int tid_in) {
;     ...
;             PG8_WAIT_V(8); PG8_WAIT_L(0); PG8_BAR; PG8_MMA(0, 0, At, B0); PG8_MMA(0, 1, At, B1); PG8_BAR; PG8_SCHED;
;             PG8_LDA(At, 1, 1); PG8_STAGE(PG8_SB(1, 0), b3, voffB); PG8_STAGE(PG8_SB(1, 1), b3 + hstep, voffB);
;             PG8_WAIT_V(6); PG8_WAIT_L(0); PG8_BAR; PG8_MMA(1, 0, At, B0); PG8_MMA(1, 1, At, B1); PG8_BAR; PG8_SCHED;
;         }
;         if (wr == 0) PG8_BAR;
	s_setprio 3
	v_mfma_f32_16x16x32_bf16 v[124:127], v[132:135], v[180:183], v[124:127]
	v_mfma_f32_16x16x32_bf16 v[120:123], v[140:143], v[180:183], v[120:123]
	v_mfma_f32_16x16x32_bf16 v[116:119], v[132:135], v[196:199], v[116:119]
	v_mfma_f32_16x16x32_bf16 v[112:115], v[140:143], v[196:199], v[112:115]
	v_mfma_f32_16x16x32_bf16 v[108:111], v[132:135], v[204:207], v[108:111]
	v_mfma_f32_16x16x32_bf16 v[104:107], v[140:143], v[204:207], v[104:107]
	v_mfma_f32_16x16x32_bf16 v[100:103], v[132:135], v[212:215], v[100:103]
	v_mfma_f32_16x16x32_bf16 v[96:99], v[140:143], v[212:215], v[96:99]
	v_mfma_f32_16x16x32_bf16 v[124:127], v[136:139], v[192:195], v[124:127]
	v_mfma_f32_16x16x32_bf16 v[120:123], v[144:147], v[192:195], v[120:123]
	v_mfma_f32_16x16x32_bf16 v[116:119], v[136:139], v[200:203], v[116:119]
	v_mfma_f32_16x16x32_bf16 v[112:115], v[144:147], v[200:203], v[112:115]
	v_mfma_f32_16x16x32_bf16 v[108:111], v[136:139], v[208:211], v[108:111]
	v_mfma_f32_16x16x32_bf16 v[104:107], v[144:147], v[208:211], v[104:107]
	v_mfma_f32_16x16x32_bf16 v[100:103], v[136:139], v[216:219], v[100:103]
	v_mfma_f32_16x16x32_bf16 v[96:99], v[144:147], v[216:219], v[96:99]
	s_setprio 0
	s_setprio 3
	v_mfma_f32_16x16x32_bf16 v[92:95], v[148:151], v[180:183], v[92:95]
	v_mfma_f32_16x16x32_bf16 v[88:91], v[172:175], v[180:183], v[88:91]
	v_mfma_f32_16x16x32_bf16 v[84:87], v[148:151], v[196:199], v[84:87]
	v_mfma_f32_16x16x32_bf16 v[80:83], v[172:175], v[196:199], v[80:83]
	v_mfma_f32_16x16x32_bf16 v[76:79], v[148:151], v[204:207], v[76:79]
	v_mfma_f32_16x16x32_bf16 v[72:75], v[172:175], v[204:207], v[72:75]
	v_mfma_f32_16x16x32_bf16 v[68:71], v[148:151], v[212:215], v[68:71]
	v_mfma_f32_16x16x32_bf16 v[64:67], v[172:175], v[212:215], v[64:67]
	v_mfma_f32_16x16x32_bf16 v[92:95], v[152:155], v[192:195], v[92:95]
	v_mfma_f32_16x16x32_bf16 v[88:91], v[176:179], v[192:195], v[88:91]
	v_mfma_f32_16x16x32_bf16 v[84:87], v[152:155], v[200:203], v[84:87]
	v_mfma_f32_16x16x32_bf16 v[80:83], v[176:179], v[200:203], v[80:83]
	v_mfma_f32_16x16x32_bf16 v[76:79], v[152:155], v[208:211], v[76:79]
	v_mfma_f32_16x16x32_bf16 v[72:75], v[176:179], v[208:211], v[72:75]
	v_mfma_f32_16x16x32_bf16 v[68:71], v[152:155], v[216:219], v[68:71]
	v_mfma_f32_16x16x32_bf16 v[64:67], v[176:179], v[216:219], v[64:67]
	s_setprio 0
	s_barrier
	s_add_i32 s44, s80, s2
	v_lshl_add_u64 v[184:185], v[184:185], 0, s[14:15]
	s_mov_b32 m0, s44
	ds_read_b128 v[180:183], v190 offset:49152
	ds_read_b128 v[192:195], v190 offset:50176
	ds_read_b128 v[196:199], v190 offset:51200
	ds_read_b128 v[200:203], v190 offset:52224
	ds_read_b128 v[204:207], v190 offset:53248
	ds_read_b128 v[208:211], v190 offset:54272
	ds_read_b128 v[212:215], v190 offset:55296
	ds_read_b128 v[216:219], v190 offset:56320
	global_load_lds_dwordx4 v[184:185], off
	s_add_i32 m0, s44, 0x2000
	s_add_u32 s42, s42, 0x80080
	v_lshl_add_u64 v[184:185], v[220:221], 0, s[14:15]
	s_addc_u32 s43, s43, 0
	s_add_i32 s44, s81, s2
	global_load_lds_dwordx4 v[184:185], off
	v_lshl_add_u64 v[184:185], s[42:43], 0, v[158:159]
	s_mov_b32 m0, s44
	s_nop 0
	global_load_lds_dwordx4 v[184:185], off
	v_lshl_add_u64 v[184:185], s[42:43], 0, v[162:163]
	s_add_i32 m0, s44, 0x2000
	s_nop 0
	global_load_lds_dwordx4 v[184:185], off
	s_waitcnt vmcnt(6)
	s_waitcnt lgkmcnt(0)
	s_barrier
	s_setprio 3
	v_mfma_f32_16x16x32_bf16 v[60:63], v[132:135], v[180:183], v[60:63]
	v_mfma_f32_16x16x32_bf16 v[56:59], v[140:143], v[180:183], v[56:59]
	v_mfma_f32_16x16x32_bf16 v[52:55], v[132:135], v[196:199], v[52:55]
	v_mfma_f32_16x16x32_bf16 v[48:51], v[140:143], v[196:199], v[48:51]
	v_mfma_f32_16x16x32_bf16 v[44:47], v[132:135], v[204:207], v[44:47]
	v_mfma_f32_16x16x32_bf16 v[40:43], v[140:143], v[204:207], v[40:43]
	v_mfma_f32_16x16x32_bf16 v[36:39], v[132:135], v[212:215], v[36:39]
	v_mfma_f32_16x16x32_bf16 v[32:35], v[140:143], v[212:215], v[32:35]
	v_mfma_f32_16x16x32_bf16 v[60:63], v[136:139], v[192:195], v[60:63]
	v_mfma_f32_16x16x32_bf16 v[56:59], v[144:147], v[192:195], v[56:59]
	v_mfma_f32_16x16x32_bf16 v[52:55], v[136:139], v[200:203], v[52:55]
	v_mfma_f32_16x16x32_bf16 v[48:51], v[144:147], v[200:203], v[48:51]
	v_mfma_f32_16x16x32_bf16 v[44:47], v[136:139], v[208:211], v[44:47]
	v_mfma_f32_16x16x32_bf16 v[40:43], v[144:147], v[208:211], v[40:43]
	v_mfma_f32_16x16x32_bf16 v[36:39], v[136:139], v[216:219], v[36:39]
	v_mfma_f32_16x16x32_bf16 v[32:35], v[144:147], v[216:219], v[32:35]
	s_setprio 0
	s_setprio 3
	v_mfma_f32_16x16x32_bf16 v[28:31], v[148:151], v[180:183], v[28:31]
	v_mfma_f32_16x16x32_bf16 v[24:27], v[172:175], v[180:183], v[24:27]
	v_mfma_f32_16x16x32_bf16 v[20:23], v[148:151], v[196:199], v[20:23]
	v_mfma_f32_16x16x32_bf16 v[16:19], v[172:175], v[196:199], v[16:19]
	v_mfma_f32_16x16x32_bf16 v[12:15], v[148:151], v[204:207], v[12:15]
	v_mfma_f32_16x16x32_bf16 v[8:11], v[172:175], v[204:207], v[8:11]
	v_mfma_f32_16x16x32_bf16 v[4:7], v[148:151], v[212:215], v[4:7]
	v_mfma_f32_16x16x32_bf16 v[0:3], v[172:175], v[212:215], v[0:3]
	v_mfma_f32_16x16x32_bf16 v[28:31], v[152:155], v[192:195], v[28:31]
	v_mfma_f32_16x16x32_bf16 v[24:27], v[176:179], v[192:195], v[24:27]
	v_mfma_f32_16x16x32_bf16 v[20:23], v[152:155], v[200:203], v[20:23]
	v_mfma_f32_16x16x32_bf16 v[16:19], v[176:179], v[200:203], v[16:19]
	v_mfma_f32_16x16x32_bf16 v[12:15], v[152:155], v[208:211], v[12:15]
	v_mfma_f32_16x16x32_bf16 v[8:11], v[176:179], v[208:211], v[8:11]
	v_mfma_f32_16x16x32_bf16 v[4:7], v[152:155], v[216:219], v[4:7]
	v_mfma_f32_16x16x32_bf16 v[0:3], v[176:179], v[216:219], v[0:3]
	s_setprio 0
	s_barrier
	s_add_i32 s79, s79, 2
	s_add_u32 s40, s40, 0x100
	s_addc_u32 s41, s41, 0
	s_cmp_gt_u32 s79, 13
	s_cbranch_scc0 .LBB0_511
	s_and_b64 vcc, exec, s[18:19]
	s_cbranch_vccz .LBB0_514
	s_barrier

; #define PG8_STAGE(bufoff, gbase, voff) do { _Pragma("unroll") for (int _i = 0; _i < 2; ++_i) \
;         __builtin_amdgcn_global_load_lds((const unsigned*)((const char*)(gbase) + (voff)[_i]), (LAS unsigned*)(lds + (bufoff) + ldsw + _i * 8192), 16, 0, 0); } while (0)
; #define PG8_LDA(dst, b, h) do { _Pragma("unroll") for (int m = 0; m < 4; ++m) _Pragma("unroll") for (int k = 0; k < 2; ++k) dst[m][k] = *(const LAS bf16x8*)(lds + PG8_SA(b, h) + aoff + m * 2048 + k * 1024); } while (0)
; #define PG8_LDB(dst, b, h) do { _Pragma("unroll") for (int n = 0; n < 2; ++n) _Pragma("unroll") for (int k = 0; k < 2; ++k) dst[n][k] = *(const LAS bf16x8*)(lds + PG8_SB(b, h) + boff + n * 2048 + k * 1024); } while (0)
; #define PG8_MMA(ai, bj, At, Bt) do { __builtin_amdgcn_s_setprio(3); _Pragma("unroll") for (int m = 0; m < 4; ++m) _Pragma("unroll") for (int n = 0; n < 2; ++n) _Pragma("unroll") for (int k = 0; k < 2; ++k) \
;         acc[ai][bj][m][n] = __builtin_amdgcn_mfma_f32_16x16x32_bf16(Bt[n][k], At[m][k], acc[ai][bj][m][n], 0, 0, 0); __builtin_amdgcn_s_setprio(0); } while (0)
; #define PG8_WAIT_V(n) asm volatile("s_waitcnt vmcnt(" #n ")" ::: "memory")
; template <class Epi, class Sched>
; __device__ __forceinline__ void gemm_phase(LAS unsigned char* lds, const Gemm g, const Sched& S, const Epi& E, int tid_in) {
;     ...
;         const char* nA = has_next ? (const char*)g.A + (size_t)nxt.pm * tstep + nxt.koff : cA; const char* nB = has_next ? (const char*)g.Bt + (size_t)nxt.pn * tstep + nxt.koff : cB;
;         for (int t = 0; t < nt; t += 2) {
;             const bool last = (t == nt - 2);
;             const char* a1 = cA + (size_t)(t + 1) * kstep;
;             const char* a2 = last ? nA : cA + (size_t)(t + 2) * kstep; const char* b2 = last ? nB : cB + (size_t)(t + 2) * kstep;
;             const char* a3 = a2 + kstep; const char* b3 = b2 + kstep;
;             PG8_LDB(B0, 0, 0); PG8_LDB(B1, 0, 1); PG8_SCHED; PG8_LDA(At, 0, 0); PG8_STAGE(PG8_SA(1, 0), a1, voffA); PG8_STAGE(PG8_SA(1, 1), a1 + hstep, voffA);
;             PG8_WAIT_V(8); PG8_WAIT_L(0); PG8_BAR; PG8_MMA(0, 0, At, B0); PG8_MMA(0, 1, At, B1); PG8_BAR; PG8_SCHED;
;             PG8_LDA(At, 0, 1); PG8_STAGE(PG8_SB(0, 0), b2, voffB); PG8_STAGE(PG8_SB(0, 1), b2 + hstep, voffB);
;             PG8_WAIT_V(6); PG8_WAIT_L(0); PG8_BAR; PG8_MMA(1, 0, At, B0); PG8_MMA(1, 1, At, B1); PG8_BAR; PG8_SCHED;
.LBB0_619:
	s_ashr_i32 s25, s24, 31
	s_lshl_b64 s[26:27], s[24:25], 20
	s_add_u32 s26, s8, s26
	s_addc_u32 s27, s9, s27
	s_and_b64 s[28:29], s[4:5], exec
	s_cselect_b32 s25, s27, s35
	s_cselect_b32 s31, s26, s34
	s_ashr_i32 s23, s22, 31
	s_lshl_b64 s[28:29], s[22:23], 20
	s_add_u32 s28, s68, s28
	s_addc_u32 s29, s69, s29
	s_and_b64 s[38:39], s[4:5], exec
	s_cselect_b32 s23, s29, s37
	s_cselect_b32 s49, s28, s36
	s_add_u32 s51, s36, 0x100
	s_addc_u32 s70, s37, 0
	v_lshl_add_u64 v[144:145], s[34:35], 0, v[136:137]
	v_lshl_add_u64 v[146:147], s[34:35], 0, v[138:139]
	s_mov_b32 s71, -2
	s_mov_b64 s[36:37], 0
	s_waitcnt lgkmcnt(0)
	ds_read_b128 v[156:159], v151
	ds_read_b128 v[160:163], v151 offset:1024
	ds_read_b128 v[164:167], v151 offset:2048
	ds_read_b128 v[168:171], v151 offset:3072
	ds_read_b128 v[172:175], v152
	ds_read_b128 v[176:179], v152 offset:1024
	ds_read_b128 v[180:183], v152 offset:2048
	ds_read_b128 v[188:191], v152 offset:3072
	s_add_u32 s38, s34, s36
	s_addc_u32 s39, s35, s37
	s_add_u32 s40, s38, 0x100
	s_addc_u32 s41, s39, 0
	s_add_u32 s38, s51, s36
	s_addc_u32 s39, s70, s37
	s_cmpk_eq_i32 s36, 0xf00
	s_cselect_b32 s39, s23, s39
	s_cselect_b32 s38, s49, s38
	s_cselect_b32 s41, s25, s41
	s_cselect_b32 s40, s31, s40
	v_lshl_add_u64 v[184:185], v[144:145], 0, s[36:37]
	v_lshl_add_u64 v[224:225], v[184:185], 0, s[16:17]
	s_add_i32 m0, s3, 0x8000
	ds_read_b128 v[192:195], v153
	ds_read_b128 v[196:199], v153 offset:1024
	ds_read_b128 v[200:203], v153 offset:2048
	ds_read_b128 v[204:207], v153 offset:3072
	ds_read_b128 v[208:211], v153 offset:4096
	ds_read_b128 v[212:215], v153 offset:5120
	ds_read_b128 v[216:219], v153 offset:6144
	ds_read_b128 v[220:223], v153 offset:7168
	global_load_lds_dwordx4 v[224:225], off
	v_lshl_add_u64 v[224:225], v[146:147], 0, s[36:37]
	v_lshl_add_u64 v[226:227], v[224:225], 0, s[16:17]
	s_add_i32 m0, s3, 0xa000
	v_lshl_add_u64 v[184:185], v[184:185], 0, s[18:19]
	global_load_lds_dwordx4 v[226:227], off
	s_add_i32 m0, s3, 0xc000
	s_nop 0
	global_load_lds_dwordx4 v[184:185], off
	v_lshl_add_u64 v[184:185], v[224:225], 0, s[18:19]
	s_add_i32 m0, s3, 0xe000
	s_nop 0
	global_load_lds_dwordx4 v[184:185], off
	s_waitcnt vmcnt(8)
	s_waitcnt lgkmcnt(0)
	s_barrier
	s_setprio 3
	v_mfma_f32_16x16x32_bf16 v[124:127], v[156:159], v[192:195], 0
	v_mfma_f32_16x16x32_bf16 v[120:123], v[164:167], v[192:195], 0
	v_mfma_f32_16x16x32_bf16 v[108:111], v[156:159], v[200:203], 0
	v_mfma_f32_16x16x32_bf16 v[104:107], v[164:167], v[200:203], 0
	v_mfma_f32_16x16x32_bf16 v[92:95], v[156:159], v[208:211], 0
	v_mfma_f32_16x16x32_bf16 v[88:91], v[164:167], v[208:211], 0
	v_mfma_f32_16x16x32_bf16 v[76:79], v[156:159], v[216:219], 0
	v_mfma_f32_16x16x32_bf16 v[72:75], v[164:167], v[216:219], 0
	v_mfma_f32_16x16x32_bf16 v[124:127], v[160:163], v[196:199], v[124:127]
	v_mfma_f32_16x16x32_bf16 v[120:123], v[168:171], v[196:199], v[120:123]
	v_mfma_f32_16x16x32_bf16 v[108:111], v[160:163], v[204:207], v[108:111]
	v_mfma_f32_16x16x32_bf16 v[104:107], v[168:171], v[204:207], v[104:107]
	v_mfma_f32_16x16x32_bf16 v[92:95], v[160:163], v[212:215], v[92:95]
	v_mfma_f32_16x16x32_bf16 v[88:91], v[168:171], v[212:215], v[88:91]
	v_mfma_f32_16x16x32_bf16 v[76:79], v[160:163], v[220:223], v[76:79]
	v_mfma_f32_16x16x32_bf16 v[72:75], v[168:171], v[220:223], v[72:75]
	s_setprio 0
	s_setprio 3
	v_mfma_f32_16x16x32_bf16 v[116:119], v[172:175], v[192:195], 0
	v_mfma_f32_16x16x32_bf16 v[112:115], v[180:183], v[192:195], 0
	v_mfma_f32_16x16x32_bf16 v[100:103], v[172:175], v[200:203], 0
	v_mfma_f32_16x16x32_bf16 v[96:99], v[180:183], v[200:203], 0
	v_mfma_f32_16x16x32_bf16 v[84:87], v[172:175], v[208:211], 0
	v_mfma_f32_16x16x32_bf16 v[80:83], v[180:183], v[208:211], 0
	v_mfma_f32_16x16x32_bf16 v[68:71], v[172:175], v[216:219], 0
	v_mfma_f32_16x16x32_bf16 v[64:67], v[180:183], v[216:219], 0
	v_mfma_f32_16x16x32_bf16 v[116:119], v[176:179], v[196:199], v[116:119]
	v_mfma_f32_16x16x32_bf16 v[112:115], v[188:191], v[196:199], v[112:115]
	v_mfma_f32_16x16x32_bf16 v[100:103], v[176:179], v[204:207], v[100:103]
	v_mfma_f32_16x16x32_bf16 v[96:99], v[188:191], v[204:207], v[96:99]
	v_mfma_f32_16x16x32_bf16 v[84:87], v[176:179], v[212:215], v[84:87]
	v_mfma_f32_16x16x32_bf16 v[80:83], v[188:191], v[212:215], v[80:83]
	v_mfma_f32_16x16x32_bf16 v[68:71], v[176:179], v[220:223], v[68:71]
	v_mfma_f32_16x16x32_bf16 v[64:67], v[188:191], v[220:223], v[64:67]
	s_setprio 0
	s_barrier
	s_add_i32 s72, s46, s2
	v_lshl_add_u64 v[184:185], s[38:39], 0, v[130:131]
	s_mov_b32 m0, s72
	ds_read_b128 v[192:195], v153 offset:16384
	ds_read_b128 v[196:199], v153 offset:17408
	ds_read_b128 v[200:203], v153 offset:18432
	ds_read_b128 v[204:207], v153 offset:19456
	ds_read_b128 v[208:211], v153 offset:20480
	ds_read_b128 v[212:215], v153 offset:21504
	ds_read_b128 v[216:219], v153 offset:22528
	ds_read_b128 v[220:223], v153 offset:23552
	global_load_lds_dwordx4 v[184:185], off
	s_add_i32 m0, s72, 0x2000
	s_add_u32 s72, s38, 0x80000
	v_lshl_add_u64 v[224:225], s[38:39], 0, v[134:135]
	s_addc_u32 s73, s39, 0
	s_add_i32 s74, s47, s2
	global_load_lds_dwordx4 v[224:225], off
	v_lshl_add_u64 v[226:227], s[72:73], 0, v[130:131]
	s_mov_b32 m0, s74
	s_nop 0
	global_load_lds_dwordx4 v[226:227], off
	v_lshl_add_u64 v[226:227], s[72:73], 0, v[134:135]
	s_add_i32 m0, s74, 0x2000
	s_nop 0
	global_load_lds_dwordx4 v[226:227], off
	s_waitcnt vmcnt(6)
	s_waitcnt lgkmcnt(0)
	s_barrier
; #define PG8_STAGE(bufoff, gbase, voff) do { _Pragma("unroll") for (int _i = 0; _i < 2; ++_i) \
;         __builtin_amdgcn_global_load_lds((const unsigned*)((const char*)(gbase) + (voff)[_i]), (LAS unsigned*)(lds + (bufoff) + ldsw + _i * 8192), 16, 0, 0); } while (0)
; #define PG8_LDA(dst, b, h) do { _Pragma("unroll") for (int m = 0; m < 4; ++m) _Pragma("unroll") for (int k = 0; k < 2; ++k) dst[m][k] = *(const LAS bf16x8*)(lds + PG8_SA(b, h) + aoff + m * 2048 + k * 1024); } while (0)
; #define PG8_LDB(dst, b, h) do { _Pragma("unroll") for (int n = 0; n < 2; ++n) _Pragma("unroll") for (int k = 0; k < 2; ++k) dst[n][k] = *(const LAS bf16x8*)(lds + PG8_SB(b, h) + boff + n * 2048 + k * 1024); } while (0)
; #define PG8_MMA(ai, bj, At, Bt) do { __builtin_amdgcn_s_setprio(3); _Pragma("unroll") for (int m = 0; m < 4; ++m) _Pragma("unroll") for (int n = 0; n < 2; ++n) _Pragma("unroll") for (int k = 0; k < 2; ++k) \
;         acc[ai][bj][m][n] = __builtin_amdgcn_mfma_f32_16x16x32_bf16(Bt[n][k], At[m][k], acc[ai][bj][m][n], 0, 0, 0); __builtin_amdgcn_s_setprio(0); } while (0)
; #define PG8_WAIT_V(n) asm volatile("s_waitcnt vmcnt(" #n ")" ::: "memory")
; #define PG8_WAIT_L(n) asm volatile("s_waitcnt lgkmcnt(" #n ")" ::: "memory")
; #define PG8_BAR __builtin_amdgcn_s_barrier()
; #define PG8_SCHED __builtin_amdgcn_sched_barrier(0)
; template <class Epi, class Sched>
; __device__ __forceinline__ void gemm_phase(LAS unsigned char* lds, const Gemm g, const Sched& S, const Epi& E, int tid_in) {
;     ...
;             PG8_WAIT_V(6); PG8_WAIT_L(0); PG8_BAR; PG8_MMA(1, 0, At, B0); PG8_MMA(1, 1, At, B1); PG8_BAR; PG8_SCHED;
;             PG8_LDB(B0, 1, 0); PG8_LDB(B1, 1, 1); PG8_SCHED; PG8_LDA(At, 1, 0); PG8_STAGE(PG8_SA(0, 0), a2, voffA); PG8_STAGE(PG8_SA(0, 1), a2 + hstep, voffA);
;             PG8_WAIT_V(8); PG8_WAIT_L(0); PG8_BAR; PG8_MMA(0, 0, At, B0); PG8_MMA(0, 1, At, B1); PG8_BAR; PG8_SCHED;
;             PG8_LDA(At, 1, 1); PG8_STAGE(PG8_SB(1, 0), b3, voffB); PG8_STAGE(PG8_SB(1, 1), b3 + hstep, voffB);
;             PG8_WAIT_V(6); PG8_WAIT_L(0); PG8_BAR; PG8_MMA(1, 0, At, B0); PG8_MMA(1, 1, At, B1); PG8_BAR; PG8_SCHED;
	s_setprio 3
	v_mfma_f32_16x16x32_bf16 v[60:63], v[156:159], v[192:195], 0
	v_mfma_f32_16x16x32_bf16 v[56:59], v[164:167], v[192:195], 0
	v_mfma_f32_16x16x32_bf16 v[44:47], v[156:159], v[200:203], 0
	v_mfma_f32_16x16x32_bf16 v[40:43], v[164:167], v[200:203], 0
	v_mfma_f32_16x16x32_bf16 v[28:31], v[156:159], v[208:211], 0
	v_mfma_f32_16x16x32_bf16 v[24:27], v[164:167], v[208:211], 0
	v_mfma_f32_16x16x32_bf16 v[12:15], v[156:159], v[216:219], 0
	v_mfma_f32_16x16x32_bf16 v[8:11], v[164:167], v[216:219], 0
	v_mfma_f32_16x16x32_bf16 v[60:63], v[160:163], v[196:199], v[60:63]
	v_mfma_f32_16x16x32_bf16 v[56:59], v[168:171], v[196:199], v[56:59]
	v_mfma_f32_16x16x32_bf16 v[44:47], v[160:163], v[204:207], v[44:47]
	v_mfma_f32_16x16x32_bf16 v[40:43], v[168:171], v[204:207], v[40:43]
	v_mfma_f32_16x16x32_bf16 v[28:31], v[160:163], v[212:215], v[28:31]
	v_mfma_f32_16x16x32_bf16 v[24:27], v[168:171], v[212:215], v[24:27]
	v_mfma_f32_16x16x32_bf16 v[12:15], v[160:163], v[220:223], v[12:15]
	v_mfma_f32_16x16x32_bf16 v[8:11], v[168:171], v[220:223], v[8:11]
	s_setprio 0
	s_setprio 3
	v_mfma_f32_16x16x32_bf16 v[52:55], v[172:175], v[192:195], 0
	v_mfma_f32_16x16x32_bf16 v[48:51], v[180:183], v[192:195], 0
	v_mfma_f32_16x16x32_bf16 v[36:39], v[172:175], v[200:203], 0
	v_mfma_f32_16x16x32_bf16 v[32:35], v[180:183], v[200:203], 0
	v_mfma_f32_16x16x32_bf16 v[20:23], v[172:175], v[208:211], 0
	v_mfma_f32_16x16x32_bf16 v[16:19], v[180:183], v[208:211], 0
	v_mfma_f32_16x16x32_bf16 v[4:7], v[172:175], v[216:219], 0
	v_mfma_f32_16x16x32_bf16 v[0:3], v[180:183], v[216:219], 0
	v_mfma_f32_16x16x32_bf16 v[52:55], v[176:179], v[196:199], v[52:55]
	v_mfma_f32_16x16x32_bf16 v[48:51], v[188:191], v[196:199], v[48:51]
	v_mfma_f32_16x16x32_bf16 v[36:39], v[176:179], v[204:207], v[36:39]
	v_mfma_f32_16x16x32_bf16 v[32:35], v[188:191], v[204:207], v[32:35]
	v_mfma_f32_16x16x32_bf16 v[20:23], v[176:179], v[212:215], v[20:23]
	v_mfma_f32_16x16x32_bf16 v[16:19], v[188:191], v[212:215], v[16:19]
	v_mfma_f32_16x16x32_bf16 v[4:7], v[176:179], v[220:223], v[4:7]
	v_mfma_f32_16x16x32_bf16 v[0:3], v[188:191], v[220:223], v[0:3]
	s_setprio 0
	s_barrier
	s_add_i32 s72, 0, 0x18000
	v_add_u32_e32 v155, s72, v149
	s_add_i32 s73, 0, 0x1c000
	ds_read_b128 v[156:159], v155
	ds_read_b128 v[160:163], v155 offset:1024
	ds_read_b128 v[164:167], v155 offset:2048
	ds_read_b128 v[168:171], v155 offset:3072
	v_add_u32_e32 v155, s73, v149
	ds_read_b128 v[172:175], v155
	ds_read_b128 v[176:179], v155 offset:1024
	ds_read_b128 v[180:183], v155 offset:2048
	ds_read_b128 v[188:191], v155 offset:3072
	s_mov_b32 m0, s3
	v_lshl_add_u64 v[226:227], s[40:41], 0, v[128:129]
	ds_read_b128 v[192:195], v153 offset:32768
	ds_read_b128 v[196:199], v153 offset:33792
	ds_read_b128 v[200:203], v153 offset:34816
	ds_read_b128 v[204:207], v153 offset:35840
	ds_read_b128 v[208:211], v153 offset:36864
	ds_read_b128 v[212:215], v153 offset:37888
	ds_read_b128 v[216:219], v153 offset:38912
	ds_read_b128 v[220:223], v153 offset:39936
	global_load_lds_dwordx4 v[226:227], off
	v_lshl_add_u64 v[226:227], s[40:41], 0, v[132:133]
	s_add_u32 s40, s40, 0x80000
	s_mov_b32 m0, s42
	s_addc_u32 s41, s41, 0
	global_load_lds_dwordx4 v[226:227], off
	v_lshl_add_u64 v[226:227], s[40:41], 0, v[128:129]
	s_mov_b32 m0, s43
	s_nop 0
	global_load_lds_dwordx4 v[226:227], off
	v_lshl_add_u64 v[226:227], s[40:41], 0, v[132:133]
	s_mov_b32 m0, s44
	s_nop 0
	global_load_lds_dwordx4 v[226:227], off
	s_waitcnt vmcnt(8)
	s_waitcnt lgkmcnt(0)
	s_barrier
	s_setprio 3
	v_mfma_f32_16x16x32_bf16 v[124:127], v[156:159], v[192:195], v[124:127]
	v_mfma_f32_16x16x32_bf16 v[120:123], v[164:167], v[192:195], v[120:123]
	v_mfma_f32_16x16x32_bf16 v[108:111], v[156:159], v[200:203], v[108:111]
	v_mfma_f32_16x16x32_bf16 v[104:107], v[164:167], v[200:203], v[104:107]
	v_mfma_f32_16x16x32_bf16 v[92:95], v[156:159], v[208:211], v[92:95]
	v_mfma_f32_16x16x32_bf16 v[88:91], v[164:167], v[208:211], v[88:91]
	v_mfma_f32_16x16x32_bf16 v[76:79], v[156:159], v[216:219], v[76:79]
	v_mfma_f32_16x16x32_bf16 v[72:75], v[164:167], v[216:219], v[72:75]
	v_mfma_f32_16x16x32_bf16 v[124:127], v[160:163], v[196:199], v[124:127]
	v_mfma_f32_16x16x32_bf16 v[120:123], v[168:171], v[196:199], v[120:123]
	v_mfma_f32_16x16x32_bf16 v[108:111], v[160:163], v[204:207], v[108:111]
	v_mfma_f32_16x16x32_bf16 v[104:107], v[168:171], v[204:207], v[104:107]
	v_mfma_f32_16x16x32_bf16 v[92:95], v[160:163], v[212:215], v[92:95]
	v_mfma_f32_16x16x32_bf16 v[88:91], v[168:171], v[212:215], v[88:91]
	v_mfma_f32_16x16x32_bf16 v[76:79], v[160:163], v[220:223], v[76:79]
	v_mfma_f32_16x16x32_bf16 v[72:75], v[168:171], v[220:223], v[72:75]
	s_setprio 0
	s_setprio 3
	v_mfma_f32_16x16x32_bf16 v[116:119], v[172:175], v[192:195], v[116:119]
	v_mfma_f32_16x16x32_bf16 v[112:115], v[180:183], v[192:195], v[112:115]
	v_mfma_f32_16x16x32_bf16 v[100:103], v[172:175], v[200:203], v[100:103]
	v_mfma_f32_16x16x32_bf16 v[96:99], v[180:183], v[200:203], v[96:99]
	v_mfma_f32_16x16x32_bf16 v[84:87], v[172:175], v[208:211], v[84:87]
	v_mfma_f32_16x16x32_bf16 v[80:83], v[180:183], v[208:211], v[80:83]
	v_mfma_f32_16x16x32_bf16 v[68:71], v[172:175], v[216:219], v[68:71]
	v_mfma_f32_16x16x32_bf16 v[64:67], v[180:183], v[216:219], v[64:67]
	v_mfma_f32_16x16x32_bf16 v[116:119], v[176:179], v[196:199], v[116:119]
	v_mfma_f32_16x16x32_bf16 v[112:115], v[188:191], v[196:199], v[112:115]
	v_mfma_f32_16x16x32_bf16 v[100:103], v[176:179], v[204:207], v[100:103]
	v_mfma_f32_16x16x32_bf16 v[96:99], v[188:191], v[204:207], v[96:99]
	v_mfma_f32_16x16x32_bf16 v[84:87], v[176:179], v[212:215], v[84:87]
	v_mfma_f32_16x16x32_bf16 v[80:83], v[188:191], v[212:215], v[80:83]
	v_mfma_f32_16x16x32_bf16 v[68:71], v[176:179], v[220:223], v[68:71]
	v_mfma_f32_16x16x32_bf16 v[64:67], v[188:191], v[220:223], v[64:67]
	s_setprio 0
	s_barrier
; #define PG8_STAGE(bufoff, gbase, voff) do { _Pragma("unroll") for (int _i = 0; _i < 2; ++_i) \
;         __builtin_amdgcn_global_load_lds((const unsigned*)((const char*)(gbase) + (voff)[_i]), (LAS unsigned*)(lds + (bufoff) + ldsw + _i * 8192), 16, 0, 0); } while (0)
; #define PG8_LDA(dst, b, h) do { _Pragma("unroll") for (int m = 0; m < 4; ++m) _Pragma("unroll") for (int k = 0; k < 2; ++k) dst[m][k] = *(const LAS bf16x8*)(lds + PG8_SA(b, h) + aoff + m * 2048 + k * 1024); } while (0)
; #define PG8_LDB(dst, b, h) do { _Pragma("unroll") for (int n = 0; n < 2; ++n) _Pragma("unroll") for (int k = 0; k < 2; ++k) dst[n][k] = *(const LAS bf16x8*)(lds + PG8_SB(b, h) + boff + n * 2048 + k * 1024); } while (0)
; #define PG8_MMA(ai, bj, At, Bt) do { __builtin_amdgcn_s_setprio(3); _Pragma("unroll") for (int m = 0; m < 4; ++m) _Pragma("unroll") for (int n = 0; n < 2; ++n) _Pragma("unroll") for (int k = 0; k < 2; ++k) \
;         acc[ai][bj][m][n] = __builtin_amdgcn_mfma_f32_16x16x32_bf16(Bt[n][k], At[m][k], acc[ai][bj][m][n], 0, 0, 0); __builtin_amdgcn_s_setprio(0); } while (0)
; #define PG8_WAIT_V(n) asm volatile("s_waitcnt vmcnt(" #n ")" ::: "memory")
; #define PG8_WAIT_L(n) asm volatile("s_waitcnt lgkmcnt(" #n ")" ::: "memory")
; #define PG8_BAR __builtin_amdgcn_s_barrier()
; #define PG8_SCHED __builtin_amdgcn_sched_barrier(0)
; template <class Epi, class Sched>
; __device__ __forceinline__ void gemm_phase(LAS unsigned char* lds, const Gemm g, const Sched& S, const Epi& E, int tid_in) {
;     ...
;             PG8_LDB(B0, 0, 0); PG8_LDB(B1, 0, 1); PG8_SCHED; PG8_LDA(At, 0, 0); PG8_STAGE(PG8_SA(1, 0), a1, voffA); PG8_STAGE(PG8_SA(1, 1), a1 + hstep, voffA);
;             PG8_WAIT_V(8); PG8_WAIT_L(0); PG8_BAR; PG8_MMA(0, 0, At, B0); PG8_MMA(0, 1, At, B1); PG8_BAR; PG8_SCHED;
;     ...
;             PG8_LDB(B0, 1, 0); PG8_LDB(B1, 1, 1); PG8_SCHED; PG8_LDA(At, 1, 0); PG8_STAGE(PG8_SA(0, 0), a2, voffA); PG8_STAGE(PG8_SA(0, 1), a2 + hstep, voffA);
;             PG8_WAIT_V(8); PG8_WAIT_L(0); PG8_BAR; PG8_MMA(0, 0, At, B0); PG8_MMA(0, 1, At, B1); PG8_BAR; PG8_SCHED;
;             PG8_LDA(At, 1, 1); PG8_STAGE(PG8_SB(1, 0), b3, voffB); PG8_STAGE(PG8_SB(1, 1), b3 + hstep, voffB);
;             PG8_WAIT_V(6); PG8_WAIT_L(0); PG8_BAR; PG8_MMA(1, 0, At, B0); PG8_MMA(1, 1, At, B1); PG8_BAR; PG8_SCHED;
;         }
	s_add_i32 s40, s72, s2
	v_lshl_add_u64 v[184:185], v[184:185], 0, s[16:17]
	s_mov_b32 m0, s40
	ds_read_b128 v[192:195], v153 offset:49152
	ds_read_b128 v[196:199], v153 offset:50176
	ds_read_b128 v[200:203], v153 offset:51200
	ds_read_b128 v[204:207], v153 offset:52224
	ds_read_b128 v[208:211], v153 offset:53248
	ds_read_b128 v[212:215], v153 offset:54272
	ds_read_b128 v[216:219], v153 offset:55296
	ds_read_b128 v[220:223], v153 offset:56320
	global_load_lds_dwordx4 v[184:185], off
	s_add_i32 m0, s40, 0x2000
	s_add_u32 s38, s38, 0x80080
	v_lshl_add_u64 v[184:185], v[224:225], 0, s[16:17]
	s_addc_u32 s39, s39, 0
	s_add_i32 s40, s73, s2
	global_load_lds_dwordx4 v[184:185], off
	v_lshl_add_u64 v[184:185], s[38:39], 0, v[130:131]
	s_mov_b32 m0, s40
	s_nop 0
	global_load_lds_dwordx4 v[184:185], off
	v_lshl_add_u64 v[184:185], s[38:39], 0, v[134:135]
	s_add_i32 m0, s40, 0x2000
	s_nop 0
	global_load_lds_dwordx4 v[184:185], off
	s_waitcnt vmcnt(6)
	s_waitcnt lgkmcnt(0)
	s_barrier
	s_setprio 3
	v_mfma_f32_16x16x32_bf16 v[60:63], v[156:159], v[192:195], v[60:63]
	v_mfma_f32_16x16x32_bf16 v[56:59], v[164:167], v[192:195], v[56:59]
	v_mfma_f32_16x16x32_bf16 v[44:47], v[156:159], v[200:203], v[44:47]
	v_mfma_f32_16x16x32_bf16 v[40:43], v[164:167], v[200:203], v[40:43]
	v_mfma_f32_16x16x32_bf16 v[28:31], v[156:159], v[208:211], v[28:31]
	v_mfma_f32_16x16x32_bf16 v[24:27], v[164:167], v[208:211], v[24:27]
	v_mfma_f32_16x16x32_bf16 v[12:15], v[156:159], v[216:219], v[12:15]
	v_mfma_f32_16x16x32_bf16 v[8:11], v[164:167], v[216:219], v[8:11]
	v_mfma_f32_16x16x32_bf16 v[60:63], v[160:163], v[196:199], v[60:63]
	v_mfma_f32_16x16x32_bf16 v[56:59], v[168:171], v[196:199], v[56:59]
	v_mfma_f32_16x16x32_bf16 v[44:47], v[160:163], v[204:207], v[44:47]
	v_mfma_f32_16x16x32_bf16 v[40:43], v[168:171], v[204:207], v[40:43]
	v_mfma_f32_16x16x32_bf16 v[28:31], v[160:163], v[212:215], v[28:31]
	v_mfma_f32_16x16x32_bf16 v[24:27], v[168:171], v[212:215], v[24:27]
	v_mfma_f32_16x16x32_bf16 v[12:15], v[160:163], v[220:223], v[12:15]
	v_mfma_f32_16x16x32_bf16 v[8:11], v[168:171], v[220:223], v[8:11]
	s_setprio 0
	s_setprio 3
	v_mfma_f32_16x16x32_bf16 v[52:55], v[172:175], v[192:195], v[52:55]
	v_mfma_f32_16x16x32_bf16 v[48:51], v[180:183], v[192:195], v[48:51]
	v_mfma_f32_16x16x32_bf16 v[36:39], v[172:175], v[200:203], v[36:39]
	v_mfma_f32_16x16x32_bf16 v[32:35], v[180:183], v[200:203], v[32:35]
	v_mfma_f32_16x16x32_bf16 v[20:23], v[172:175], v[208:211], v[20:23]
	v_mfma_f32_16x16x32_bf16 v[16:19], v[180:183], v[208:211], v[16:19]
	v_mfma_f32_16x16x32_bf16 v[4:7], v[172:175], v[216:219], v[4:7]
	v_mfma_f32_16x16x32_bf16 v[0:3], v[180:183], v[216:219], v[0:3]
	v_mfma_f32_16x16x32_bf16 v[52:55], v[176:179], v[196:199], v[52:55]
	v_mfma_f32_16x16x32_bf16 v[48:51], v[188:191], v[196:199], v[48:51]
	v_mfma_f32_16x16x32_bf16 v[36:39], v[176:179], v[204:207], v[36:39]
	v_mfma_f32_16x16x32_bf16 v[32:35], v[188:191], v[204:207], v[32:35]
	v_mfma_f32_16x16x32_bf16 v[20:23], v[176:179], v[212:215], v[20:23]
	v_mfma_f32_16x16x32_bf16 v[16:19], v[188:191], v[212:215], v[16:19]
	v_mfma_f32_16x16x32_bf16 v[4:7], v[176:179], v[220:223], v[4:7]
	v_mfma_f32_16x16x32_bf16 v[0:3], v[188:191], v[220:223], v[0:3]
	s_setprio 0
	s_barrier
	s_add_i32 s71, s71, 2
	s_add_u32 s36, s36, 0x100
	s_addc_u32 s37, s37, 0
	s_cmp_gt_u32 s71, 29
	s_cbranch_scc0 .LBB0_620
	s_branch .Lpeel_exit_1
.LBB0_620:
	ds_read_b128 v[156:159], v151
	ds_read_b128 v[160:163], v151 offset:1024
	ds_read_b128 v[164:167], v151 offset:2048
	ds_read_b128 v[168:171], v151 offset:3072
	ds_read_b128 v[172:175], v152
	ds_read_b128 v[176:179], v152 offset:1024
	ds_read_b128 v[180:183], v152 offset:2048
	ds_read_b128 v[188:191], v152 offset:3072
	s_add_u32 s38, s34, s36
	s_addc_u32 s39, s35, s37
	s_add_u32 s40, s38, 0x100
	s_addc_u32 s41, s39, 0
	s_add_u32 s38, s51, s36
	s_addc_u32 s39, s70, s37
	s_cmpk_eq_i32 s36, 0xf00
	s_cselect_b32 s39, s23, s39
	s_cselect_b32 s38, s49, s38
	s_cselect_b32 s41, s25, s41
	s_cselect_b32 s40, s31, s40
	v_lshl_add_u64 v[184:185], v[144:145], 0, s[36:37]
	v_lshl_add_u64 v[224:225], v[184:185], 0, s[16:17]
	s_add_i32 m0, s3, 0x8000
	ds_read_b128 v[192:195], v153
	ds_read_b128 v[196:199], v153 offset:1024
	ds_read_b128 v[200:203], v153 offset:2048
	ds_read_b128 v[204:207], v153 offset:3072
	ds_read_b128 v[208:211], v153 offset:4096
	ds_read_b128 v[212:215], v153 offset:5120
	ds_read_b128 v[216:219], v153 offset:6144
	ds_read_b128 v[220:223], v153 offset:7168
	global_load_lds_dwordx4 v[224:225], off
	v_lshl_add_u64 v[224:225], v[146:147], 0, s[36:37]
	v_lshl_add_u64 v[226:227], v[224:225], 0, s[16:17]
	s_add_i32 m0, s3, 0xa000
	v_lshl_add_u64 v[184:185], v[184:185], 0, s[18:19]
	global_load_lds_dwordx4 v[226:227], off
	s_add_i32 m0, s3, 0xc000
	s_nop 0
	global_load_lds_dwordx4 v[184:185], off
	v_lshl_add_u64 v[184:185], v[224:225], 0, s[18:19]
	s_add_i32 m0, s3, 0xe000
	s_nop 0
	global_load_lds_dwordx4 v[184:185], off
	s_waitcnt vmcnt(8)
	s_waitcnt lgkmcnt(0)
	s_barrier
; #define PG8_STAGE(bufoff, gbase, voff) do { _Pragma("unroll") for (int _i = 0; _i < 2; ++_i) \
;         __builtin_amdgcn_global_load_lds((const unsigned*)((const char*)(gbase) + (voff)[_i]), (LAS unsigned*)(lds + (bufoff) + ldsw + _i * 8192), 16, 0, 0); } while (0)
; #define PG8_LDA(dst, b, h) do { _Pragma("unroll") for (int m = 0; m < 4; ++m) _Pragma("unroll") for (int k = 0; k < 2; ++k) dst[m][k] = *(const LAS bf16x8*)(lds + PG8_SA(b, h) + aoff + m * 2048 + k * 1024); } while (0)
; #define PG8_LDB(dst, b, h) do { _Pragma("unroll") for (int n = 0; n < 2; ++n) _Pragma("unroll") for (int k = 0; k < 2; ++k) dst[n][k] = *(const LAS bf16x8*)(lds + PG8_SB(b, h) + boff + n * 2048 + k * 1024); } while (0)
; #define PG8_MMA(ai, bj, At, Bt) do { __builtin_amdgcn_s_setprio(3); _Pragma("unroll") for (int m = 0; m < 4; ++m) _Pragma("unroll") for (int n = 0; n < 2; ++n) _Pragma("unroll") for (int k = 0; k < 2; ++k) \
;         acc[ai][bj][m][n] = __builtin_amdgcn_mfma_f32_16x16x32_bf16(Bt[n][k], At[m][k], acc[ai][bj][m][n], 0, 0, 0); __builtin_amdgcn_s_setprio(0); } while (0)
; #define PG8_WAIT_V(n) asm volatile("s_waitcnt vmcnt(" #n ")" ::: "memory")
; #define PG8_WAIT_L(n) asm volatile("s_waitcnt lgkmcnt(" #n ")" ::: "memory")
; #define PG8_BAR __builtin_amdgcn_s_barrier()
; #define PG8_SCHED __builtin_amdgcn_sched_barrier(0)
; template <class Epi, class Sched>
; __device__ __forceinline__ void gemm_phase(LAS unsigned char* lds, const Gemm g, const Sched& S, const Epi& E, int tid_in) {
;     ...
;             PG8_WAIT_V(8); PG8_WAIT_L(0); PG8_BAR; PG8_MMA(0, 0, At, B0); PG8_MMA(0, 1, At, B1); PG8_BAR; PG8_SCHED;
;             PG8_LDA(At, 0, 1); PG8_STAGE(PG8_SB(0, 0), b2, voffB); PG8_STAGE(PG8_SB(0, 1), b2 + hstep, voffB);
;             PG8_WAIT_V(6); PG8_WAIT_L(0); PG8_BAR; PG8_MMA(1, 0, At, B0); PG8_MMA(1, 1, At, B1); PG8_BAR; PG8_SCHED;
;             PG8_LDB(B0, 1, 0); PG8_LDB(B1, 1, 1); PG8_SCHED; PG8_LDA(At, 1, 0); PG8_STAGE(PG8_SA(0, 0), a2, voffA); PG8_STAGE(PG8_SA(0, 1), a2 + hstep, voffA);
;             PG8_WAIT_V(8); PG8_WAIT_L(0); PG8_BAR; PG8_MMA(0, 0, At, B0); PG8_MMA(0, 1, At, B1); PG8_BAR; PG8_SCHED;
	s_setprio 3
	v_mfma_f32_16x16x32_bf16 v[124:127], v[156:159], v[192:195], v[124:127]
	v_mfma_f32_16x16x32_bf16 v[120:123], v[164:167], v[192:195], v[120:123]
	v_mfma_f32_16x16x32_bf16 v[108:111], v[156:159], v[200:203], v[108:111]
	v_mfma_f32_16x16x32_bf16 v[104:107], v[164:167], v[200:203], v[104:107]
	v_mfma_f32_16x16x32_bf16 v[92:95], v[156:159], v[208:211], v[92:95]
	v_mfma_f32_16x16x32_bf16 v[88:91], v[164:167], v[208:211], v[88:91]
	v_mfma_f32_16x16x32_bf16 v[76:79], v[156:159], v[216:219], v[76:79]
	v_mfma_f32_16x16x32_bf16 v[72:75], v[164:167], v[216:219], v[72:75]
	v_mfma_f32_16x16x32_bf16 v[124:127], v[160:163], v[196:199], v[124:127]
	v_mfma_f32_16x16x32_bf16 v[120:123], v[168:171], v[196:199], v[120:123]
	v_mfma_f32_16x16x32_bf16 v[108:111], v[160:163], v[204:207], v[108:111]
	v_mfma_f32_16x16x32_bf16 v[104:107], v[168:171], v[204:207], v[104:107]
	v_mfma_f32_16x16x32_bf16 v[92:95], v[160:163], v[212:215], v[92:95]
	v_mfma_f32_16x16x32_bf16 v[88:91], v[168:171], v[212:215], v[88:91]
	v_mfma_f32_16x16x32_bf16 v[76:79], v[160:163], v[220:223], v[76:79]
	v_mfma_f32_16x16x32_bf16 v[72:75], v[168:171], v[220:223], v[72:75]
	s_setprio 0
	s_setprio 3
	v_mfma_f32_16x16x32_bf16 v[116:119], v[172:175], v[192:195], v[116:119]
	v_mfma_f32_16x16x32_bf16 v[112:115], v[180:183], v[192:195], v[112:115]
	v_mfma_f32_16x16x32_bf16 v[100:103], v[172:175], v[200:203], v[100:103]
	v_mfma_f32_16x16x32_bf16 v[96:99], v[180:183], v[200:203], v[96:99]
	v_mfma_f32_16x16x32_bf16 v[84:87], v[172:175], v[208:211], v[84:87]
	v_mfma_f32_16x16x32_bf16 v[80:83], v[180:183], v[208:211], v[80:83]
	v_mfma_f32_16x16x32_bf16 v[68:71], v[172:175], v[216:219], v[68:71]
	v_mfma_f32_16x16x32_bf16 v[64:67], v[180:183], v[216:219], v[64:67]
	v_mfma_f32_16x16x32_bf16 v[116:119], v[176:179], v[196:199], v[116:119]
	v_mfma_f32_16x16x32_bf16 v[112:115], v[188:191], v[196:199], v[112:115]
	v_mfma_f32_16x16x32_bf16 v[100:103], v[176:179], v[204:207], v[100:103]
	v_mfma_f32_16x16x32_bf16 v[96:99], v[188:191], v[204:207], v[96:99]
	v_mfma_f32_16x16x32_bf16 v[84:87], v[176:179], v[212:215], v[84:87]
	v_mfma_f32_16x16x32_bf16 v[80:83], v[188:191], v[212:215], v[80:83]
	v_mfma_f32_16x16x32_bf16 v[68:71], v[176:179], v[220:223], v[68:71]
	v_mfma_f32_16x16x32_bf16 v[64:67], v[188:191], v[220:223], v[64:67]
	s_setprio 0
	s_barrier
	s_add_i32 s72, s46, s2
	v_lshl_add_u64 v[184:185], s[38:39], 0, v[130:131]
	s_mov_b32 m0, s72
	ds_read_b128 v[192:195], v153 offset:16384
	ds_read_b128 v[196:199], v153 offset:17408
	ds_read_b128 v[200:203], v153 offset:18432
	ds_read_b128 v[204:207], v153 offset:19456
	ds_read_b128 v[208:211], v153 offset:20480
	ds_read_b128 v[212:215], v153 offset:21504
	ds_read_b128 v[216:219], v153 offset:22528
	ds_read_b128 v[220:223], v153 offset:23552
	global_load_lds_dwordx4 v[184:185], off
	s_add_i32 m0, s72, 0x2000
	s_add_u32 s72, s38, 0x80000
	v_lshl_add_u64 v[224:225], s[38:39], 0, v[134:135]
	s_addc_u32 s73, s39, 0
	s_add_i32 s74, s47, s2
	global_load_lds_dwordx4 v[224:225], off
	v_lshl_add_u64 v[226:227], s[72:73], 0, v[130:131]
	s_mov_b32 m0, s74
	s_nop 0
	global_load_lds_dwordx4 v[226:227], off
	v_lshl_add_u64 v[226:227], s[72:73], 0, v[134:135]
	s_add_i32 m0, s74, 0x2000
	s_nop 0
	global_load_lds_dwordx4 v[226:227], off
	s_waitcnt vmcnt(6)
	s_waitcnt lgkmcnt(0)
	s_barrier
	s_setprio 3
	v_mfma_f32_16x16x32_bf16 v[60:63], v[156:159], v[192:195], v[60:63]
	v_mfma_f32_16x16x32_bf16 v[56:59], v[164:167], v[192:195], v[56:59]
	v_mfma_f32_16x16x32_bf16 v[44:47], v[156:159], v[200:203], v[44:47]
	v_mfma_f32_16x16x32_bf16 v[40:43], v[164:167], v[200:203], v[40:43]
	v_mfma_f32_16x16x32_bf16 v[28:31], v[156:159], v[208:211], v[28:31]
	v_mfma_f32_16x16x32_bf16 v[24:27], v[164:167], v[208:211], v[24:27]
	v_mfma_f32_16x16x32_bf16 v[12:15], v[156:159], v[216:219], v[12:15]
	v_mfma_f32_16x16x32_bf16 v[8:11], v[164:167], v[216:219], v[8:11]
	v_mfma_f32_16x16x32_bf16 v[60:63], v[160:163], v[196:199], v[60:63]
	v_mfma_f32_16x16x32_bf16 v[56:59], v[168:171], v[196:199], v[56:59]
	v_mfma_f32_16x16x32_bf16 v[44:47], v[160:163], v[204:207], v[44:47]
	v_mfma_f32_16x16x32_bf16 v[40:43], v[168:171], v[204:207], v[40:43]
	v_mfma_f32_16x16x32_bf16 v[28:31], v[160:163], v[212:215], v[28:31]
	v_mfma_f32_16x16x32_bf16 v[24:27], v[168:171], v[212:215], v[24:27]
	v_mfma_f32_16x16x32_bf16 v[12:15], v[160:163], v[220:223], v[12:15]
	v_mfma_f32_16x16x32_bf16 v[8:11], v[168:171], v[220:223], v[8:11]
	s_setprio 0
	s_setprio 3
	v_mfma_f32_16x16x32_bf16 v[52:55], v[172:175], v[192:195], v[52:55]
	v_mfma_f32_16x16x32_bf16 v[48:51], v[180:183], v[192:195], v[48:51]
	v_mfma_f32_16x16x32_bf16 v[36:39], v[172:175], v[200:203], v[36:39]
	v_mfma_f32_16x16x32_bf16 v[32:35], v[180:183], v[200:203], v[32:35]
	v_mfma_f32_16x16x32_bf16 v[20:23], v[172:175], v[208:211], v[20:23]
	v_mfma_f32_16x16x32_bf16 v[16:19], v[180:183], v[208:211], v[16:19]
	v_mfma_f32_16x16x32_bf16 v[4:7], v[172:175], v[216:219], v[4:7]
	v_mfma_f32_16x16x32_bf16 v[0:3], v[180:183], v[216:219], v[0:3]
	v_mfma_f32_16x16x32_bf16 v[52:55], v[176:179], v[196:199], v[52:55]
	v_mfma_f32_16x16x32_bf16 v[48:51], v[188:191], v[196:199], v[48:51]
	v_mfma_f32_16x16x32_bf16 v[36:39], v[176:179], v[204:207], v[36:39]
	v_mfma_f32_16x16x32_bf16 v[32:35], v[188:191], v[204:207], v[32:35]
	v_mfma_f32_16x16x32_bf16 v[20:23], v[176:179], v[212:215], v[20:23]
	v_mfma_f32_16x16x32_bf16 v[16:19], v[188:191], v[212:215], v[16:19]
	v_mfma_f32_16x16x32_bf16 v[4:7], v[176:179], v[220:223], v[4:7]
	v_mfma_f32_16x16x32_bf16 v[0:3], v[188:191], v[220:223], v[0:3]
	s_setprio 0
	s_barrier
; #define PG8_STAGE(bufoff, gbase, voff) do { _Pragma("unroll") for (int _i = 0; _i < 2; ++_i) \
;         __builtin_amdgcn_global_load_lds((const unsigned*)((const char*)(gbase) + (voff)[_i]), (LAS unsigned*)(lds + (bufoff) + ldsw + _i * 8192), 16, 0, 0); } while (0)
; #define PG8_LDA(dst, b, h) do { _Pragma("unroll") for (int m = 0; m < 4; ++m) _Pragma("unroll") for (int k = 0; k < 2; ++k) dst[m][k] = *(const LAS bf16x8*)(lds + PG8_SA(b, h) + aoff + m * 2048 + k * 1024); } while (0)
; #define PG8_LDB(dst, b, h) do { _Pragma("unroll") for (int n = 0; n < 2; ++n) _Pragma("unroll") for (int k = 0; k < 2; ++k) dst[n][k] = *(const LAS bf16x8*)(lds + PG8_SB(b, h) + boff + n * 2048 + k * 1024); } while (0)
; #define PG8_MMA(ai, bj, At, Bt) do { __builtin_amdgcn_s_setprio(3); _Pragma("unroll") for (int m = 0; m < 4; ++m) _Pragma("unroll") for (int n = 0; n < 2; ++n) _Pragma("unroll") for (int k = 0; k < 2; ++k) \
;         acc[ai][bj][m][n] = __builtin_amdgcn_mfma_f32_16x16x32_bf16(Bt[n][k], At[m][k], acc[ai][bj][m][n], 0, 0, 0); __builtin_amdgcn_s_setprio(0); } while (0)
; #define PG8_WAIT_V(n) asm volatile("s_waitcnt vmcnt(" #n ")" ::: "memory")
; #define PG8_WAIT_L(n) asm volatile("s_waitcnt lgkmcnt(" #n ")" ::: "memory")
; #define PG8_BAR __builtin_amdgcn_s_barrier()
; #define PG8_SCHED __builtin_amdgcn_sched_barrier(0)
; template <class Epi, class Sched>
; __device__ __forceinline__ void gemm_phase(LAS unsigned char* lds, const Gemm g, const Sched& S, const Epi& E, int tid_in) {
;     ...
;             PG8_LDB(B0, 1, 0); PG8_LDB(B1, 1, 1); PG8_SCHED; PG8_LDA(At, 1, 0); PG8_STAGE(PG8_SA(0, 0), a2, voffA); PG8_STAGE(PG8_SA(0, 1), a2 + hstep, voffA);
;             PG8_WAIT_V(8); PG8_WAIT_L(0); PG8_BAR; PG8_MMA(0, 0, At, B0); PG8_MMA(0, 1, At, B1); PG8_BAR; PG8_SCHED;
;             PG8_LDA(At, 1, 1); PG8_STAGE(PG8_SB(1, 0), b3, voffB); PG8_STAGE(PG8_SB(1, 1), b3 + hstep, voffB);
;             PG8_WAIT_V(6); PG8_WAIT_L(0); PG8_BAR; PG8_MMA(1, 0, At, B0); PG8_MMA(1, 1, At, B1); PG8_BAR; PG8_SCHED;
;         }
	s_add_i32 s72, 0, 0x18000
	v_add_u32_e32 v155, s72, v149
	s_add_i32 s73, 0, 0x1c000
	ds_read_b128 v[156:159], v155
	ds_read_b128 v[160:163], v155 offset:1024
	ds_read_b128 v[164:167], v155 offset:2048
	ds_read_b128 v[168:171], v155 offset:3072
	v_add_u32_e32 v155, s73, v149
	ds_read_b128 v[172:175], v155
	ds_read_b128 v[176:179], v155 offset:1024
	ds_read_b128 v[180:183], v155 offset:2048
	ds_read_b128 v[188:191], v155 offset:3072
	s_mov_b32 m0, s3
	v_lshl_add_u64 v[226:227], s[40:41], 0, v[128:129]
	ds_read_b128 v[192:195], v153 offset:32768
	ds_read_b128 v[196:199], v153 offset:33792
	ds_read_b128 v[200:203], v153 offset:34816
	ds_read_b128 v[204:207], v153 offset:35840
	ds_read_b128 v[208:211], v153 offset:36864
	ds_read_b128 v[212:215], v153 offset:37888
	ds_read_b128 v[216:219], v153 offset:38912
	ds_read_b128 v[220:223], v153 offset:39936
	global_load_lds_dwordx4 v[226:227], off
	v_lshl_add_u64 v[226:227], s[40:41], 0, v[132:133]
	s_add_u32 s40, s40, 0x80000
	s_mov_b32 m0, s42
	s_addc_u32 s41, s41, 0
	global_load_lds_dwordx4 v[226:227], off
	v_lshl_add_u64 v[226:227], s[40:41], 0, v[128:129]
	s_mov_b32 m0, s43
	s_nop 0
	global_load_lds_dwordx4 v[226:227], off
	v_lshl_add_u64 v[226:227], s[40:41], 0, v[132:133]
	s_mov_b32 m0, s44
	s_nop 0
	global_load_lds_dwordx4 v[226:227], off
	s_waitcnt vmcnt(8)
	s_waitcnt lgkmcnt(0)
	s_barrier
	s_setprio 3
	v_mfma_f32_16x16x32_bf16 v[124:127], v[156:159], v[192:195], v[124:127]
	v_mfma_f32_16x16x32_bf16 v[120:123], v[164:167], v[192:195], v[120:123]
	v_mfma_f32_16x16x32_bf16 v[108:111], v[156:159], v[200:203], v[108:111]
	v_mfma_f32_16x16x32_bf16 v[104:107], v[164:167], v[200:203], v[104:107]
	v_mfma_f32_16x16x32_bf16 v[92:95], v[156:159], v[208:211], v[92:95]
	v_mfma_f32_16x16x32_bf16 v[88:91], v[164:167], v[208:211], v[88:91]
	v_mfma_f32_16x16x32_bf16 v[76:79], v[156:159], v[216:219], v[76:79]
	v_mfma_f32_16x16x32_bf16 v[72:75], v[164:167], v[216:219], v[72:75]
	v_mfma_f32_16x16x32_bf16 v[124:127], v[160:163], v[196:199], v[124:127]
	v_mfma_f32_16x16x32_bf16 v[120:123], v[168:171], v[196:199], v[120:123]
	v_mfma_f32_16x16x32_bf16 v[108:111], v[160:163], v[204:207], v[108:111]
	v_mfma_f32_16x16x32_bf16 v[104:107], v[168:171], v[204:207], v[104:107]
	v_mfma_f32_16x16x32_bf16 v[92:95], v[160:163], v[212:215], v[92:95]
	v_mfma_f32_16x16x32_bf16 v[88:91], v[168:171], v[212:215], v[88:91]
	v_mfma_f32_16x16x32_bf16 v[76:79], v[160:163], v[220:223], v[76:79]
	v_mfma_f32_16x16x32_bf16 v[72:75], v[168:171], v[220:223], v[72:75]
	s_setprio 0
	s_setprio 3
	v_mfma_f32_16x16x32_bf16 v[116:119], v[172:175], v[192:195], v[116:119]
	v_mfma_f32_16x16x32_bf16 v[112:115], v[180:183], v[192:195], v[112:115]
	v_mfma_f32_16x16x32_bf16 v[100:103], v[172:175], v[200:203], v[100:103]
	v_mfma_f32_16x16x32_bf16 v[96:99], v[180:183], v[200:203], v[96:99]
	v_mfma_f32_16x16x32_bf16 v[84:87], v[172:175], v[208:211], v[84:87]
	v_mfma_f32_16x16x32_bf16 v[80:83], v[180:183], v[208:211], v[80:83]
	v_mfma_f32_16x16x32_bf16 v[68:71], v[172:175], v[216:219], v[68:71]
	v_mfma_f32_16x16x32_bf16 v[64:67], v[180:183], v[216:219], v[64:67]
	v_mfma_f32_16x16x32_bf16 v[116:119], v[176:179], v[196:199], v[116:119]
	v_mfma_f32_16x16x32_bf16 v[112:115], v[188:191], v[196:199], v[112:115]
	v_mfma_f32_16x16x32_bf16 v[100:103], v[176:179], v[204:207], v[100:103]
	v_mfma_f32_16x16x32_bf16 v[96:99], v[188:191], v[204:207], v[96:99]
	v_mfma_f32_16x16x32_bf16 v[84:87], v[176:179], v[212:215], v[84:87]
	v_mfma_f32_16x16x32_bf16 v[80:83], v[188:191], v[212:215], v[80:83]
	v_mfma_f32_16x16x32_bf16 v[68:71], v[176:179], v[220:223], v[68:71]
	v_mfma_f32_16x16x32_bf16 v[64:67], v[188:191], v[220:223], v[64:67]
	s_setprio 0
	s_barrier
	s_add_i32 s40, s72, s2
	v_lshl_add_u64 v[184:185], v[184:185], 0, s[16:17]
	s_mov_b32 m0, s40
	ds_read_b128 v[192:195], v153 offset:49152
	ds_read_b128 v[196:199], v153 offset:50176
	ds_read_b128 v[200:203], v153 offset:51200
	ds_read_b128 v[204:207], v153 offset:52224
	ds_read_b128 v[208:211], v153 offset:53248
	ds_read_b128 v[212:215], v153 offset:54272
	ds_read_b128 v[216:219], v153 offset:55296
	ds_read_b128 v[220:223], v153 offset:56320
	global_load_lds_dwordx4 v[184:185], off
	s_add_i32 m0, s40, 0x2000
	s_add_u32 s38, s38, 0x80080
	v_lshl_add_u64 v[184:185], v[224:225], 0, s[16:17]
	s_addc_u32 s39, s39, 0
	s_add_i32 s40, s73, s2
	global_load_lds_dwordx4 v[184:185], off
	v_lshl_add_u64 v[184:185], s[38:39], 0, v[130:131]
	s_mov_b32 m0, s40
	s_nop 0
	global_load_lds_dwordx4 v[184:185], off
	v_lshl_add_u64 v[184:185], s[38:39], 0, v[134:135]
	s_add_i32 m0, s40, 0x2000
	s_nop 0
	global_load_lds_dwordx4 v[184:185], off
	s_waitcnt vmcnt(6)
	s_waitcnt lgkmcnt(0)
	s_barrier
	s_setprio 3
	v_mfma_f32_16x16x32_bf16 v[60:63], v[156:159], v[192:195], v[60:63]
	v_mfma_f32_16x16x32_bf16 v[56:59], v[164:167], v[192:195], v[56:59]
	v_mfma_f32_16x16x32_bf16 v[44:47], v[156:159], v[200:203], v[44:47]
	v_mfma_f32_16x16x32_bf16 v[40:43], v[164:167], v[200:203], v[40:43]
	v_mfma_f32_16x16x32_bf16 v[28:31], v[156:159], v[208:211], v[28:31]
	v_mfma_f32_16x16x32_bf16 v[24:27], v[164:167], v[208:211], v[24:27]
	v_mfma_f32_16x16x32_bf16 v[12:15], v[156:159], v[216:219], v[12:15]
	v_mfma_f32_16x16x32_bf16 v[8:11], v[164:167], v[216:219], v[8:11]
	v_mfma_f32_16x16x32_bf16 v[60:63], v[160:163], v[196:199], v[60:63]
	v_mfma_f32_16x16x32_bf16 v[56:59], v[168:171], v[196:199], v[56:59]
	v_mfma_f32_16x16x32_bf16 v[44:47], v[160:163], v[204:207], v[44:47]
	v_mfma_f32_16x16x32_bf16 v[40:43], v[168:171], v[204:207], v[40:43]
	v_mfma_f32_16x16x32_bf16 v[28:31], v[160:163], v[212:215], v[28:31]
	v_mfma_f32_16x16x32_bf16 v[24:27], v[168:171], v[212:215], v[24:27]
	v_mfma_f32_16x16x32_bf16 v[12:15], v[160:163], v[220:223], v[12:15]
	v_mfma_f32_16x16x32_bf16 v[8:11], v[168:171], v[220:223], v[8:11]
	s_setprio 0
	s_setprio 3
	v_mfma_f32_16x16x32_bf16 v[52:55], v[172:175], v[192:195], v[52:55]
	v_mfma_f32_16x16x32_bf16 v[48:51], v[180:183], v[192:195], v[48:51]
	v_mfma_f32_16x16x32_bf16 v[36:39], v[172:175], v[200:203], v[36:39]
	v_mfma_f32_16x16x32_bf16 v[32:35], v[180:183], v[200:203], v[32:35]
	v_mfma_f32_16x16x32_bf16 v[20:23], v[172:175], v[208:211], v[20:23]
	v_mfma_f32_16x16x32_bf16 v[16:19], v[180:183], v[208:211], v[16:19]
	v_mfma_f32_16x16x32_bf16 v[4:7], v[172:175], v[216:219], v[4:7]
	v_mfma_f32_16x16x32_bf16 v[0:3], v[180:183], v[216:219], v[0:3]
	v_mfma_f32_16x16x32_bf16 v[52:55], v[176:179], v[196:199], v[52:55]
	v_mfma_f32_16x16x32_bf16 v[48:51], v[188:191], v[196:199], v[48:51]
	v_mfma_f32_16x16x32_bf16 v[36:39], v[176:179], v[204:207], v[36:39]
	v_mfma_f32_16x16x32_bf16 v[32:35], v[188:191], v[204:207], v[32:35]
	v_mfma_f32_16x16x32_bf16 v[20:23], v[176:179], v[212:215], v[20:23]
	v_mfma_f32_16x16x32_bf16 v[16:19], v[188:191], v[212:215], v[16:19]
	v_mfma_f32_16x16x32_bf16 v[4:7], v[176:179], v[220:223], v[4:7]
	v_mfma_f32_16x16x32_bf16 v[0:3], v[188:191], v[220:223], v[0:3]
	s_setprio 0
	s_barrier
	s_add_i32 s71, s71, 2
	s_add_u32 s36, s36, 0x100
	s_addc_u32 s37, s37, 0
	s_cmp_gt_u32 s71, 29
	s_cbranch_scc0 .LBB0_620

; #define PG8_STAGE(bufoff, gbase, voff) do { _Pragma("unroll") for (int _i = 0; _i < 2; ++_i) \
;         __builtin_amdgcn_global_load_lds((const unsigned*)((const char*)(gbase) + (voff)[_i]), (LAS unsigned*)(lds + (bufoff) + ldsw + _i * 8192), 16, 0, 0); } while (0)
; #define PG8_LDA(dst, b, h) do { _Pragma("unroll") for (int m = 0; m < 4; ++m) _Pragma("unroll") for (int k = 0; k < 2; ++k) dst[m][k] = *(const LAS bf16x8*)(lds + PG8_SA(b, h) + aoff + m * 2048 + k * 1024); } while (0)
; #define PG8_LDB(dst, b, h) do { _Pragma("unroll") for (int n = 0; n < 2; ++n) _Pragma("unroll") for (int k = 0; k < 2; ++k) dst[n][k] = *(const LAS bf16x8*)(lds + PG8_SB(b, h) + boff + n * 2048 + k * 1024); } while (0)
; #define PG8_MMA(ai, bj, At, Bt) do { __builtin_amdgcn_s_setprio(3); _Pragma("unroll") for (int m = 0; m < 4; ++m) _Pragma("unroll") for (int n = 0; n < 2; ++n) _Pragma("unroll") for (int k = 0; k < 2; ++k) \
;         acc[ai][bj][m][n] = __builtin_amdgcn_mfma_f32_16x16x32_bf16(Bt[n][k], At[m][k], acc[ai][bj][m][n], 0, 0, 0); __builtin_amdgcn_s_setprio(0); } while (0)
; #define PG8_WAIT_V(n) asm volatile("s_waitcnt vmcnt(" #n ")" ::: "memory")
; template <class Epi, class Sched>
; __device__ __forceinline__ void gemm_phase(LAS unsigned char* lds, const Gemm g, const Sched& S, const Epi& E, int tid_in) {
;     ...
;         const char* nA = has_next ? (const char*)g.A + (size_t)nxt.pm * tstep + nxt.koff : cA; const char* nB = has_next ? (const char*)g.Bt + (size_t)nxt.pn * tstep + nxt.koff : cB;
;         for (int t = 0; t < nt; t += 2) {
;             const bool last = (t == nt - 2);
;             const char* a1 = cA + (size_t)(t + 1) * kstep;
;             const char* a2 = last ? nA : cA + (size_t)(t + 2) * kstep; const char* b2 = last ? nB : cB + (size_t)(t + 2) * kstep;
;             const char* a3 = a2 + kstep; const char* b3 = b2 + kstep;
;             PG8_LDB(B0, 0, 0); PG8_LDB(B1, 0, 1); PG8_SCHED; PG8_LDA(At, 0, 0); PG8_STAGE(PG8_SA(1, 0), a1, voffA); PG8_STAGE(PG8_SA(1, 1), a1 + hstep, voffA);
;             PG8_WAIT_V(8); PG8_WAIT_L(0); PG8_BAR; PG8_MMA(0, 0, At, B0); PG8_MMA(0, 1, At, B1); PG8_BAR; PG8_SCHED;
;             PG8_LDA(At, 0, 1); PG8_STAGE(PG8_SB(0, 0), b2, voffB); PG8_STAGE(PG8_SB(0, 1), b2 + hstep, voffB);
;             PG8_WAIT_V(6); PG8_WAIT_L(0); PG8_BAR; PG8_MMA(1, 0, At, B0); PG8_MMA(1, 1, At, B1); PG8_BAR; PG8_SCHED;
.LBB0_762:
	s_ashr_i32 s21, s20, 31
	s_lshl_b64 s[22:23], s[20:21], 20
	s_add_u32 s22, s58, s22
	s_addc_u32 s23, s59, s23
	s_and_b64 s[24:25], s[4:5], exec
	s_cselect_b32 s21, s23, s29
	s_cselect_b32 s48, s22, s28
	s_ashr_i32 s19, s18, 31
	s_lshl_b64 s[24:25], s[18:19], 20
	s_add_u32 s24, s2, s24
	s_addc_u32 s25, s3, s25
	s_and_b64 s[34:35], s[4:5], exec
	s_cselect_b32 s19, s25, s31
	s_cselect_b32 s49, s24, s30
	s_add_u32 s51, s30, 0x100
	v_lshl_add_u64 v[144:145], s[28:29], 0, v[136:137]
	v_lshl_add_u64 v[146:147], s[28:29], 0, v[138:139]
	s_addc_u32 s68, s31, 0
	s_mov_b32 s69, -2
	s_mov_b64 s[30:31], 0
	ds_read_b128 v[154:157], v151
	ds_read_b128 v[158:161], v151 offset:1024
	ds_read_b128 v[162:165], v151 offset:2048
	ds_read_b128 v[166:169], v151 offset:3072
	ds_read_b128 v[170:173], v152
	ds_read_b128 v[174:177], v152 offset:1024
	ds_read_b128 v[178:181], v152 offset:2048
	ds_read_b128 v[182:185], v152 offset:3072
	s_add_u32 s34, s28, s30
	s_addc_u32 s35, s29, s31
	s_add_u32 s36, s34, 0x100
	s_addc_u32 s37, s35, 0
	s_add_u32 s34, s51, s30
	s_addc_u32 s35, s68, s31
	s_cmpk_eq_i32 s30, 0xf00
	s_cselect_b32 s35, s19, s35
	s_cselect_b32 s34, s49, s34
	s_cselect_b32 s37, s21, s37
	s_cselect_b32 s36, s48, s36
	v_lshl_add_u64 v[220:221], v[146:147], 0, s[30:31]
	v_lshl_add_u64 v[222:223], v[220:221], 0, s[8:9]
	s_add_i32 m0, s27, 0x8000
	ds_read_b128 v[188:191], v153
	ds_read_b128 v[192:195], v153 offset:1024
	ds_read_b128 v[196:199], v153 offset:2048
	ds_read_b128 v[200:203], v153 offset:3072
	ds_read_b128 v[204:207], v153 offset:4096
	ds_read_b128 v[208:211], v153 offset:5120
	ds_read_b128 v[212:215], v153 offset:6144
	ds_read_b128 v[216:219], v153 offset:7168
	global_load_lds_dwordx4 v[222:223], off
	v_lshl_add_u64 v[222:223], v[144:145], 0, s[30:31]
	v_lshl_add_u64 v[224:225], v[222:223], 0, s[8:9]
	s_add_i32 m0, s27, 0xa000
	v_lshl_add_u64 v[220:221], v[220:221], 0, s[14:15]
	global_load_lds_dwordx4 v[224:225], off
	s_add_i32 m0, s27, 0xc000
	s_nop 0
	global_load_lds_dwordx4 v[220:221], off
	v_lshl_add_u64 v[220:221], v[222:223], 0, s[14:15]
	s_add_i32 m0, s27, 0xe000
	s_nop 0
	global_load_lds_dwordx4 v[220:221], off
	s_waitcnt vmcnt(8)
	s_waitcnt lgkmcnt(0)
	s_barrier
	s_setprio 3
	v_mfma_f32_16x16x32_bf16 v[124:127], v[154:157], v[188:191], 0
	v_mfma_f32_16x16x32_bf16 v[120:123], v[162:165], v[188:191], 0
	v_mfma_f32_16x16x32_bf16 v[108:111], v[154:157], v[196:199], 0
	v_mfma_f32_16x16x32_bf16 v[104:107], v[162:165], v[196:199], 0
	v_mfma_f32_16x16x32_bf16 v[92:95], v[154:157], v[204:207], 0
	v_mfma_f32_16x16x32_bf16 v[88:91], v[162:165], v[204:207], 0
	v_mfma_f32_16x16x32_bf16 v[76:79], v[154:157], v[212:215], 0
	v_mfma_f32_16x16x32_bf16 v[72:75], v[162:165], v[212:215], 0
	v_mfma_f32_16x16x32_bf16 v[124:127], v[158:161], v[192:195], v[124:127]
	v_mfma_f32_16x16x32_bf16 v[120:123], v[166:169], v[192:195], v[120:123]
	v_mfma_f32_16x16x32_bf16 v[108:111], v[158:161], v[200:203], v[108:111]
	v_mfma_f32_16x16x32_bf16 v[104:107], v[166:169], v[200:203], v[104:107]
	v_mfma_f32_16x16x32_bf16 v[92:95], v[158:161], v[208:211], v[92:95]
	v_mfma_f32_16x16x32_bf16 v[88:91], v[166:169], v[208:211], v[88:91]
	v_mfma_f32_16x16x32_bf16 v[76:79], v[158:161], v[216:219], v[76:79]
	v_mfma_f32_16x16x32_bf16 v[72:75], v[166:169], v[216:219], v[72:75]
	s_setprio 0
	s_setprio 3
	v_mfma_f32_16x16x32_bf16 v[116:119], v[170:173], v[188:191], 0
	v_mfma_f32_16x16x32_bf16 v[112:115], v[178:181], v[188:191], 0
	v_mfma_f32_16x16x32_bf16 v[100:103], v[170:173], v[196:199], 0
	v_mfma_f32_16x16x32_bf16 v[96:99], v[178:181], v[196:199], 0
	v_mfma_f32_16x16x32_bf16 v[84:87], v[170:173], v[204:207], 0
	v_mfma_f32_16x16x32_bf16 v[80:83], v[178:181], v[204:207], 0
	v_mfma_f32_16x16x32_bf16 v[68:71], v[170:173], v[212:215], 0
	v_mfma_f32_16x16x32_bf16 v[64:67], v[178:181], v[212:215], 0
	v_mfma_f32_16x16x32_bf16 v[116:119], v[174:177], v[192:195], v[116:119]
	v_mfma_f32_16x16x32_bf16 v[112:115], v[182:185], v[192:195], v[112:115]
	v_mfma_f32_16x16x32_bf16 v[100:103], v[174:177], v[200:203], v[100:103]
	v_mfma_f32_16x16x32_bf16 v[96:99], v[182:185], v[200:203], v[96:99]
	v_mfma_f32_16x16x32_bf16 v[84:87], v[174:177], v[208:211], v[84:87]
	v_mfma_f32_16x16x32_bf16 v[80:83], v[182:185], v[208:211], v[80:83]
	v_mfma_f32_16x16x32_bf16 v[68:71], v[174:177], v[216:219], v[68:71]
	v_mfma_f32_16x16x32_bf16 v[64:67], v[182:185], v[216:219], v[64:67]
	s_setprio 0
	s_barrier
	s_add_i32 s70, s44, s38
	v_lshl_add_u64 v[220:221], s[34:35], 0, v[132:133]
	s_mov_b32 m0, s70
	ds_read_b128 v[188:191], v153 offset:16384
	ds_read_b128 v[192:195], v153 offset:17408
	ds_read_b128 v[196:199], v153 offset:18432
	ds_read_b128 v[200:203], v153 offset:19456
	ds_read_b128 v[204:207], v153 offset:20480
	ds_read_b128 v[208:211], v153 offset:21504
	ds_read_b128 v[212:215], v153 offset:22528
	ds_read_b128 v[216:219], v153 offset:23552
	global_load_lds_dwordx4 v[220:221], off
	s_add_i32 m0, s70, 0x2000
	s_add_u32 s70, s34, 0x80000
	v_lshl_add_u64 v[222:223], s[34:35], 0, v[128:129]
	s_addc_u32 s71, s35, 0
	s_add_i32 s72, s45, s38
	global_load_lds_dwordx4 v[222:223], off
	v_lshl_add_u64 v[224:225], s[70:71], 0, v[132:133]
	s_mov_b32 m0, s72
	s_nop 0
	global_load_lds_dwordx4 v[224:225], off
	v_lshl_add_u64 v[224:225], s[70:71], 0, v[128:129]
	s_add_i32 m0, s72, 0x2000
	s_nop 0
	global_load_lds_dwordx4 v[224:225], off
	s_waitcnt vmcnt(6)
	s_waitcnt lgkmcnt(0)
	s_barrier
; #define PG8_STAGE(bufoff, gbase, voff) do { _Pragma("unroll") for (int _i = 0; _i < 2; ++_i) \
;         __builtin_amdgcn_global_load_lds((const unsigned*)((const char*)(gbase) + (voff)[_i]), (LAS unsigned*)(lds + (bufoff) + ldsw + _i * 8192), 16, 0, 0); } while (0)
; #define PG8_LDA(dst, b, h) do { _Pragma("unroll") for (int m = 0; m < 4; ++m) _Pragma("unroll") for (int k = 0; k < 2; ++k) dst[m][k] = *(const LAS bf16x8*)(lds + PG8_SA(b, h) + aoff + m * 2048 + k * 1024); } while (0)
; #define PG8_LDB(dst, b, h) do { _Pragma("unroll") for (int n = 0; n < 2; ++n) _Pragma("unroll") for (int k = 0; k < 2; ++k) dst[n][k] = *(const LAS bf16x8*)(lds + PG8_SB(b, h) + boff + n * 2048 + k * 1024); } while (0)
; #define PG8_MMA(ai, bj, At, Bt) do { __builtin_amdgcn_s_setprio(3); _Pragma("unroll") for (int m = 0; m < 4; ++m) _Pragma("unroll") for (int n = 0; n < 2; ++n) _Pragma("unroll") for (int k = 0; k < 2; ++k) \
;         acc[ai][bj][m][n] = __builtin_amdgcn_mfma_f32_16x16x32_bf16(Bt[n][k], At[m][k], acc[ai][bj][m][n], 0, 0, 0); __builtin_amdgcn_s_setprio(0); } while (0)
; #define PG8_WAIT_V(n) asm volatile("s_waitcnt vmcnt(" #n ")" ::: "memory")
; #define PG8_WAIT_L(n) asm volatile("s_waitcnt lgkmcnt(" #n ")" ::: "memory")
; #define PG8_BAR __builtin_amdgcn_s_barrier()
; #define PG8_SCHED __builtin_amdgcn_sched_barrier(0)
; template <class Epi, class Sched>
; __device__ __forceinline__ void gemm_phase(LAS unsigned char* lds, const Gemm g, const Sched& S, const Epi& E, int tid_in) {
;     ...
;             PG8_WAIT_V(6); PG8_WAIT_L(0); PG8_BAR; PG8_MMA(1, 0, At, B0); PG8_MMA(1, 1, At, B1); PG8_BAR; PG8_SCHED;
;             PG8_LDB(B0, 1, 0); PG8_LDB(B1, 1, 1); PG8_SCHED; PG8_LDA(At, 1, 0); PG8_STAGE(PG8_SA(0, 0), a2, voffA); PG8_STAGE(PG8_SA(0, 1), a2 + hstep, voffA);
;             PG8_WAIT_V(8); PG8_WAIT_L(0); PG8_BAR; PG8_MMA(0, 0, At, B0); PG8_MMA(0, 1, At, B1); PG8_BAR; PG8_SCHED;
;             PG8_LDA(At, 1, 1); PG8_STAGE(PG8_SB(1, 0), b3, voffB); PG8_STAGE(PG8_SB(1, 1), b3 + hstep, voffB);
;             PG8_WAIT_V(6); PG8_WAIT_L(0); PG8_BAR; PG8_MMA(1, 0, At, B0); PG8_MMA(1, 1, At, B1); PG8_BAR; PG8_SCHED;
	s_setprio 3
	v_mfma_f32_16x16x32_bf16 v[60:63], v[154:157], v[188:191], 0
	v_mfma_f32_16x16x32_bf16 v[56:59], v[162:165], v[188:191], 0
	v_mfma_f32_16x16x32_bf16 v[44:47], v[154:157], v[196:199], 0
	v_mfma_f32_16x16x32_bf16 v[40:43], v[162:165], v[196:199], 0
	v_mfma_f32_16x16x32_bf16 v[28:31], v[154:157], v[204:207], 0
	v_mfma_f32_16x16x32_bf16 v[24:27], v[162:165], v[204:207], 0
	v_mfma_f32_16x16x32_bf16 v[12:15], v[154:157], v[212:215], 0
	v_mfma_f32_16x16x32_bf16 v[8:11], v[162:165], v[212:215], 0
	v_mfma_f32_16x16x32_bf16 v[60:63], v[158:161], v[192:195], v[60:63]
	v_mfma_f32_16x16x32_bf16 v[56:59], v[166:169], v[192:195], v[56:59]
	v_mfma_f32_16x16x32_bf16 v[44:47], v[158:161], v[200:203], v[44:47]
	v_mfma_f32_16x16x32_bf16 v[40:43], v[166:169], v[200:203], v[40:43]
	v_mfma_f32_16x16x32_bf16 v[28:31], v[158:161], v[208:211], v[28:31]
	v_mfma_f32_16x16x32_bf16 v[24:27], v[166:169], v[208:211], v[24:27]
	v_mfma_f32_16x16x32_bf16 v[12:15], v[158:161], v[216:219], v[12:15]
	v_mfma_f32_16x16x32_bf16 v[8:11], v[166:169], v[216:219], v[8:11]
	s_setprio 0
	s_setprio 3
	v_mfma_f32_16x16x32_bf16 v[52:55], v[170:173], v[188:191], 0
	v_mfma_f32_16x16x32_bf16 v[48:51], v[178:181], v[188:191], 0
	v_mfma_f32_16x16x32_bf16 v[36:39], v[170:173], v[196:199], 0
	v_mfma_f32_16x16x32_bf16 v[32:35], v[178:181], v[196:199], 0
	v_mfma_f32_16x16x32_bf16 v[20:23], v[170:173], v[204:207], 0
	v_mfma_f32_16x16x32_bf16 v[16:19], v[178:181], v[204:207], 0
	v_mfma_f32_16x16x32_bf16 v[4:7], v[170:173], v[212:215], 0
	v_mfma_f32_16x16x32_bf16 v[0:3], v[178:181], v[212:215], 0
	v_mfma_f32_16x16x32_bf16 v[52:55], v[174:177], v[192:195], v[52:55]
	v_mfma_f32_16x16x32_bf16 v[48:51], v[182:185], v[192:195], v[48:51]
	v_mfma_f32_16x16x32_bf16 v[36:39], v[174:177], v[200:203], v[36:39]
	v_mfma_f32_16x16x32_bf16 v[32:35], v[182:185], v[200:203], v[32:35]
	v_mfma_f32_16x16x32_bf16 v[20:23], v[174:177], v[208:211], v[20:23]
	v_mfma_f32_16x16x32_bf16 v[16:19], v[182:185], v[208:211], v[16:19]
	v_mfma_f32_16x16x32_bf16 v[4:7], v[174:177], v[216:219], v[4:7]
	v_mfma_f32_16x16x32_bf16 v[0:3], v[182:185], v[216:219], v[0:3]
	s_setprio 0
	s_barrier
	s_add_i32 s70, 0, 0x18000
	s_add_i32 s71, 0, 0x1c000
	v_add_u32_e32 v166, s70, v149
	v_add_u32_e32 v182, s71, v149
	ds_read_b128 v[154:157], v166
	ds_read_b128 v[158:161], v166 offset:1024
	ds_read_b128 v[162:165], v166 offset:2048
	ds_read_b128 v[166:169], v166 offset:3072
	ds_read_b128 v[170:173], v182
	ds_read_b128 v[174:177], v182 offset:1024
	ds_read_b128 v[178:181], v182 offset:2048
	ds_read_b128 v[182:185], v182 offset:3072
	s_mov_b32 m0, s27
	v_lshl_add_u64 v[224:225], s[36:37], 0, v[134:135]
	ds_read_b128 v[188:191], v153 offset:32768
	ds_read_b128 v[192:195], v153 offset:33792
	ds_read_b128 v[196:199], v153 offset:34816
	ds_read_b128 v[200:203], v153 offset:35840
	ds_read_b128 v[204:207], v153 offset:36864
	ds_read_b128 v[208:211], v153 offset:37888
	ds_read_b128 v[212:215], v153 offset:38912
	ds_read_b128 v[216:219], v153 offset:39936
	global_load_lds_dwordx4 v[224:225], off
	v_lshl_add_u64 v[224:225], s[36:37], 0, v[130:131]
	s_add_u32 s36, s36, 0x80000
	s_mov_b32 m0, s40
	s_addc_u32 s37, s37, 0
	global_load_lds_dwordx4 v[224:225], off
	v_lshl_add_u64 v[224:225], s[36:37], 0, v[134:135]
	s_mov_b32 m0, s41
	s_nop 0
	global_load_lds_dwordx4 v[224:225], off
	v_lshl_add_u64 v[224:225], s[36:37], 0, v[130:131]
	s_mov_b32 m0, s42
	s_nop 0
	global_load_lds_dwordx4 v[224:225], off
	s_waitcnt vmcnt(8)
	s_waitcnt lgkmcnt(0)
	s_barrier
	s_setprio 3
	v_mfma_f32_16x16x32_bf16 v[124:127], v[154:157], v[188:191], v[124:127]
	v_mfma_f32_16x16x32_bf16 v[120:123], v[162:165], v[188:191], v[120:123]
	v_mfma_f32_16x16x32_bf16 v[108:111], v[154:157], v[196:199], v[108:111]
	v_mfma_f32_16x16x32_bf16 v[104:107], v[162:165], v[196:199], v[104:107]
	v_mfma_f32_16x16x32_bf16 v[92:95], v[154:157], v[204:207], v[92:95]
	v_mfma_f32_16x16x32_bf16 v[88:91], v[162:165], v[204:207], v[88:91]
	v_mfma_f32_16x16x32_bf16 v[76:79], v[154:157], v[212:215], v[76:79]
	v_mfma_f32_16x16x32_bf16 v[72:75], v[162:165], v[212:215], v[72:75]
	v_mfma_f32_16x16x32_bf16 v[124:127], v[158:161], v[192:195], v[124:127]
	v_mfma_f32_16x16x32_bf16 v[120:123], v[166:169], v[192:195], v[120:123]
	v_mfma_f32_16x16x32_bf16 v[108:111], v[158:161], v[200:203], v[108:111]
	v_mfma_f32_16x16x32_bf16 v[104:107], v[166:169], v[200:203], v[104:107]
	v_mfma_f32_16x16x32_bf16 v[92:95], v[158:161], v[208:211], v[92:95]
	v_mfma_f32_16x16x32_bf16 v[88:91], v[166:169], v[208:211], v[88:91]
	v_mfma_f32_16x16x32_bf16 v[76:79], v[158:161], v[216:219], v[76:79]
	v_mfma_f32_16x16x32_bf16 v[72:75], v[166:169], v[216:219], v[72:75]
	s_setprio 0
	s_setprio 3
	v_mfma_f32_16x16x32_bf16 v[116:119], v[170:173], v[188:191], v[116:119]
	v_mfma_f32_16x16x32_bf16 v[112:115], v[178:181], v[188:191], v[112:115]
	v_mfma_f32_16x16x32_bf16 v[100:103], v[170:173], v[196:199], v[100:103]
	v_mfma_f32_16x16x32_bf16 v[96:99], v[178:181], v[196:199], v[96:99]
	v_mfma_f32_16x16x32_bf16 v[84:87], v[170:173], v[204:207], v[84:87]
	v_mfma_f32_16x16x32_bf16 v[80:83], v[178:181], v[204:207], v[80:83]
	v_mfma_f32_16x16x32_bf16 v[68:71], v[170:173], v[212:215], v[68:71]
	v_mfma_f32_16x16x32_bf16 v[64:67], v[178:181], v[212:215], v[64:67]
	v_mfma_f32_16x16x32_bf16 v[116:119], v[174:177], v[192:195], v[116:119]
	v_mfma_f32_16x16x32_bf16 v[112:115], v[182:185], v[192:195], v[112:115]
	v_mfma_f32_16x16x32_bf16 v[100:103], v[174:177], v[200:203], v[100:103]
	v_mfma_f32_16x16x32_bf16 v[96:99], v[182:185], v[200:203], v[96:99]
	v_mfma_f32_16x16x32_bf16 v[84:87], v[174:177], v[208:211], v[84:87]
	v_mfma_f32_16x16x32_bf16 v[80:83], v[182:185], v[208:211], v[80:83]
	v_mfma_f32_16x16x32_bf16 v[68:71], v[174:177], v[216:219], v[68:71]
	v_mfma_f32_16x16x32_bf16 v[64:67], v[182:185], v[216:219], v[64:67]
	s_setprio 0
	s_barrier
; #define PG8_STAGE(bufoff, gbase, voff) do { _Pragma("unroll") for (int _i = 0; _i < 2; ++_i) \
;         __builtin_amdgcn_global_load_lds((const unsigned*)((const char*)(gbase) + (voff)[_i]), (LAS unsigned*)(lds + (bufoff) + ldsw + _i * 8192), 16, 0, 0); } while (0)
; #define PG8_LDA(dst, b, h) do { _Pragma("unroll") for (int m = 0; m < 4; ++m) _Pragma("unroll") for (int k = 0; k < 2; ++k) dst[m][k] = *(const LAS bf16x8*)(lds + PG8_SA(b, h) + aoff + m * 2048 + k * 1024); } while (0)
; #define PG8_LDB(dst, b, h) do { _Pragma("unroll") for (int n = 0; n < 2; ++n) _Pragma("unroll") for (int k = 0; k < 2; ++k) dst[n][k] = *(const LAS bf16x8*)(lds + PG8_SB(b, h) + boff + n * 2048 + k * 1024); } while (0)
; #define PG8_MMA(ai, bj, At, Bt) do { __builtin_amdgcn_s_setprio(3); _Pragma("unroll") for (int m = 0; m < 4; ++m) _Pragma("unroll") for (int n = 0; n < 2; ++n) _Pragma("unroll") for (int k = 0; k < 2; ++k) \
;         acc[ai][bj][m][n] = __builtin_amdgcn_mfma_f32_16x16x32_bf16(Bt[n][k], At[m][k], acc[ai][bj][m][n], 0, 0, 0); __builtin_amdgcn_s_setprio(0); } while (0)
; #define PG8_WAIT_V(n) asm volatile("s_waitcnt vmcnt(" #n ")" ::: "memory")
; #define PG8_WAIT_L(n) asm volatile("s_waitcnt lgkmcnt(" #n ")" ::: "memory")
; #define PG8_BAR __builtin_amdgcn_s_barrier()
; #define PG8_SCHED __builtin_amdgcn_sched_barrier(0)
; template <class Epi, class Sched>
; __device__ __forceinline__ void gemm_phase(LAS unsigned char* lds, const Gemm g, const Sched& S, const Epi& E, int tid_in) {
;     ...
;             PG8_LDB(B0, 0, 0); PG8_LDB(B1, 0, 1); PG8_SCHED; PG8_LDA(At, 0, 0); PG8_STAGE(PG8_SA(1, 0), a1, voffA); PG8_STAGE(PG8_SA(1, 1), a1 + hstep, voffA);
;             PG8_WAIT_V(8); PG8_WAIT_L(0); PG8_BAR; PG8_MMA(0, 0, At, B0); PG8_MMA(0, 1, At, B1); PG8_BAR; PG8_SCHED;
;     ...
;             PG8_LDB(B0, 1, 0); PG8_LDB(B1, 1, 1); PG8_SCHED; PG8_LDA(At, 1, 0); PG8_STAGE(PG8_SA(0, 0), a2, voffA); PG8_STAGE(PG8_SA(0, 1), a2 + hstep, voffA);
;             PG8_WAIT_V(8); PG8_WAIT_L(0); PG8_BAR; PG8_MMA(0, 0, At, B0); PG8_MMA(0, 1, At, B1); PG8_BAR; PG8_SCHED;
;             PG8_LDA(At, 1, 1); PG8_STAGE(PG8_SB(1, 0), b3, voffB); PG8_STAGE(PG8_SB(1, 1), b3 + hstep, voffB);
;             PG8_WAIT_V(6); PG8_WAIT_L(0); PG8_BAR; PG8_MMA(1, 0, At, B0); PG8_MMA(1, 1, At, B1); PG8_BAR; PG8_SCHED;
;         }
	s_add_i32 s36, s70, s38
	v_lshl_add_u64 v[220:221], v[220:221], 0, s[8:9]
	s_mov_b32 m0, s36
	ds_read_b128 v[188:191], v153 offset:49152
	ds_read_b128 v[192:195], v153 offset:50176
	ds_read_b128 v[196:199], v153 offset:51200
	ds_read_b128 v[200:203], v153 offset:52224
	ds_read_b128 v[204:207], v153 offset:53248
	ds_read_b128 v[208:211], v153 offset:54272
	ds_read_b128 v[212:215], v153 offset:55296
	ds_read_b128 v[216:219], v153 offset:56320
	global_load_lds_dwordx4 v[220:221], off
	s_add_i32 m0, s36, 0x2000
	s_add_u32 s34, s34, 0x80080
	v_lshl_add_u64 v[220:221], v[222:223], 0, s[8:9]
	s_addc_u32 s35, s35, 0
	s_add_i32 s36, s71, s38
	global_load_lds_dwordx4 v[220:221], off
	v_lshl_add_u64 v[220:221], s[34:35], 0, v[132:133]
	s_mov_b32 m0, s36
	s_nop 0
	global_load_lds_dwordx4 v[220:221], off
	v_lshl_add_u64 v[220:221], s[34:35], 0, v[128:129]
	s_add_i32 m0, s36, 0x2000
	s_nop 0
	global_load_lds_dwordx4 v[220:221], off
	s_waitcnt vmcnt(6)
	s_waitcnt lgkmcnt(0)
	s_barrier
	s_setprio 3
	v_mfma_f32_16x16x32_bf16 v[60:63], v[154:157], v[188:191], v[60:63]
	v_mfma_f32_16x16x32_bf16 v[56:59], v[162:165], v[188:191], v[56:59]
	v_mfma_f32_16x16x32_bf16 v[44:47], v[154:157], v[196:199], v[44:47]
	v_mfma_f32_16x16x32_bf16 v[40:43], v[162:165], v[196:199], v[40:43]
	v_mfma_f32_16x16x32_bf16 v[28:31], v[154:157], v[204:207], v[28:31]
	v_mfma_f32_16x16x32_bf16 v[24:27], v[162:165], v[204:207], v[24:27]
	v_mfma_f32_16x16x32_bf16 v[12:15], v[154:157], v[212:215], v[12:15]
	v_mfma_f32_16x16x32_bf16 v[8:11], v[162:165], v[212:215], v[8:11]
	v_mfma_f32_16x16x32_bf16 v[60:63], v[158:161], v[192:195], v[60:63]
	v_mfma_f32_16x16x32_bf16 v[56:59], v[166:169], v[192:195], v[56:59]
	v_mfma_f32_16x16x32_bf16 v[44:47], v[158:161], v[200:203], v[44:47]
	v_mfma_f32_16x16x32_bf16 v[40:43], v[166:169], v[200:203], v[40:43]
	v_mfma_f32_16x16x32_bf16 v[28:31], v[158:161], v[208:211], v[28:31]
	v_mfma_f32_16x16x32_bf16 v[24:27], v[166:169], v[208:211], v[24:27]
	v_mfma_f32_16x16x32_bf16 v[12:15], v[158:161], v[216:219], v[12:15]
	v_mfma_f32_16x16x32_bf16 v[8:11], v[166:169], v[216:219], v[8:11]
	s_setprio 0
	s_setprio 3
	v_mfma_f32_16x16x32_bf16 v[52:55], v[170:173], v[188:191], v[52:55]
	v_mfma_f32_16x16x32_bf16 v[48:51], v[178:181], v[188:191], v[48:51]
	v_mfma_f32_16x16x32_bf16 v[36:39], v[170:173], v[196:199], v[36:39]
	v_mfma_f32_16x16x32_bf16 v[32:35], v[178:181], v[196:199], v[32:35]
	v_mfma_f32_16x16x32_bf16 v[20:23], v[170:173], v[204:207], v[20:23]
	v_mfma_f32_16x16x32_bf16 v[16:19], v[178:181], v[204:207], v[16:19]
	v_mfma_f32_16x16x32_bf16 v[4:7], v[170:173], v[212:215], v[4:7]
	v_mfma_f32_16x16x32_bf16 v[0:3], v[178:181], v[212:215], v[0:3]
	v_mfma_f32_16x16x32_bf16 v[52:55], v[174:177], v[192:195], v[52:55]
	v_mfma_f32_16x16x32_bf16 v[48:51], v[182:185], v[192:195], v[48:51]
	v_mfma_f32_16x16x32_bf16 v[36:39], v[174:177], v[200:203], v[36:39]
	v_mfma_f32_16x16x32_bf16 v[32:35], v[182:185], v[200:203], v[32:35]
	v_mfma_f32_16x16x32_bf16 v[20:23], v[174:177], v[208:211], v[20:23]
	v_mfma_f32_16x16x32_bf16 v[16:19], v[182:185], v[208:211], v[16:19]
	v_mfma_f32_16x16x32_bf16 v[4:7], v[174:177], v[216:219], v[4:7]
	v_mfma_f32_16x16x32_bf16 v[0:3], v[182:185], v[216:219], v[0:3]
	s_setprio 0
	s_barrier
	s_add_i32 s69, s69, 2
	s_add_u32 s30, s30, 0x100
	s_addc_u32 s31, s31, 0
	s_cmp_gt_u32 s69, 29
	s_cbranch_scc0 .LBB0_763
	s_branch .Lpeel_exit_2
.LBB0_763:
	ds_read_b128 v[154:157], v151
	ds_read_b128 v[158:161], v151 offset:1024
	ds_read_b128 v[162:165], v151 offset:2048
	ds_read_b128 v[166:169], v151 offset:3072
	ds_read_b128 v[170:173], v152
	ds_read_b128 v[174:177], v152 offset:1024
	ds_read_b128 v[178:181], v152 offset:2048
	ds_read_b128 v[182:185], v152 offset:3072
	s_add_u32 s34, s28, s30
	s_addc_u32 s35, s29, s31
	s_add_u32 s36, s34, 0x100
	s_addc_u32 s37, s35, 0
	s_add_u32 s34, s51, s30
	s_addc_u32 s35, s68, s31
	s_cmpk_eq_i32 s30, 0xf00
	s_cselect_b32 s35, s19, s35
	s_cselect_b32 s34, s49, s34
	s_cselect_b32 s37, s21, s37
	s_cselect_b32 s36, s48, s36
	v_lshl_add_u64 v[220:221], v[146:147], 0, s[30:31]
	v_lshl_add_u64 v[222:223], v[220:221], 0, s[8:9]
	s_add_i32 m0, s27, 0x8000
	ds_read_b128 v[188:191], v153
	ds_read_b128 v[192:195], v153 offset:1024
	ds_read_b128 v[196:199], v153 offset:2048
	ds_read_b128 v[200:203], v153 offset:3072
	ds_read_b128 v[204:207], v153 offset:4096
	ds_read_b128 v[208:211], v153 offset:5120
	ds_read_b128 v[212:215], v153 offset:6144
	ds_read_b128 v[216:219], v153 offset:7168
	global_load_lds_dwordx4 v[222:223], off
	v_lshl_add_u64 v[222:223], v[144:145], 0, s[30:31]
	v_lshl_add_u64 v[224:225], v[222:223], 0, s[8:9]
	s_add_i32 m0, s27, 0xa000
	v_lshl_add_u64 v[220:221], v[220:221], 0, s[14:15]
	global_load_lds_dwordx4 v[224:225], off
	s_add_i32 m0, s27, 0xc000
	s_nop 0
	global_load_lds_dwordx4 v[220:221], off
	v_lshl_add_u64 v[220:221], v[222:223], 0, s[14:15]
	s_add_i32 m0, s27, 0xe000
	s_nop 0
	global_load_lds_dwordx4 v[220:221], off
	s_waitcnt vmcnt(8)
	s_waitcnt lgkmcnt(0)
	s_barrier
; #define PG8_STAGE(bufoff, gbase, voff) do { _Pragma("unroll") for (int _i = 0; _i < 2; ++_i) \
;         __builtin_amdgcn_global_load_lds((const unsigned*)((const char*)(gbase) + (voff)[_i]), (LAS unsigned*)(lds + (bufoff) + ldsw + _i * 8192), 16, 0, 0); } while (0)
; #define PG8_LDA(dst, b, h) do { _Pragma("unroll") for (int m = 0; m < 4; ++m) _Pragma("unroll") for (int k = 0; k < 2; ++k) dst[m][k] = *(const LAS bf16x8*)(lds + PG8_SA(b, h) + aoff + m * 2048 + k * 1024); } while (0)
; #define PG8_MMA(ai, bj, At, Bt) do { __builtin_amdgcn_s_setprio(3); _Pragma("unroll") for (int m = 0; m < 4; ++m) _Pragma("unroll") for (int n = 0; n < 2; ++n) _Pragma("unroll") for (int k = 0; k < 2; ++k) \
;         acc[ai][bj][m][n] = __builtin_amdgcn_mfma_f32_16x16x32_bf16(Bt[n][k], At[m][k], acc[ai][bj][m][n], 0, 0, 0); __builtin_amdgcn_s_setprio(0); } while (0)
; #define PG8_WAIT_V(n) asm volatile("s_waitcnt vmcnt(" #n ")" ::: "memory")
; #define PG8_WAIT_L(n) asm volatile("s_waitcnt lgkmcnt(" #n ")" ::: "memory")
; #define PG8_BAR __builtin_amdgcn_s_barrier()
; #define PG8_SCHED __builtin_amdgcn_sched_barrier(0)
; template <class Epi, class Sched>
; __device__ __forceinline__ void gemm_phase(LAS unsigned char* lds, const Gemm g, const Sched& S, const Epi& E, int tid_in) {
;     ...
;             PG8_WAIT_V(8); PG8_WAIT_L(0); PG8_BAR; PG8_MMA(0, 0, At, B0); PG8_MMA(0, 1, At, B1); PG8_BAR; PG8_SCHED;
;             PG8_LDA(At, 0, 1); PG8_STAGE(PG8_SB(0, 0), b2, voffB); PG8_STAGE(PG8_SB(0, 1), b2 + hstep, voffB);
;             PG8_WAIT_V(6); PG8_WAIT_L(0); PG8_BAR; PG8_MMA(1, 0, At, B0); PG8_MMA(1, 1, At, B1); PG8_BAR; PG8_SCHED;
	s_setprio 3
	v_mfma_f32_16x16x32_bf16 v[124:127], v[154:157], v[188:191], v[124:127]
	v_mfma_f32_16x16x32_bf16 v[120:123], v[162:165], v[188:191], v[120:123]
	v_mfma_f32_16x16x32_bf16 v[108:111], v[154:157], v[196:199], v[108:111]
	v_mfma_f32_16x16x32_bf16 v[104:107], v[162:165], v[196:199], v[104:107]
	v_mfma_f32_16x16x32_bf16 v[92:95], v[154:157], v[204:207], v[92:95]
	v_mfma_f32_16x16x32_bf16 v[88:91], v[162:165], v[204:207], v[88:91]
	v_mfma_f32_16x16x32_bf16 v[76:79], v[154:157], v[212:215], v[76:79]
	v_mfma_f32_16x16x32_bf16 v[72:75], v[162:165], v[212:215], v[72:75]
	v_mfma_f32_16x16x32_bf16 v[124:127], v[158:161], v[192:195], v[124:127]
	v_mfma_f32_16x16x32_bf16 v[120:123], v[166:169], v[192:195], v[120:123]
	v_mfma_f32_16x16x32_bf16 v[108:111], v[158:161], v[200:203], v[108:111]
	v_mfma_f32_16x16x32_bf16 v[104:107], v[166:169], v[200:203], v[104:107]
	v_mfma_f32_16x16x32_bf16 v[92:95], v[158:161], v[208:211], v[92:95]
	v_mfma_f32_16x16x32_bf16 v[88:91], v[166:169], v[208:211], v[88:91]
	v_mfma_f32_16x16x32_bf16 v[76:79], v[158:161], v[216:219], v[76:79]
	v_mfma_f32_16x16x32_bf16 v[72:75], v[166:169], v[216:219], v[72:75]
	s_setprio 0
	s_setprio 3
	v_mfma_f32_16x16x32_bf16 v[116:119], v[170:173], v[188:191], v[116:119]
	v_mfma_f32_16x16x32_bf16 v[112:115], v[178:181], v[188:191], v[112:115]
	v_mfma_f32_16x16x32_bf16 v[100:103], v[170:173], v[196:199], v[100:103]
	v_mfma_f32_16x16x32_bf16 v[96:99], v[178:181], v[196:199], v[96:99]
	v_mfma_f32_16x16x32_bf16 v[84:87], v[170:173], v[204:207], v[84:87]
	v_mfma_f32_16x16x32_bf16 v[80:83], v[178:181], v[204:207], v[80:83]
	v_mfma_f32_16x16x32_bf16 v[68:71], v[170:173], v[212:215], v[68:71]
	v_mfma_f32_16x16x32_bf16 v[64:67], v[178:181], v[212:215], v[64:67]
	v_mfma_f32_16x16x32_bf16 v[116:119], v[174:177], v[192:195], v[116:119]
	v_mfma_f32_16x16x32_bf16 v[112:115], v[182:185], v[192:195], v[112:115]
	v_mfma_f32_16x16x32_bf16 v[100:103], v[174:177], v[200:203], v[100:103]
	v_mfma_f32_16x16x32_bf16 v[96:99], v[182:185], v[200:203], v[96:99]
	v_mfma_f32_16x16x32_bf16 v[84:87], v[174:177], v[208:211], v[84:87]
	v_mfma_f32_16x16x32_bf16 v[80:83], v[182:185], v[208:211], v[80:83]
	v_mfma_f32_16x16x32_bf16 v[68:71], v[174:177], v[216:219], v[68:71]
	v_mfma_f32_16x16x32_bf16 v[64:67], v[182:185], v[216:219], v[64:67]
	s_setprio 0
	s_barrier
	s_add_i32 s70, s44, s38
	v_lshl_add_u64 v[220:221], s[34:35], 0, v[132:133]
	s_mov_b32 m0, s70
	ds_read_b128 v[188:191], v153 offset:16384
	ds_read_b128 v[192:195], v153 offset:17408
	ds_read_b128 v[196:199], v153 offset:18432
	ds_read_b128 v[200:203], v153 offset:19456
	ds_read_b128 v[204:207], v153 offset:20480
	ds_read_b128 v[208:211], v153 offset:21504
	ds_read_b128 v[212:215], v153 offset:22528
	ds_read_b128 v[216:219], v153 offset:23552
	global_load_lds_dwordx4 v[220:221], off
	s_add_i32 m0, s70, 0x2000
	s_add_u32 s70, s34, 0x80000
	v_lshl_add_u64 v[222:223], s[34:35], 0, v[128:129]
	s_addc_u32 s71, s35, 0
	s_add_i32 s72, s45, s38
	global_load_lds_dwordx4 v[222:223], off
	v_lshl_add_u64 v[224:225], s[70:71], 0, v[132:133]
	s_mov_b32 m0, s72
	s_nop 0
	global_load_lds_dwordx4 v[224:225], off
	v_lshl_add_u64 v[224:225], s[70:71], 0, v[128:129]
	s_add_i32 m0, s72, 0x2000
	s_nop 0
	global_load_lds_dwordx4 v[224:225], off
	s_waitcnt vmcnt(6)
	s_waitcnt lgkmcnt(0)
	s_barrier
	s_setprio 3
	v_mfma_f32_16x16x32_bf16 v[60:63], v[154:157], v[188:191], v[60:63]
	v_mfma_f32_16x16x32_bf16 v[56:59], v[162:165], v[188:191], v[56:59]
	v_mfma_f32_16x16x32_bf16 v[44:47], v[154:157], v[196:199], v[44:47]
	v_mfma_f32_16x16x32_bf16 v[40:43], v[162:165], v[196:199], v[40:43]
	v_mfma_f32_16x16x32_bf16 v[28:31], v[154:157], v[204:207], v[28:31]
	v_mfma_f32_16x16x32_bf16 v[24:27], v[162:165], v[204:207], v[24:27]
	v_mfma_f32_16x16x32_bf16 v[12:15], v[154:157], v[212:215], v[12:15]
	v_mfma_f32_16x16x32_bf16 v[8:11], v[162:165], v[212:215], v[8:11]
	v_mfma_f32_16x16x32_bf16 v[60:63], v[158:161], v[192:195], v[60:63]
	v_mfma_f32_16x16x32_bf16 v[56:59], v[166:169], v[192:195], v[56:59]
	v_mfma_f32_16x16x32_bf16 v[44:47], v[158:161], v[200:203], v[44:47]
	v_mfma_f32_16x16x32_bf16 v[40:43], v[166:169], v[200:203], v[40:43]
	v_mfma_f32_16x16x32_bf16 v[28:31], v[158:161], v[208:211], v[28:31]
	v_mfma_f32_16x16x32_bf16 v[24:27], v[166:169], v[208:211], v[24:27]
	v_mfma_f32_16x16x32_bf16 v[12:15], v[158:161], v[216:219], v[12:15]
	v_mfma_f32_16x16x32_bf16 v[8:11], v[166:169], v[216:219], v[8:11]
	s_setprio 0
	s_setprio 3
	v_mfma_f32_16x16x32_bf16 v[52:55], v[170:173], v[188:191], v[52:55]
	v_mfma_f32_16x16x32_bf16 v[48:51], v[178:181], v[188:191], v[48:51]
	v_mfma_f32_16x16x32_bf16 v[36:39], v[170:173], v[196:199], v[36:39]
	v_mfma_f32_16x16x32_bf16 v[32:35], v[178:181], v[196:199], v[32:35]
	v_mfma_f32_16x16x32_bf16 v[20:23], v[170:173], v[204:207], v[20:23]
	v_mfma_f32_16x16x32_bf16 v[16:19], v[178:181], v[204:207], v[16:19]
	v_mfma_f32_16x16x32_bf16 v[4:7], v[170:173], v[212:215], v[4:7]
	v_mfma_f32_16x16x32_bf16 v[0:3], v[178:181], v[212:215], v[0:3]
	v_mfma_f32_16x16x32_bf16 v[52:55], v[174:177], v[192:195], v[52:55]
	v_mfma_f32_16x16x32_bf16 v[48:51], v[182:185], v[192:195], v[48:51]
	v_mfma_f32_16x16x32_bf16 v[36:39], v[174:177], v[200:203], v[36:39]
	v_mfma_f32_16x16x32_bf16 v[32:35], v[182:185], v[200:203], v[32:35]
	v_mfma_f32_16x16x32_bf16 v[20:23], v[174:177], v[208:211], v[20:23]
	v_mfma_f32_16x16x32_bf16 v[16:19], v[182:185], v[208:211], v[16:19]
	v_mfma_f32_16x16x32_bf16 v[4:7], v[174:177], v[216:219], v[4:7]
	v_mfma_f32_16x16x32_bf16 v[0:3], v[182:185], v[216:219], v[0:3]
	s_setprio 0
	s_barrier
; #define PG8_STAGE(bufoff, gbase, voff) do { _Pragma("unroll") for (int _i = 0; _i < 2; ++_i) \
;         __builtin_amdgcn_global_load_lds((const unsigned*)((const char*)(gbase) + (voff)[_i]), (LAS unsigned*)(lds + (bufoff) + ldsw + _i * 8192), 16, 0, 0); } while (0)
; #define PG8_LDA(dst, b, h) do { _Pragma("unroll") for (int m = 0; m < 4; ++m) _Pragma("unroll") for (int k = 0; k < 2; ++k) dst[m][k] = *(const LAS bf16x8*)(lds + PG8_SA(b, h) + aoff + m * 2048 + k * 1024); } while (0)
; #define PG8_LDB(dst, b, h) do { _Pragma("unroll") for (int n = 0; n < 2; ++n) _Pragma("unroll") for (int k = 0; k < 2; ++k) dst[n][k] = *(const LAS bf16x8*)(lds + PG8_SB(b, h) + boff + n * 2048 + k * 1024); } while (0)
; #define PG8_MMA(ai, bj, At, Bt) do { __builtin_amdgcn_s_setprio(3); _Pragma("unroll") for (int m = 0; m < 4; ++m) _Pragma("unroll") for (int n = 0; n < 2; ++n) _Pragma("unroll") for (int k = 0; k < 2; ++k) \
;         acc[ai][bj][m][n] = __builtin_amdgcn_mfma_f32_16x16x32_bf16(Bt[n][k], At[m][k], acc[ai][bj][m][n], 0, 0, 0); __builtin_amdgcn_s_setprio(0); } while (0)
; #define PG8_WAIT_V(n) asm volatile("s_waitcnt vmcnt(" #n ")" ::: "memory")
; #define PG8_WAIT_L(n) asm volatile("s_waitcnt lgkmcnt(" #n ")" ::: "memory")
; #define PG8_BAR __builtin_amdgcn_s_barrier()
; #define PG8_SCHED __builtin_amdgcn_sched_barrier(0)
; template <class Epi, class Sched>
; __device__ __forceinline__ void gemm_phase(LAS unsigned char* lds, const Gemm g, const Sched& S, const Epi& E, int tid_in) {
;     ...
;             PG8_LDB(B0, 1, 0); PG8_LDB(B1, 1, 1); PG8_SCHED; PG8_LDA(At, 1, 0); PG8_STAGE(PG8_SA(0, 0), a2, voffA); PG8_STAGE(PG8_SA(0, 1), a2 + hstep, voffA);
;             PG8_WAIT_V(8); PG8_WAIT_L(0); PG8_BAR; PG8_MMA(0, 0, At, B0); PG8_MMA(0, 1, At, B1); PG8_BAR; PG8_SCHED;
;             PG8_LDA(At, 1, 1); PG8_STAGE(PG8_SB(1, 0), b3, voffB); PG8_STAGE(PG8_SB(1, 1), b3 + hstep, voffB);
;             PG8_WAIT_V(6); PG8_WAIT_L(0); PG8_BAR; PG8_MMA(1, 0, At, B0); PG8_MMA(1, 1, At, B1); PG8_BAR; PG8_SCHED;
	s_add_i32 s70, 0, 0x18000
	s_add_i32 s71, 0, 0x1c000
	v_add_u32_e32 v166, s70, v149
	v_add_u32_e32 v182, s71, v149
	ds_read_b128 v[154:157], v166
	ds_read_b128 v[158:161], v166 offset:1024
	ds_read_b128 v[162:165], v166 offset:2048
	ds_read_b128 v[166:169], v166 offset:3072
	ds_read_b128 v[170:173], v182
	ds_read_b128 v[174:177], v182 offset:1024
	ds_read_b128 v[178:181], v182 offset:2048
	ds_read_b128 v[182:185], v182 offset:3072
	s_mov_b32 m0, s27
	v_lshl_add_u64 v[224:225], s[36:37], 0, v[134:135]
	ds_read_b128 v[188:191], v153 offset:32768
	ds_read_b128 v[192:195], v153 offset:33792
	ds_read_b128 v[196:199], v153 offset:34816
	ds_read_b128 v[200:203], v153 offset:35840
	ds_read_b128 v[204:207], v153 offset:36864
	ds_read_b128 v[208:211], v153 offset:37888
	ds_read_b128 v[212:215], v153 offset:38912
	ds_read_b128 v[216:219], v153 offset:39936
	global_load_lds_dwordx4 v[224:225], off
	v_lshl_add_u64 v[224:225], s[36:37], 0, v[130:131]
	s_add_u32 s36, s36, 0x80000
	s_mov_b32 m0, s40
	s_addc_u32 s37, s37, 0
	global_load_lds_dwordx4 v[224:225], off
	v_lshl_add_u64 v[224:225], s[36:37], 0, v[134:135]
	s_mov_b32 m0, s41
	s_nop 0
	global_load_lds_dwordx4 v[224:225], off
	v_lshl_add_u64 v[224:225], s[36:37], 0, v[130:131]
	s_mov_b32 m0, s42
	s_nop 0
	global_load_lds_dwordx4 v[224:225], off
	s_waitcnt vmcnt(8)
	s_waitcnt lgkmcnt(0)
	s_barrier
	s_setprio 3
	v_mfma_f32_16x16x32_bf16 v[124:127], v[154:157], v[188:191], v[124:127]
	v_mfma_f32_16x16x32_bf16 v[120:123], v[162:165], v[188:191], v[120:123]
	v_mfma_f32_16x16x32_bf16 v[108:111], v[154:157], v[196:199], v[108:111]
	v_mfma_f32_16x16x32_bf16 v[104:107], v[162:165], v[196:199], v[104:107]
	v_mfma_f32_16x16x32_bf16 v[92:95], v[154:157], v[204:207], v[92:95]
	v_mfma_f32_16x16x32_bf16 v[88:91], v[162:165], v[204:207], v[88:91]
	v_mfma_f32_16x16x32_bf16 v[76:79], v[154:157], v[212:215], v[76:79]
	v_mfma_f32_16x16x32_bf16 v[72:75], v[162:165], v[212:215], v[72:75]
	v_mfma_f32_16x16x32_bf16 v[124:127], v[158:161], v[192:195], v[124:127]
	v_mfma_f32_16x16x32_bf16 v[120:123], v[166:169], v[192:195], v[120:123]
	v_mfma_f32_16x16x32_bf16 v[108:111], v[158:161], v[200:203], v[108:111]
	v_mfma_f32_16x16x32_bf16 v[104:107], v[166:169], v[200:203], v[104:107]
	v_mfma_f32_16x16x32_bf16 v[92:95], v[158:161], v[208:211], v[92:95]
	v_mfma_f32_16x16x32_bf16 v[88:91], v[166:169], v[208:211], v[88:91]
	v_mfma_f32_16x16x32_bf16 v[76:79], v[158:161], v[216:219], v[76:79]
	v_mfma_f32_16x16x32_bf16 v[72:75], v[166:169], v[216:219], v[72:75]
	s_setprio 0
	s_setprio 3
	v_mfma_f32_16x16x32_bf16 v[116:119], v[170:173], v[188:191], v[116:119]
	v_mfma_f32_16x16x32_bf16 v[112:115], v[178:181], v[188:191], v[112:115]
	v_mfma_f32_16x16x32_bf16 v[100:103], v[170:173], v[196:199], v[100:103]
	v_mfma_f32_16x16x32_bf16 v[96:99], v[178:181], v[196:199], v[96:99]
	v_mfma_f32_16x16x32_bf16 v[84:87], v[170:173], v[204:207], v[84:87]
	v_mfma_f32_16x16x32_bf16 v[80:83], v[178:181], v[204:207], v[80:83]
	v_mfma_f32_16x16x32_bf16 v[68:71], v[170:173], v[212:215], v[68:71]
	v_mfma_f32_16x16x32_bf16 v[64:67], v[178:181], v[212:215], v[64:67]
	v_mfma_f32_16x16x32_bf16 v[116:119], v[174:177], v[192:195], v[116:119]
	v_mfma_f32_16x16x32_bf16 v[112:115], v[182:185], v[192:195], v[112:115]
	v_mfma_f32_16x16x32_bf16 v[100:103], v[174:177], v[200:203], v[100:103]
	v_mfma_f32_16x16x32_bf16 v[96:99], v[182:185], v[200:203], v[96:99]
	v_mfma_f32_16x16x32_bf16 v[84:87], v[174:177], v[208:211], v[84:87]
	v_mfma_f32_16x16x32_bf16 v[80:83], v[182:185], v[208:211], v[80:83]
	v_mfma_f32_16x16x32_bf16 v[68:71], v[174:177], v[216:219], v[68:71]
	v_mfma_f32_16x16x32_bf16 v[64:67], v[182:185], v[216:219], v[64:67]
	s_setprio 0
	s_barrier
	s_add_i32 s36, s70, s38
	v_lshl_add_u64 v[220:221], v[220:221], 0, s[8:9]
	s_mov_b32 m0, s36
	ds_read_b128 v[188:191], v153 offset:49152
	ds_read_b128 v[192:195], v153 offset:50176
	ds_read_b128 v[196:199], v153 offset:51200
	ds_read_b128 v[200:203], v153 offset:52224
	ds_read_b128 v[204:207], v153 offset:53248
	ds_read_b128 v[208:211], v153 offset:54272
	ds_read_b128 v[212:215], v153 offset:55296
	ds_read_b128 v[216:219], v153 offset:56320
	global_load_lds_dwordx4 v[220:221], off
	s_add_i32 m0, s36, 0x2000
	s_add_u32 s34, s34, 0x80080
	v_lshl_add_u64 v[220:221], v[222:223], 0, s[8:9]
	s_addc_u32 s35, s35, 0
	s_add_i32 s36, s71, s38
	global_load_lds_dwordx4 v[220:221], off
	v_lshl_add_u64 v[220:221], s[34:35], 0, v[132:133]
	s_mov_b32 m0, s36
	s_nop 0
	global_load_lds_dwordx4 v[220:221], off
	v_lshl_add_u64 v[220:221], s[34:35], 0, v[128:129]
	s_add_i32 m0, s36, 0x2000
	s_nop 0
	global_load_lds_dwordx4 v[220:221], off
	s_waitcnt vmcnt(6)
	s_waitcnt lgkmcnt(0)
	s_barrier
	s_setprio 3
	v_mfma_f32_16x16x32_bf16 v[60:63], v[154:157], v[188:191], v[60:63]
	v_mfma_f32_16x16x32_bf16 v[56:59], v[162:165], v[188:191], v[56:59]
	v_mfma_f32_16x16x32_bf16 v[44:47], v[154:157], v[196:199], v[44:47]
	v_mfma_f32_16x16x32_bf16 v[40:43], v[162:165], v[196:199], v[40:43]
	v_mfma_f32_16x16x32_bf16 v[28:31], v[154:157], v[204:207], v[28:31]
	v_mfma_f32_16x16x32_bf16 v[24:27], v[162:165], v[204:207], v[24:27]
	v_mfma_f32_16x16x32_bf16 v[12:15], v[154:157], v[212:215], v[12:15]
	v_mfma_f32_16x16x32_bf16 v[8:11], v[162:165], v[212:215], v[8:11]
	v_mfma_f32_16x16x32_bf16 v[60:63], v[158:161], v[192:195], v[60:63]
	v_mfma_f32_16x16x32_bf16 v[56:59], v[166:169], v[192:195], v[56:59]
	v_mfma_f32_16x16x32_bf16 v[44:47], v[158:161], v[200:203], v[44:47]
	v_mfma_f32_16x16x32_bf16 v[40:43], v[166:169], v[200:203], v[40:43]
	v_mfma_f32_16x16x32_bf16 v[28:31], v[158:161], v[208:211], v[28:31]
	v_mfma_f32_16x16x32_bf16 v[24:27], v[166:169], v[208:211], v[24:27]
	v_mfma_f32_16x16x32_bf16 v[12:15], v[158:161], v[216:219], v[12:15]
	v_mfma_f32_16x16x32_bf16 v[8:11], v[166:169], v[216:219], v[8:11]
	s_setprio 0
	s_setprio 3
	v_mfma_f32_16x16x32_bf16 v[52:55], v[170:173], v[188:191], v[52:55]
	v_mfma_f32_16x16x32_bf16 v[48:51], v[178:181], v[188:191], v[48:51]
	v_mfma_f32_16x16x32_bf16 v[36:39], v[170:173], v[196:199], v[36:39]
	v_mfma_f32_16x16x32_bf16 v[32:35], v[178:181], v[196:199], v[32:35]
	v_mfma_f32_16x16x32_bf16 v[20:23], v[170:173], v[204:207], v[20:23]
	v_mfma_f32_16x16x32_bf16 v[16:19], v[178:181], v[204:207], v[16:19]
	v_mfma_f32_16x16x32_bf16 v[4:7], v[170:173], v[212:215], v[4:7]
	v_mfma_f32_16x16x32_bf16 v[0:3], v[178:181], v[212:215], v[0:3]
	v_mfma_f32_16x16x32_bf16 v[52:55], v[174:177], v[192:195], v[52:55]
	v_mfma_f32_16x16x32_bf16 v[48:51], v[182:185], v[192:195], v[48:51]
	v_mfma_f32_16x16x32_bf16 v[36:39], v[174:177], v[200:203], v[36:39]
	v_mfma_f32_16x16x32_bf16 v[32:35], v[182:185], v[200:203], v[32:35]
	v_mfma_f32_16x16x32_bf16 v[20:23], v[174:177], v[208:211], v[20:23]
	v_mfma_f32_16x16x32_bf16 v[16:19], v[182:185], v[208:211], v[16:19]
	v_mfma_f32_16x16x32_bf16 v[4:7], v[174:177], v[216:219], v[4:7]
	v_mfma_f32_16x16x32_bf16 v[0:3], v[182:185], v[216:219], v[0:3]
	s_setprio 0
	s_barrier
	s_add_i32 s69, s69, 2
	s_add_u32 s30, s30, 0x100
	s_addc_u32 s31, s31, 0
	s_cmp_gt_u32 s69, 29
	s_cbranch_scc0 .LBB0_763

; #define PG8_STAGE(bufoff, gbase, voff) do { _Pragma("unroll") for (int _i = 0; _i < 2; ++_i) \
;         __builtin_amdgcn_global_load_lds((const unsigned*)((const char*)(gbase) + (voff)[_i]), (LAS unsigned*)(lds + (bufoff) + ldsw + _i * 8192), 16, 0, 0); } while (0)
; #define PG8_LDA(dst, b, h) do { _Pragma("unroll") for (int m = 0; m < 4; ++m) _Pragma("unroll") for (int k = 0; k < 2; ++k) dst[m][k] = *(const LAS bf16x8*)(lds + PG8_SA(b, h) + aoff + m * 2048 + k * 1024); } while (0)
; #define PG8_LDB(dst, b, h) do { _Pragma("unroll") for (int n = 0; n < 2; ++n) _Pragma("unroll") for (int k = 0; k < 2; ++k) dst[n][k] = *(const LAS bf16x8*)(lds + PG8_SB(b, h) + boff + n * 2048 + k * 1024); } while (0)
; #define PG8_MMA(ai, bj, At, Bt) do { __builtin_amdgcn_s_setprio(3); _Pragma("unroll") for (int m = 0; m < 4; ++m) _Pragma("unroll") for (int n = 0; n < 2; ++n) _Pragma("unroll") for (int k = 0; k < 2; ++k) \
;         acc[ai][bj][m][n] = __builtin_amdgcn_mfma_f32_16x16x32_bf16(Bt[n][k], At[m][k], acc[ai][bj][m][n], 0, 0, 0); __builtin_amdgcn_s_setprio(0); } while (0)
; #define PG8_WAIT_V(n) asm volatile("s_waitcnt vmcnt(" #n ")" ::: "memory")
; #define PG8_WAIT_L(n) asm volatile("s_waitcnt lgkmcnt(" #n ")" ::: "memory")
; #define PG8_BAR __builtin_amdgcn_s_barrier()
; #define PG8_SCHED __builtin_amdgcn_sched_barrier(0)
; template <class Epi, class Sched>
; __device__ __forceinline__ void gemm_phase(LAS unsigned char* lds, const Gemm g, const Sched& S, const Epi& E, int tid_in) {
;     ...
;         for (int t = 0; t < nt; t += 2) {
;             const bool last = (t == nt - 2);
;             const char* a1 = cA + (size_t)(t + 1) * kstep;
;             const char* a2 = last ? nA : cA + (size_t)(t + 2) * kstep; const char* b2 = last ? nB : cB + (size_t)(t + 2) * kstep;
;             const char* a3 = a2 + kstep; const char* b3 = b2 + kstep;
;             PG8_LDB(B0, 0, 0); PG8_LDB(B1, 0, 1); PG8_SCHED; PG8_LDA(At, 0, 0); PG8_STAGE(PG8_SA(1, 0), a1, voffA); PG8_STAGE(PG8_SA(1, 1), a1 + hstep, voffA);
;             PG8_WAIT_V(8); PG8_WAIT_L(0); PG8_BAR; PG8_MMA(0, 0, At, B0); PG8_MMA(0, 1, At, B1); PG8_BAR; PG8_SCHED;
;             PG8_LDA(At, 0, 1); PG8_STAGE(PG8_SB(0, 0), b2, voffB); PG8_STAGE(PG8_SB(0, 1), b2 + hstep, voffB);
;             PG8_WAIT_V(6); PG8_WAIT_L(0); PG8_BAR; PG8_MMA(1, 0, At, B0); PG8_MMA(1, 1, At, B1); PG8_BAR; PG8_SCHED;
.LBB0_841:
	s_add_u32 s46, s28, 0x100
	s_addc_u32 s47, s29, 0
	v_lshl_add_u64 v[144:145], s[26:27], 0, v[136:137]
	v_lshl_add_u64 v[146:147], s[26:27], 0, v[138:139]
	s_mov_b32 s48, -2
	s_mov_b64 s[28:29], 0
	s_waitcnt lgkmcnt(0)
	ds_read_b128 v[156:159], v151
	ds_read_b128 v[160:163], v151 offset:1024
	ds_read_b128 v[164:167], v151 offset:2048
	ds_read_b128 v[168:171], v151 offset:3072
	ds_read_b128 v[172:175], v152
	ds_read_b128 v[176:179], v152 offset:1024
	ds_read_b128 v[180:183], v152 offset:2048
	ds_read_b128 v[188:191], v152 offset:3072
	s_add_u32 s30, s26, s28
	s_addc_u32 s31, s27, s29
	s_add_u32 s34, s30, 0x100
	s_addc_u32 s35, s31, 0
	s_add_u32 s30, s46, s28
	s_addc_u32 s31, s47, s29
	s_cmpk_eq_i32 s28, 0x2b00
	s_cselect_b32 s31, s25, s31
	s_cselect_b32 s30, s24, s30
	s_cselect_b32 s35, s7, s35
	s_cselect_b32 s34, s6, s34
	v_lshl_add_u64 v[184:185], v[144:145], 0, s[28:29]
	v_lshl_add_u64 v[224:225], v[184:185], 0, s[18:19]
	s_add_i32 m0, s3, 0x8000
	ds_read_b128 v[192:195], v153
	ds_read_b128 v[196:199], v153 offset:1024
	ds_read_b128 v[200:203], v153 offset:2048
	ds_read_b128 v[204:207], v153 offset:3072
	ds_read_b128 v[208:211], v153 offset:4096
	ds_read_b128 v[212:215], v153 offset:5120
	ds_read_b128 v[216:219], v153 offset:6144
	ds_read_b128 v[220:223], v153 offset:7168
	global_load_lds_dwordx4 v[224:225], off
	v_lshl_add_u64 v[224:225], v[146:147], 0, s[28:29]
	v_lshl_add_u64 v[226:227], v[224:225], 0, s[18:19]
	s_add_i32 m0, s3, 0xa000
	v_lshl_add_u64 v[184:185], v[184:185], 0, s[20:21]
	global_load_lds_dwordx4 v[226:227], off
	s_add_i32 m0, s3, 0xc000
	s_nop 0
	global_load_lds_dwordx4 v[184:185], off
	v_lshl_add_u64 v[184:185], v[224:225], 0, s[20:21]
	s_add_i32 m0, s3, 0xe000
	s_nop 0
	global_load_lds_dwordx4 v[184:185], off
	s_waitcnt vmcnt(8)
	s_waitcnt lgkmcnt(0)
	s_barrier
	s_setprio 3
	v_mfma_f32_16x16x32_bf16 v[124:127], v[156:159], v[192:195], 0
	v_mfma_f32_16x16x32_bf16 v[120:123], v[164:167], v[192:195], 0
	v_mfma_f32_16x16x32_bf16 v[108:111], v[156:159], v[200:203], 0
	v_mfma_f32_16x16x32_bf16 v[104:107], v[164:167], v[200:203], 0
	v_mfma_f32_16x16x32_bf16 v[92:95], v[156:159], v[208:211], 0
	v_mfma_f32_16x16x32_bf16 v[88:91], v[164:167], v[208:211], 0
	v_mfma_f32_16x16x32_bf16 v[76:79], v[156:159], v[216:219], 0
	v_mfma_f32_16x16x32_bf16 v[72:75], v[164:167], v[216:219], 0
	v_mfma_f32_16x16x32_bf16 v[124:127], v[160:163], v[196:199], v[124:127]
	v_mfma_f32_16x16x32_bf16 v[120:123], v[168:171], v[196:199], v[120:123]
	v_mfma_f32_16x16x32_bf16 v[108:111], v[160:163], v[204:207], v[108:111]
	v_mfma_f32_16x16x32_bf16 v[104:107], v[168:171], v[204:207], v[104:107]
	v_mfma_f32_16x16x32_bf16 v[92:95], v[160:163], v[212:215], v[92:95]
	v_mfma_f32_16x16x32_bf16 v[88:91], v[168:171], v[212:215], v[88:91]
	v_mfma_f32_16x16x32_bf16 v[76:79], v[160:163], v[220:223], v[76:79]
	v_mfma_f32_16x16x32_bf16 v[72:75], v[168:171], v[220:223], v[72:75]
	s_setprio 0
	s_setprio 3
	v_mfma_f32_16x16x32_bf16 v[116:119], v[172:175], v[192:195], 0
	v_mfma_f32_16x16x32_bf16 v[112:115], v[180:183], v[192:195], 0
	v_mfma_f32_16x16x32_bf16 v[100:103], v[172:175], v[200:203], 0
	v_mfma_f32_16x16x32_bf16 v[96:99], v[180:183], v[200:203], 0
	v_mfma_f32_16x16x32_bf16 v[84:87], v[172:175], v[208:211], 0
	v_mfma_f32_16x16x32_bf16 v[80:83], v[180:183], v[208:211], 0
	v_mfma_f32_16x16x32_bf16 v[68:71], v[172:175], v[216:219], 0
	v_mfma_f32_16x16x32_bf16 v[64:67], v[180:183], v[216:219], 0
	v_mfma_f32_16x16x32_bf16 v[116:119], v[176:179], v[196:199], v[116:119]
	v_mfma_f32_16x16x32_bf16 v[112:115], v[188:191], v[196:199], v[112:115]
	v_mfma_f32_16x16x32_bf16 v[100:103], v[176:179], v[204:207], v[100:103]
	v_mfma_f32_16x16x32_bf16 v[96:99], v[188:191], v[204:207], v[96:99]
	v_mfma_f32_16x16x32_bf16 v[84:87], v[176:179], v[212:215], v[84:87]
	v_mfma_f32_16x16x32_bf16 v[80:83], v[188:191], v[212:215], v[80:83]
	v_mfma_f32_16x16x32_bf16 v[68:71], v[176:179], v[220:223], v[68:71]
	v_mfma_f32_16x16x32_bf16 v[64:67], v[188:191], v[220:223], v[64:67]
	s_setprio 0
	s_barrier
	s_add_i32 s49, s40, s2
	v_lshl_add_u64 v[184:185], s[30:31], 0, v[130:131]
	s_mov_b32 m0, s49
	ds_read_b128 v[192:195], v153 offset:16384
	ds_read_b128 v[196:199], v153 offset:17408
	ds_read_b128 v[200:203], v153 offset:18432
	ds_read_b128 v[204:207], v153 offset:19456
	ds_read_b128 v[208:211], v153 offset:20480
	ds_read_b128 v[212:215], v153 offset:21504
	ds_read_b128 v[216:219], v153 offset:22528
	ds_read_b128 v[220:223], v153 offset:23552
	global_load_lds_dwordx4 v[184:185], off
	s_add_i32 m0, s49, 0x2000
	s_add_u32 s68, s30, 0x160000
	v_lshl_add_u64 v[224:225], s[30:31], 0, v[134:135]
	s_addc_u32 s69, s31, 0
	s_add_i32 s49, s41, s2
	global_load_lds_dwordx4 v[224:225], off
	v_lshl_add_u64 v[226:227], s[68:69], 0, v[130:131]
	s_mov_b32 m0, s49
	s_nop 0
	global_load_lds_dwordx4 v[226:227], off
	v_lshl_add_u64 v[226:227], s[68:69], 0, v[134:135]
	s_add_i32 m0, s49, 0x2000
	s_nop 0
	global_load_lds_dwordx4 v[226:227], off
	s_waitcnt vmcnt(6)
	s_waitcnt lgkmcnt(0)
	s_barrier
; #define PG8_STAGE(bufoff, gbase, voff) do { _Pragma("unroll") for (int _i = 0; _i < 2; ++_i) \
;         __builtin_amdgcn_global_load_lds((const unsigned*)((const char*)(gbase) + (voff)[_i]), (LAS unsigned*)(lds + (bufoff) + ldsw + _i * 8192), 16, 0, 0); } while (0)
; #define PG8_LDA(dst, b, h) do { _Pragma("unroll") for (int m = 0; m < 4; ++m) _Pragma("unroll") for (int k = 0; k < 2; ++k) dst[m][k] = *(const LAS bf16x8*)(lds + PG8_SA(b, h) + aoff + m * 2048 + k * 1024); } while (0)
; #define PG8_LDB(dst, b, h) do { _Pragma("unroll") for (int n = 0; n < 2; ++n) _Pragma("unroll") for (int k = 0; k < 2; ++k) dst[n][k] = *(const LAS bf16x8*)(lds + PG8_SB(b, h) + boff + n * 2048 + k * 1024); } while (0)
; #define PG8_MMA(ai, bj, At, Bt) do { __builtin_amdgcn_s_setprio(3); _Pragma("unroll") for (int m = 0; m < 4; ++m) _Pragma("unroll") for (int n = 0; n < 2; ++n) _Pragma("unroll") for (int k = 0; k < 2; ++k) \
;         acc[ai][bj][m][n] = __builtin_amdgcn_mfma_f32_16x16x32_bf16(Bt[n][k], At[m][k], acc[ai][bj][m][n], 0, 0, 0); __builtin_amdgcn_s_setprio(0); } while (0)
; #define PG8_WAIT_V(n) asm volatile("s_waitcnt vmcnt(" #n ")" ::: "memory")
; #define PG8_WAIT_L(n) asm volatile("s_waitcnt lgkmcnt(" #n ")" ::: "memory")
; #define PG8_BAR __builtin_amdgcn_s_barrier()
; #define PG8_SCHED __builtin_amdgcn_sched_barrier(0)
; template <class Epi, class Sched>
; __device__ __forceinline__ void gemm_phase(LAS unsigned char* lds, const Gemm g, const Sched& S, const Epi& E, int tid_in) {
;     ...
;             PG8_WAIT_V(6); PG8_WAIT_L(0); PG8_BAR; PG8_MMA(1, 0, At, B0); PG8_MMA(1, 1, At, B1); PG8_BAR; PG8_SCHED;
;             PG8_LDB(B0, 1, 0); PG8_LDB(B1, 1, 1); PG8_SCHED; PG8_LDA(At, 1, 0); PG8_STAGE(PG8_SA(0, 0), a2, voffA); PG8_STAGE(PG8_SA(0, 1), a2 + hstep, voffA);
;             PG8_WAIT_V(8); PG8_WAIT_L(0); PG8_BAR; PG8_MMA(0, 0, At, B0); PG8_MMA(0, 1, At, B1); PG8_BAR; PG8_SCHED;
	s_setprio 3
	v_mfma_f32_16x16x32_bf16 v[60:63], v[156:159], v[192:195], 0
	v_mfma_f32_16x16x32_bf16 v[56:59], v[164:167], v[192:195], 0
	v_mfma_f32_16x16x32_bf16 v[44:47], v[156:159], v[200:203], 0
	v_mfma_f32_16x16x32_bf16 v[40:43], v[164:167], v[200:203], 0
	v_mfma_f32_16x16x32_bf16 v[28:31], v[156:159], v[208:211], 0
	v_mfma_f32_16x16x32_bf16 v[24:27], v[164:167], v[208:211], 0
	v_mfma_f32_16x16x32_bf16 v[12:15], v[156:159], v[216:219], 0
	v_mfma_f32_16x16x32_bf16 v[8:11], v[164:167], v[216:219], 0
	v_mfma_f32_16x16x32_bf16 v[60:63], v[160:163], v[196:199], v[60:63]
	v_mfma_f32_16x16x32_bf16 v[56:59], v[168:171], v[196:199], v[56:59]
	v_mfma_f32_16x16x32_bf16 v[44:47], v[160:163], v[204:207], v[44:47]
	v_mfma_f32_16x16x32_bf16 v[40:43], v[168:171], v[204:207], v[40:43]
	v_mfma_f32_16x16x32_bf16 v[28:31], v[160:163], v[212:215], v[28:31]
	v_mfma_f32_16x16x32_bf16 v[24:27], v[168:171], v[212:215], v[24:27]
	v_mfma_f32_16x16x32_bf16 v[12:15], v[160:163], v[220:223], v[12:15]
	v_mfma_f32_16x16x32_bf16 v[8:11], v[168:171], v[220:223], v[8:11]
	s_setprio 0
	s_setprio 3
	v_mfma_f32_16x16x32_bf16 v[52:55], v[172:175], v[192:195], 0
	v_mfma_f32_16x16x32_bf16 v[48:51], v[180:183], v[192:195], 0
	v_mfma_f32_16x16x32_bf16 v[36:39], v[172:175], v[200:203], 0
	v_mfma_f32_16x16x32_bf16 v[32:35], v[180:183], v[200:203], 0
	v_mfma_f32_16x16x32_bf16 v[20:23], v[172:175], v[208:211], 0
	v_mfma_f32_16x16x32_bf16 v[16:19], v[180:183], v[208:211], 0
	v_mfma_f32_16x16x32_bf16 v[4:7], v[172:175], v[216:219], 0
	v_mfma_f32_16x16x32_bf16 v[0:3], v[180:183], v[216:219], 0
	v_mfma_f32_16x16x32_bf16 v[52:55], v[176:179], v[196:199], v[52:55]
	v_mfma_f32_16x16x32_bf16 v[48:51], v[188:191], v[196:199], v[48:51]
	v_mfma_f32_16x16x32_bf16 v[36:39], v[176:179], v[204:207], v[36:39]
	v_mfma_f32_16x16x32_bf16 v[32:35], v[188:191], v[204:207], v[32:35]
	v_mfma_f32_16x16x32_bf16 v[20:23], v[176:179], v[212:215], v[20:23]
	v_mfma_f32_16x16x32_bf16 v[16:19], v[188:191], v[212:215], v[16:19]
	v_mfma_f32_16x16x32_bf16 v[4:7], v[176:179], v[220:223], v[4:7]
	v_mfma_f32_16x16x32_bf16 v[0:3], v[188:191], v[220:223], v[0:3]
	s_setprio 0
	s_barrier
	s_add_i32 s49, 0, 0x18000
	v_add_u32_e32 v155, s49, v149
	s_add_i32 s51, 0, 0x1c000
	ds_read_b128 v[156:159], v155
	ds_read_b128 v[160:163], v155 offset:1024
	ds_read_b128 v[164:167], v155 offset:2048
	ds_read_b128 v[168:171], v155 offset:3072
	v_add_u32_e32 v155, s51, v149
	ds_read_b128 v[172:175], v155
	ds_read_b128 v[176:179], v155 offset:1024
	ds_read_b128 v[180:183], v155 offset:2048
	ds_read_b128 v[188:191], v155 offset:3072
	s_mov_b32 m0, s3
	v_lshl_add_u64 v[226:227], s[34:35], 0, v[128:129]
	ds_read_b128 v[192:195], v153 offset:32768
	ds_read_b128 v[196:199], v153 offset:33792
	ds_read_b128 v[200:203], v153 offset:34816
	ds_read_b128 v[204:207], v153 offset:35840
	ds_read_b128 v[208:211], v153 offset:36864
	ds_read_b128 v[212:215], v153 offset:37888
	ds_read_b128 v[216:219], v153 offset:38912
	ds_read_b128 v[220:223], v153 offset:39936
	global_load_lds_dwordx4 v[226:227], off
	v_lshl_add_u64 v[226:227], s[34:35], 0, v[132:133]
	s_add_u32 s34, s34, 0x160000
	s_mov_b32 m0, s36
	s_addc_u32 s35, s35, 0
	global_load_lds_dwordx4 v[226:227], off
	v_lshl_add_u64 v[226:227], s[34:35], 0, v[128:129]
	s_mov_b32 m0, s37
	s_nop 0
	global_load_lds_dwordx4 v[226:227], off
	v_lshl_add_u64 v[226:227], s[34:35], 0, v[132:133]
	s_mov_b32 m0, s38
	s_nop 0
	global_load_lds_dwordx4 v[226:227], off
	s_waitcnt vmcnt(8)
	s_waitcnt lgkmcnt(0)
	s_barrier
	s_setprio 3
	v_mfma_f32_16x16x32_bf16 v[124:127], v[156:159], v[192:195], v[124:127]
	v_mfma_f32_16x16x32_bf16 v[120:123], v[164:167], v[192:195], v[120:123]
	v_mfma_f32_16x16x32_bf16 v[108:111], v[156:159], v[200:203], v[108:111]
	v_mfma_f32_16x16x32_bf16 v[104:107], v[164:167], v[200:203], v[104:107]
	v_mfma_f32_16x16x32_bf16 v[92:95], v[156:159], v[208:211], v[92:95]
	v_mfma_f32_16x16x32_bf16 v[88:91], v[164:167], v[208:211], v[88:91]
	v_mfma_f32_16x16x32_bf16 v[76:79], v[156:159], v[216:219], v[76:79]
	v_mfma_f32_16x16x32_bf16 v[72:75], v[164:167], v[216:219], v[72:75]
	v_mfma_f32_16x16x32_bf16 v[124:127], v[160:163], v[196:199], v[124:127]
	v_mfma_f32_16x16x32_bf16 v[120:123], v[168:171], v[196:199], v[120:123]
	v_mfma_f32_16x16x32_bf16 v[108:111], v[160:163], v[204:207], v[108:111]
	v_mfma_f32_16x16x32_bf16 v[104:107], v[168:171], v[204:207], v[104:107]
	v_mfma_f32_16x16x32_bf16 v[92:95], v[160:163], v[212:215], v[92:95]
	v_mfma_f32_16x16x32_bf16 v[88:91], v[168:171], v[212:215], v[88:91]
	v_mfma_f32_16x16x32_bf16 v[76:79], v[160:163], v[220:223], v[76:79]
	v_mfma_f32_16x16x32_bf16 v[72:75], v[168:171], v[220:223], v[72:75]
	s_setprio 0
	s_setprio 3
	v_mfma_f32_16x16x32_bf16 v[116:119], v[172:175], v[192:195], v[116:119]
	v_mfma_f32_16x16x32_bf16 v[112:115], v[180:183], v[192:195], v[112:115]
	v_mfma_f32_16x16x32_bf16 v[100:103], v[172:175], v[200:203], v[100:103]
	v_mfma_f32_16x16x32_bf16 v[96:99], v[180:183], v[200:203], v[96:99]
	v_mfma_f32_16x16x32_bf16 v[84:87], v[172:175], v[208:211], v[84:87]
	v_mfma_f32_16x16x32_bf16 v[80:83], v[180:183], v[208:211], v[80:83]
	v_mfma_f32_16x16x32_bf16 v[68:71], v[172:175], v[216:219], v[68:71]
	v_mfma_f32_16x16x32_bf16 v[64:67], v[180:183], v[216:219], v[64:67]
	v_mfma_f32_16x16x32_bf16 v[116:119], v[176:179], v[196:199], v[116:119]
	v_mfma_f32_16x16x32_bf16 v[112:115], v[188:191], v[196:199], v[112:115]
	v_mfma_f32_16x16x32_bf16 v[100:103], v[176:179], v[204:207], v[100:103]
	v_mfma_f32_16x16x32_bf16 v[96:99], v[188:191], v[204:207], v[96:99]
	v_mfma_f32_16x16x32_bf16 v[84:87], v[176:179], v[212:215], v[84:87]
	v_mfma_f32_16x16x32_bf16 v[80:83], v[188:191], v[212:215], v[80:83]
	v_mfma_f32_16x16x32_bf16 v[68:71], v[176:179], v[220:223], v[68:71]
	v_mfma_f32_16x16x32_bf16 v[64:67], v[188:191], v[220:223], v[64:67]
	s_setprio 0
	s_barrier
; #define PG8_STAGE(bufoff, gbase, voff) do { _Pragma("unroll") for (int _i = 0; _i < 2; ++_i) \
;         __builtin_amdgcn_global_load_lds((const unsigned*)((const char*)(gbase) + (voff)[_i]), (LAS unsigned*)(lds + (bufoff) + ldsw + _i * 8192), 16, 0, 0); } while (0)
; #define PG8_LDA(dst, b, h) do { _Pragma("unroll") for (int m = 0; m < 4; ++m) _Pragma("unroll") for (int k = 0; k < 2; ++k) dst[m][k] = *(const LAS bf16x8*)(lds + PG8_SA(b, h) + aoff + m * 2048 + k * 1024); } while (0)
; #define PG8_LDB(dst, b, h) do { _Pragma("unroll") for (int n = 0; n < 2; ++n) _Pragma("unroll") for (int k = 0; k < 2; ++k) dst[n][k] = *(const LAS bf16x8*)(lds + PG8_SB(b, h) + boff + n * 2048 + k * 1024); } while (0)
; #define PG8_MMA(ai, bj, At, Bt) do { __builtin_amdgcn_s_setprio(3); _Pragma("unroll") for (int m = 0; m < 4; ++m) _Pragma("unroll") for (int n = 0; n < 2; ++n) _Pragma("unroll") for (int k = 0; k < 2; ++k) \
;         acc[ai][bj][m][n] = __builtin_amdgcn_mfma_f32_16x16x32_bf16(Bt[n][k], At[m][k], acc[ai][bj][m][n], 0, 0, 0); __builtin_amdgcn_s_setprio(0); } while (0)
; #define PG8_WAIT_V(n) asm volatile("s_waitcnt vmcnt(" #n ")" ::: "memory")
; #define PG8_BAR __builtin_amdgcn_s_barrier()
; template <class Epi, class Sched>
; __device__ __forceinline__ void gemm_phase(LAS unsigned char* lds, const Gemm g, const Sched& S, const Epi& E, int tid_in) {
;     ...
;             PG8_LDB(B0, 0, 0); PG8_LDB(B1, 0, 1); PG8_SCHED; PG8_LDA(At, 0, 0); PG8_STAGE(PG8_SA(1, 0), a1, voffA); PG8_STAGE(PG8_SA(1, 1), a1 + hstep, voffA);
;             PG8_WAIT_V(8); PG8_WAIT_L(0); PG8_BAR; PG8_MMA(0, 0, At, B0); PG8_MMA(0, 1, At, B1); PG8_BAR; PG8_SCHED;
;             PG8_LDA(At, 0, 1); PG8_STAGE(PG8_SB(0, 0), b2, voffB); PG8_STAGE(PG8_SB(0, 1), b2 + hstep, voffB);
;             PG8_WAIT_V(6); PG8_WAIT_L(0); PG8_BAR; PG8_MMA(1, 0, At, B0); PG8_MMA(1, 1, At, B1); PG8_BAR; PG8_SCHED;
;             PG8_LDB(B0, 1, 0); PG8_LDB(B1, 1, 1); PG8_SCHED; PG8_LDA(At, 1, 0); PG8_STAGE(PG8_SA(0, 0), a2, voffA); PG8_STAGE(PG8_SA(0, 1), a2 + hstep, voffA);
;             PG8_WAIT_V(8); PG8_WAIT_L(0); PG8_BAR; PG8_MMA(0, 0, At, B0); PG8_MMA(0, 1, At, B1); PG8_BAR; PG8_SCHED;
;             PG8_LDA(At, 1, 1); PG8_STAGE(PG8_SB(1, 0), b3, voffB); PG8_STAGE(PG8_SB(1, 1), b3 + hstep, voffB);
;             PG8_WAIT_V(6); PG8_WAIT_L(0); PG8_BAR; PG8_MMA(1, 0, At, B0); PG8_MMA(1, 1, At, B1); PG8_BAR; PG8_SCHED;
	s_add_i32 s34, s49, s2
	v_lshl_add_u64 v[184:185], v[184:185], 0, s[18:19]
	s_mov_b32 m0, s34
	ds_read_b128 v[192:195], v153 offset:49152
	ds_read_b128 v[196:199], v153 offset:50176
	ds_read_b128 v[200:203], v153 offset:51200
	ds_read_b128 v[204:207], v153 offset:52224
	ds_read_b128 v[208:211], v153 offset:53248
	ds_read_b128 v[212:215], v153 offset:54272
	ds_read_b128 v[216:219], v153 offset:55296
	ds_read_b128 v[220:223], v153 offset:56320
	global_load_lds_dwordx4 v[184:185], off
	s_add_i32 m0, s34, 0x2000
	s_add_u32 s30, s30, 0x160080
	v_lshl_add_u64 v[184:185], v[224:225], 0, s[18:19]
	s_addc_u32 s31, s31, 0
	s_add_i32 s34, s51, s2
	global_load_lds_dwordx4 v[184:185], off
	v_lshl_add_u64 v[184:185], s[30:31], 0, v[130:131]
	s_mov_b32 m0, s34
	s_nop 0
	global_load_lds_dwordx4 v[184:185], off
	v_lshl_add_u64 v[184:185], s[30:31], 0, v[134:135]
	s_add_i32 m0, s34, 0x2000
	s_nop 0
	global_load_lds_dwordx4 v[184:185], off
	s_waitcnt vmcnt(6)
	s_waitcnt lgkmcnt(0)
	s_barrier
	s_setprio 3
	v_mfma_f32_16x16x32_bf16 v[60:63], v[156:159], v[192:195], v[60:63]
	v_mfma_f32_16x16x32_bf16 v[56:59], v[164:167], v[192:195], v[56:59]
	v_mfma_f32_16x16x32_bf16 v[44:47], v[156:159], v[200:203], v[44:47]
	v_mfma_f32_16x16x32_bf16 v[40:43], v[164:167], v[200:203], v[40:43]
	v_mfma_f32_16x16x32_bf16 v[28:31], v[156:159], v[208:211], v[28:31]
	v_mfma_f32_16x16x32_bf16 v[24:27], v[164:167], v[208:211], v[24:27]
	v_mfma_f32_16x16x32_bf16 v[12:15], v[156:159], v[216:219], v[12:15]
	v_mfma_f32_16x16x32_bf16 v[8:11], v[164:167], v[216:219], v[8:11]
	v_mfma_f32_16x16x32_bf16 v[60:63], v[160:163], v[196:199], v[60:63]
	v_mfma_f32_16x16x32_bf16 v[56:59], v[168:171], v[196:199], v[56:59]
	v_mfma_f32_16x16x32_bf16 v[44:47], v[160:163], v[204:207], v[44:47]
	v_mfma_f32_16x16x32_bf16 v[40:43], v[168:171], v[204:207], v[40:43]
	v_mfma_f32_16x16x32_bf16 v[28:31], v[160:163], v[212:215], v[28:31]
	v_mfma_f32_16x16x32_bf16 v[24:27], v[168:171], v[212:215], v[24:27]
	v_mfma_f32_16x16x32_bf16 v[12:15], v[160:163], v[220:223], v[12:15]
	v_mfma_f32_16x16x32_bf16 v[8:11], v[168:171], v[220:223], v[8:11]
	s_setprio 0
	s_setprio 3
	v_mfma_f32_16x16x32_bf16 v[52:55], v[172:175], v[192:195], v[52:55]
	v_mfma_f32_16x16x32_bf16 v[48:51], v[180:183], v[192:195], v[48:51]
	v_mfma_f32_16x16x32_bf16 v[36:39], v[172:175], v[200:203], v[36:39]
	v_mfma_f32_16x16x32_bf16 v[32:35], v[180:183], v[200:203], v[32:35]
	v_mfma_f32_16x16x32_bf16 v[20:23], v[172:175], v[208:211], v[20:23]
	v_mfma_f32_16x16x32_bf16 v[16:19], v[180:183], v[208:211], v[16:19]
	v_mfma_f32_16x16x32_bf16 v[4:7], v[172:175], v[216:219], v[4:7]
	v_mfma_f32_16x16x32_bf16 v[0:3], v[180:183], v[216:219], v[0:3]
	v_mfma_f32_16x16x32_bf16 v[52:55], v[176:179], v[196:199], v[52:55]
	v_mfma_f32_16x16x32_bf16 v[48:51], v[188:191], v[196:199], v[48:51]
	v_mfma_f32_16x16x32_bf16 v[36:39], v[176:179], v[204:207], v[36:39]
	v_mfma_f32_16x16x32_bf16 v[32:35], v[188:191], v[204:207], v[32:35]
	v_mfma_f32_16x16x32_bf16 v[20:23], v[176:179], v[212:215], v[20:23]
	v_mfma_f32_16x16x32_bf16 v[16:19], v[188:191], v[212:215], v[16:19]
	v_mfma_f32_16x16x32_bf16 v[4:7], v[176:179], v[220:223], v[4:7]
	v_mfma_f32_16x16x32_bf16 v[0:3], v[188:191], v[220:223], v[0:3]
	s_setprio 0
	s_barrier
	s_add_i32 s48, s48, 2
	s_add_u32 s28, s28, 0x100
	s_addc_u32 s29, s29, 0
	s_cmpk_gt_u32 s48, 0x55
	s_cbranch_scc0 .LBB0_842
	s_branch .Lpeel_exit_3
.LBB0_842:
	ds_read_b128 v[156:159], v151
	ds_read_b128 v[160:163], v151 offset:1024
	ds_read_b128 v[164:167], v151 offset:2048
	ds_read_b128 v[168:171], v151 offset:3072
	ds_read_b128 v[172:175], v152
	ds_read_b128 v[176:179], v152 offset:1024
	ds_read_b128 v[180:183], v152 offset:2048
	ds_read_b128 v[188:191], v152 offset:3072
	s_add_u32 s30, s26, s28
	s_addc_u32 s31, s27, s29
	s_add_u32 s34, s30, 0x100
	s_addc_u32 s35, s31, 0
	s_add_u32 s30, s46, s28
	s_addc_u32 s31, s47, s29
	s_cmpk_eq_i32 s28, 0x2b00
	s_cselect_b32 s31, s25, s31
	s_cselect_b32 s30, s24, s30
	s_cselect_b32 s35, s7, s35
	s_cselect_b32 s34, s6, s34
	v_lshl_add_u64 v[184:185], v[144:145], 0, s[28:29]
	v_lshl_add_u64 v[224:225], v[184:185], 0, s[18:19]
	s_add_i32 m0, s3, 0x8000
	ds_read_b128 v[192:195], v153
	ds_read_b128 v[196:199], v153 offset:1024
	ds_read_b128 v[200:203], v153 offset:2048
	ds_read_b128 v[204:207], v153 offset:3072
	ds_read_b128 v[208:211], v153 offset:4096
	ds_read_b128 v[212:215], v153 offset:5120
	ds_read_b128 v[216:219], v153 offset:6144
	ds_read_b128 v[220:223], v153 offset:7168
	global_load_lds_dwordx4 v[224:225], off
	v_lshl_add_u64 v[224:225], v[146:147], 0, s[28:29]
	v_lshl_add_u64 v[226:227], v[224:225], 0, s[18:19]
	s_add_i32 m0, s3, 0xa000
	v_lshl_add_u64 v[184:185], v[184:185], 0, s[20:21]
	global_load_lds_dwordx4 v[226:227], off
	s_add_i32 m0, s3, 0xc000
	s_nop 0
	global_load_lds_dwordx4 v[184:185], off
	v_lshl_add_u64 v[184:185], v[224:225], 0, s[20:21]
	s_add_i32 m0, s3, 0xe000
	s_nop 0
	global_load_lds_dwordx4 v[184:185], off
	s_waitcnt vmcnt(8)
	s_waitcnt lgkmcnt(0)
	s_barrier
; #define PG8_STAGE(bufoff, gbase, voff) do { _Pragma("unroll") for (int _i = 0; _i < 2; ++_i) \
;         __builtin_amdgcn_global_load_lds((const unsigned*)((const char*)(gbase) + (voff)[_i]), (LAS unsigned*)(lds + (bufoff) + ldsw + _i * 8192), 16, 0, 0); } while (0)
; #define PG8_LDA(dst, b, h) do { _Pragma("unroll") for (int m = 0; m < 4; ++m) _Pragma("unroll") for (int k = 0; k < 2; ++k) dst[m][k] = *(const LAS bf16x8*)(lds + PG8_SA(b, h) + aoff + m * 2048 + k * 1024); } while (0)
; #define PG8_MMA(ai, bj, At, Bt) do { __builtin_amdgcn_s_setprio(3); _Pragma("unroll") for (int m = 0; m < 4; ++m) _Pragma("unroll") for (int n = 0; n < 2; ++n) _Pragma("unroll") for (int k = 0; k < 2; ++k) \
;         acc[ai][bj][m][n] = __builtin_amdgcn_mfma_f32_16x16x32_bf16(Bt[n][k], At[m][k], acc[ai][bj][m][n], 0, 0, 0); __builtin_amdgcn_s_setprio(0); } while (0)
; #define PG8_WAIT_V(n) asm volatile("s_waitcnt vmcnt(" #n ")" ::: "memory")
; #define PG8_WAIT_L(n) asm volatile("s_waitcnt lgkmcnt(" #n ")" ::: "memory")
; #define PG8_BAR __builtin_amdgcn_s_barrier()
; #define PG8_SCHED __builtin_amdgcn_sched_barrier(0)
; template <class Epi, class Sched>
; __device__ __forceinline__ void gemm_phase(LAS unsigned char* lds, const Gemm g, const Sched& S, const Epi& E, int tid_in) {
;     ...
;             PG8_WAIT_V(8); PG8_WAIT_L(0); PG8_BAR; PG8_MMA(0, 0, At, B0); PG8_MMA(0, 1, At, B1); PG8_BAR; PG8_SCHED;
;             PG8_LDA(At, 0, 1); PG8_STAGE(PG8_SB(0, 0), b2, voffB); PG8_STAGE(PG8_SB(0, 1), b2 + hstep, voffB);
;             PG8_WAIT_V(6); PG8_WAIT_L(0); PG8_BAR; PG8_MMA(1, 0, At, B0); PG8_MMA(1, 1, At, B1); PG8_BAR; PG8_SCHED;
	s_setprio 3
	v_mfma_f32_16x16x32_bf16 v[124:127], v[156:159], v[192:195], v[124:127]
	v_mfma_f32_16x16x32_bf16 v[120:123], v[164:167], v[192:195], v[120:123]
	v_mfma_f32_16x16x32_bf16 v[108:111], v[156:159], v[200:203], v[108:111]
	v_mfma_f32_16x16x32_bf16 v[104:107], v[164:167], v[200:203], v[104:107]
	v_mfma_f32_16x16x32_bf16 v[92:95], v[156:159], v[208:211], v[92:95]
	v_mfma_f32_16x16x32_bf16 v[88:91], v[164:167], v[208:211], v[88:91]
	v_mfma_f32_16x16x32_bf16 v[76:79], v[156:159], v[216:219], v[76:79]
	v_mfma_f32_16x16x32_bf16 v[72:75], v[164:167], v[216:219], v[72:75]
	v_mfma_f32_16x16x32_bf16 v[124:127], v[160:163], v[196:199], v[124:127]
	v_mfma_f32_16x16x32_bf16 v[120:123], v[168:171], v[196:199], v[120:123]
	v_mfma_f32_16x16x32_bf16 v[108:111], v[160:163], v[204:207], v[108:111]
	v_mfma_f32_16x16x32_bf16 v[104:107], v[168:171], v[204:207], v[104:107]
	v_mfma_f32_16x16x32_bf16 v[92:95], v[160:163], v[212:215], v[92:95]
	v_mfma_f32_16x16x32_bf16 v[88:91], v[168:171], v[212:215], v[88:91]
	v_mfma_f32_16x16x32_bf16 v[76:79], v[160:163], v[220:223], v[76:79]
	v_mfma_f32_16x16x32_bf16 v[72:75], v[168:171], v[220:223], v[72:75]
	s_setprio 0
	s_setprio 3
	v_mfma_f32_16x16x32_bf16 v[116:119], v[172:175], v[192:195], v[116:119]
	v_mfma_f32_16x16x32_bf16 v[112:115], v[180:183], v[192:195], v[112:115]
	v_mfma_f32_16x16x32_bf16 v[100:103], v[172:175], v[200:203], v[100:103]
	v_mfma_f32_16x16x32_bf16 v[96:99], v[180:183], v[200:203], v[96:99]
	v_mfma_f32_16x16x32_bf16 v[84:87], v[172:175], v[208:211], v[84:87]
	v_mfma_f32_16x16x32_bf16 v[80:83], v[180:183], v[208:211], v[80:83]
	v_mfma_f32_16x16x32_bf16 v[68:71], v[172:175], v[216:219], v[68:71]
	v_mfma_f32_16x16x32_bf16 v[64:67], v[180:183], v[216:219], v[64:67]
	v_mfma_f32_16x16x32_bf16 v[116:119], v[176:179], v[196:199], v[116:119]
	v_mfma_f32_16x16x32_bf16 v[112:115], v[188:191], v[196:199], v[112:115]
	v_mfma_f32_16x16x32_bf16 v[100:103], v[176:179], v[204:207], v[100:103]
	v_mfma_f32_16x16x32_bf16 v[96:99], v[188:191], v[204:207], v[96:99]
	v_mfma_f32_16x16x32_bf16 v[84:87], v[176:179], v[212:215], v[84:87]
	v_mfma_f32_16x16x32_bf16 v[80:83], v[188:191], v[212:215], v[80:83]
	v_mfma_f32_16x16x32_bf16 v[68:71], v[176:179], v[220:223], v[68:71]
	v_mfma_f32_16x16x32_bf16 v[64:67], v[188:191], v[220:223], v[64:67]
	s_setprio 0
	s_barrier
	s_add_i32 s49, s40, s2
	v_lshl_add_u64 v[184:185], s[30:31], 0, v[130:131]
	s_mov_b32 m0, s49
	ds_read_b128 v[192:195], v153 offset:16384
	ds_read_b128 v[196:199], v153 offset:17408
	ds_read_b128 v[200:203], v153 offset:18432
	ds_read_b128 v[204:207], v153 offset:19456
	ds_read_b128 v[208:211], v153 offset:20480
	ds_read_b128 v[212:215], v153 offset:21504
	ds_read_b128 v[216:219], v153 offset:22528
	ds_read_b128 v[220:223], v153 offset:23552
	global_load_lds_dwordx4 v[184:185], off
	s_add_i32 m0, s49, 0x2000
	s_add_u32 s68, s30, 0x160000
	v_lshl_add_u64 v[224:225], s[30:31], 0, v[134:135]
	s_addc_u32 s69, s31, 0
	s_add_i32 s49, s41, s2
	global_load_lds_dwordx4 v[224:225], off
	v_lshl_add_u64 v[226:227], s[68:69], 0, v[130:131]
	s_mov_b32 m0, s49
	s_nop 0
	global_load_lds_dwordx4 v[226:227], off
	v_lshl_add_u64 v[226:227], s[68:69], 0, v[134:135]
	s_add_i32 m0, s49, 0x2000
	s_nop 0
	global_load_lds_dwordx4 v[226:227], off
	s_waitcnt vmcnt(6)
	s_waitcnt lgkmcnt(0)
	s_barrier
	s_setprio 3
	v_mfma_f32_16x16x32_bf16 v[60:63], v[156:159], v[192:195], v[60:63]
	v_mfma_f32_16x16x32_bf16 v[56:59], v[164:167], v[192:195], v[56:59]
	v_mfma_f32_16x16x32_bf16 v[44:47], v[156:159], v[200:203], v[44:47]
	v_mfma_f32_16x16x32_bf16 v[40:43], v[164:167], v[200:203], v[40:43]
	v_mfma_f32_16x16x32_bf16 v[28:31], v[156:159], v[208:211], v[28:31]
	v_mfma_f32_16x16x32_bf16 v[24:27], v[164:167], v[208:211], v[24:27]
	v_mfma_f32_16x16x32_bf16 v[12:15], v[156:159], v[216:219], v[12:15]
	v_mfma_f32_16x16x32_bf16 v[8:11], v[164:167], v[216:219], v[8:11]
	v_mfma_f32_16x16x32_bf16 v[60:63], v[160:163], v[196:199], v[60:63]
	v_mfma_f32_16x16x32_bf16 v[56:59], v[168:171], v[196:199], v[56:59]
	v_mfma_f32_16x16x32_bf16 v[44:47], v[160:163], v[204:207], v[44:47]
	v_mfma_f32_16x16x32_bf16 v[40:43], v[168:171], v[204:207], v[40:43]
	v_mfma_f32_16x16x32_bf16 v[28:31], v[160:163], v[212:215], v[28:31]
	v_mfma_f32_16x16x32_bf16 v[24:27], v[168:171], v[212:215], v[24:27]
	v_mfma_f32_16x16x32_bf16 v[12:15], v[160:163], v[220:223], v[12:15]
	v_mfma_f32_16x16x32_bf16 v[8:11], v[168:171], v[220:223], v[8:11]
	s_setprio 0
	s_setprio 3
	v_mfma_f32_16x16x32_bf16 v[52:55], v[172:175], v[192:195], v[52:55]
	v_mfma_f32_16x16x32_bf16 v[48:51], v[180:183], v[192:195], v[48:51]
	v_mfma_f32_16x16x32_bf16 v[36:39], v[172:175], v[200:203], v[36:39]
	v_mfma_f32_16x16x32_bf16 v[32:35], v[180:183], v[200:203], v[32:35]
	v_mfma_f32_16x16x32_bf16 v[20:23], v[172:175], v[208:211], v[20:23]
	v_mfma_f32_16x16x32_bf16 v[16:19], v[180:183], v[208:211], v[16:19]
	v_mfma_f32_16x16x32_bf16 v[4:7], v[172:175], v[216:219], v[4:7]
	v_mfma_f32_16x16x32_bf16 v[0:3], v[180:183], v[216:219], v[0:3]
	v_mfma_f32_16x16x32_bf16 v[52:55], v[176:179], v[196:199], v[52:55]
	v_mfma_f32_16x16x32_bf16 v[48:51], v[188:191], v[196:199], v[48:51]
	v_mfma_f32_16x16x32_bf16 v[36:39], v[176:179], v[204:207], v[36:39]
	v_mfma_f32_16x16x32_bf16 v[32:35], v[188:191], v[204:207], v[32:35]
	v_mfma_f32_16x16x32_bf16 v[20:23], v[176:179], v[212:215], v[20:23]
	v_mfma_f32_16x16x32_bf16 v[16:19], v[188:191], v[212:215], v[16:19]
	v_mfma_f32_16x16x32_bf16 v[4:7], v[176:179], v[220:223], v[4:7]
	v_mfma_f32_16x16x32_bf16 v[0:3], v[188:191], v[220:223], v[0:3]
	s_setprio 0
	s_barrier
; #define PG8_STAGE(bufoff, gbase, voff) do { _Pragma("unroll") for (int _i = 0; _i < 2; ++_i) \
;         __builtin_amdgcn_global_load_lds((const unsigned*)((const char*)(gbase) + (voff)[_i]), (LAS unsigned*)(lds + (bufoff) + ldsw + _i * 8192), 16, 0, 0); } while (0)
; #define PG8_LDA(dst, b, h) do { _Pragma("unroll") for (int m = 0; m < 4; ++m) _Pragma("unroll") for (int k = 0; k < 2; ++k) dst[m][k] = *(const LAS bf16x8*)(lds + PG8_SA(b, h) + aoff + m * 2048 + k * 1024); } while (0)
; #define PG8_LDB(dst, b, h) do { _Pragma("unroll") for (int n = 0; n < 2; ++n) _Pragma("unroll") for (int k = 0; k < 2; ++k) dst[n][k] = *(const LAS bf16x8*)(lds + PG8_SB(b, h) + boff + n * 2048 + k * 1024); } while (0)
; #define PG8_MMA(ai, bj, At, Bt) do { __builtin_amdgcn_s_setprio(3); _Pragma("unroll") for (int m = 0; m < 4; ++m) _Pragma("unroll") for (int n = 0; n < 2; ++n) _Pragma("unroll") for (int k = 0; k < 2; ++k) \
;         acc[ai][bj][m][n] = __builtin_amdgcn_mfma_f32_16x16x32_bf16(Bt[n][k], At[m][k], acc[ai][bj][m][n], 0, 0, 0); __builtin_amdgcn_s_setprio(0); } while (0)
; #define PG8_WAIT_V(n) asm volatile("s_waitcnt vmcnt(" #n ")" ::: "memory")
; #define PG8_WAIT_L(n) asm volatile("s_waitcnt lgkmcnt(" #n ")" ::: "memory")
; #define PG8_BAR __builtin_amdgcn_s_barrier()
; #define PG8_SCHED __builtin_amdgcn_sched_barrier(0)
; template <class Epi, class Sched>
; __device__ __forceinline__ void gemm_phase(LAS unsigned char* lds, const Gemm g, const Sched& S, const Epi& E, int tid_in) {
;     ...
;             PG8_LDB(B0, 1, 0); PG8_LDB(B1, 1, 1); PG8_SCHED; PG8_LDA(At, 1, 0); PG8_STAGE(PG8_SA(0, 0), a2, voffA); PG8_STAGE(PG8_SA(0, 1), a2 + hstep, voffA);
;             PG8_WAIT_V(8); PG8_WAIT_L(0); PG8_BAR; PG8_MMA(0, 0, At, B0); PG8_MMA(0, 1, At, B1); PG8_BAR; PG8_SCHED;
	s_add_i32 s49, 0, 0x18000
	v_add_u32_e32 v155, s49, v149
	s_add_i32 s51, 0, 0x1c000
	ds_read_b128 v[156:159], v155
	ds_read_b128 v[160:163], v155 offset:1024
	ds_read_b128 v[164:167], v155 offset:2048
	ds_read_b128 v[168:171], v155 offset:3072
	v_add_u32_e32 v155, s51, v149
	ds_read_b128 v[172:175], v155
	ds_read_b128 v[176:179], v155 offset:1024
	ds_read_b128 v[180:183], v155 offset:2048
	ds_read_b128 v[188:191], v155 offset:3072
	s_mov_b32 m0, s3
	v_lshl_add_u64 v[226:227], s[34:35], 0, v[128:129]
	ds_read_b128 v[192:195], v153 offset:32768
	ds_read_b128 v[196:199], v153 offset:33792
	ds_read_b128 v[200:203], v153 offset:34816
	ds_read_b128 v[204:207], v153 offset:35840
	ds_read_b128 v[208:211], v153 offset:36864
	ds_read_b128 v[212:215], v153 offset:37888
	ds_read_b128 v[216:219], v153 offset:38912
	ds_read_b128 v[220:223], v153 offset:39936
	global_load_lds_dwordx4 v[226:227], off
	v_lshl_add_u64 v[226:227], s[34:35], 0, v[132:133]
	s_add_u32 s34, s34, 0x160000
	s_mov_b32 m0, s36
	s_addc_u32 s35, s35, 0
	global_load_lds_dwordx4 v[226:227], off
	v_lshl_add_u64 v[226:227], s[34:35], 0, v[128:129]
	s_mov_b32 m0, s37
	s_nop 0
	global_load_lds_dwordx4 v[226:227], off
	v_lshl_add_u64 v[226:227], s[34:35], 0, v[132:133]
	s_mov_b32 m0, s38
	s_nop 0
	global_load_lds_dwordx4 v[226:227], off
	s_waitcnt vmcnt(8)
	s_waitcnt lgkmcnt(0)
	s_barrier
	s_setprio 3
	v_mfma_f32_16x16x32_bf16 v[124:127], v[156:159], v[192:195], v[124:127]
	v_mfma_f32_16x16x32_bf16 v[120:123], v[164:167], v[192:195], v[120:123]
	v_mfma_f32_16x16x32_bf16 v[108:111], v[156:159], v[200:203], v[108:111]
	v_mfma_f32_16x16x32_bf16 v[104:107], v[164:167], v[200:203], v[104:107]
	v_mfma_f32_16x16x32_bf16 v[92:95], v[156:159], v[208:211], v[92:95]
	v_mfma_f32_16x16x32_bf16 v[88:91], v[164:167], v[208:211], v[88:91]
	v_mfma_f32_16x16x32_bf16 v[76:79], v[156:159], v[216:219], v[76:79]
	v_mfma_f32_16x16x32_bf16 v[72:75], v[164:167], v[216:219], v[72:75]
	v_mfma_f32_16x16x32_bf16 v[124:127], v[160:163], v[196:199], v[124:127]
	v_mfma_f32_16x16x32_bf16 v[120:123], v[168:171], v[196:199], v[120:123]
	v_mfma_f32_16x16x32_bf16 v[108:111], v[160:163], v[204:207], v[108:111]
	v_mfma_f32_16x16x32_bf16 v[104:107], v[168:171], v[204:207], v[104:107]
	v_mfma_f32_16x16x32_bf16 v[92:95], v[160:163], v[212:215], v[92:95]
	v_mfma_f32_16x16x32_bf16 v[88:91], v[168:171], v[212:215], v[88:91]
	v_mfma_f32_16x16x32_bf16 v[76:79], v[160:163], v[220:223], v[76:79]
	v_mfma_f32_16x16x32_bf16 v[72:75], v[168:171], v[220:223], v[72:75]
	s_setprio 0
	s_setprio 3
	v_mfma_f32_16x16x32_bf16 v[116:119], v[172:175], v[192:195], v[116:119]
	v_mfma_f32_16x16x32_bf16 v[112:115], v[180:183], v[192:195], v[112:115]
	v_mfma_f32_16x16x32_bf16 v[100:103], v[172:175], v[200:203], v[100:103]
	v_mfma_f32_16x16x32_bf16 v[96:99], v[180:183], v[200:203], v[96:99]
	v_mfma_f32_16x16x32_bf16 v[84:87], v[172:175], v[208:211], v[84:87]
	v_mfma_f32_16x16x32_bf16 v[80:83], v[180:183], v[208:211], v[80:83]
	v_mfma_f32_16x16x32_bf16 v[68:71], v[172:175], v[216:219], v[68:71]
	v_mfma_f32_16x16x32_bf16 v[64:67], v[180:183], v[216:219], v[64:67]
	v_mfma_f32_16x16x32_bf16 v[116:119], v[176:179], v[196:199], v[116:119]
	v_mfma_f32_16x16x32_bf16 v[112:115], v[188:191], v[196:199], v[112:115]
	v_mfma_f32_16x16x32_bf16 v[100:103], v[176:179], v[204:207], v[100:103]
	v_mfma_f32_16x16x32_bf16 v[96:99], v[188:191], v[204:207], v[96:99]
	v_mfma_f32_16x16x32_bf16 v[84:87], v[176:179], v[212:215], v[84:87]
	v_mfma_f32_16x16x32_bf16 v[80:83], v[188:191], v[212:215], v[80:83]
	v_mfma_f32_16x16x32_bf16 v[68:71], v[176:179], v[220:223], v[68:71]
	v_mfma_f32_16x16x32_bf16 v[64:67], v[188:191], v[220:223], v[64:67]
	s_setprio 0
	s_barrier
; #define PG8_STAGE(bufoff, gbase, voff) do { _Pragma("unroll") for (int _i = 0; _i < 2; ++_i) \
;         __builtin_amdgcn_global_load_lds((const unsigned*)((const char*)(gbase) + (voff)[_i]), (LAS unsigned*)(lds + (bufoff) + ldsw + _i * 8192), 16, 0, 0); } while (0)
; #define PG8_LDA(dst, b, h) do { _Pragma("unroll") for (int m = 0; m < 4; ++m) _Pragma("unroll") for (int k = 0; k < 2; ++k) dst[m][k] = *(const LAS bf16x8*)(lds + PG8_SA(b, h) + aoff + m * 2048 + k * 1024); } while (0)
; #define PG8_MMA(ai, bj, At, Bt) do { __builtin_amdgcn_s_setprio(3); _Pragma("unroll") for (int m = 0; m < 4; ++m) _Pragma("unroll") for (int n = 0; n < 2; ++n) _Pragma("unroll") for (int k = 0; k < 2; ++k) \
;         acc[ai][bj][m][n] = __builtin_amdgcn_mfma_f32_16x16x32_bf16(Bt[n][k], At[m][k], acc[ai][bj][m][n], 0, 0, 0); __builtin_amdgcn_s_setprio(0); } while (0)
; #define PG8_WAIT_V(n) asm volatile("s_waitcnt vmcnt(" #n ")" ::: "memory")
; #define PG8_WAIT_L(n) asm volatile("s_waitcnt lgkmcnt(" #n ")" ::: "memory")
; #define PG8_BAR __builtin_amdgcn_s_barrier()
; #define PG8_SCHED __builtin_amdgcn_sched_barrier(0)
; template <class Epi, class Sched>
; __device__ __forceinline__ void gemm_phase(LAS unsigned char* lds, const Gemm g, const Sched& S, const Epi& E, int tid_in) {
;     ...
;             PG8_LDA(At, 1, 1); PG8_STAGE(PG8_SB(1, 0), b3, voffB); PG8_STAGE(PG8_SB(1, 1), b3 + hstep, voffB);
;             PG8_WAIT_V(6); PG8_WAIT_L(0); PG8_BAR; PG8_MMA(1, 0, At, B0); PG8_MMA(1, 1, At, B1); PG8_BAR; PG8_SCHED;
	s_add_i32 s34, s49, s2
	v_lshl_add_u64 v[184:185], v[184:185], 0, s[18:19]
	s_mov_b32 m0, s34
	ds_read_b128 v[192:195], v153 offset:49152
	ds_read_b128 v[196:199], v153 offset:50176
	ds_read_b128 v[200:203], v153 offset:51200
	ds_read_b128 v[204:207], v153 offset:52224
	ds_read_b128 v[208:211], v153 offset:53248
	ds_read_b128 v[212:215], v153 offset:54272
	ds_read_b128 v[216:219], v153 offset:55296
	ds_read_b128 v[220:223], v153 offset:56320
	global_load_lds_dwordx4 v[184:185], off
	s_add_i32 m0, s34, 0x2000
	s_add_u32 s30, s30, 0x160080
	v_lshl_add_u64 v[184:185], v[224:225], 0, s[18:19]
	s_addc_u32 s31, s31, 0
	s_add_i32 s34, s51, s2
	global_load_lds_dwordx4 v[184:185], off
	v_lshl_add_u64 v[184:185], s[30:31], 0, v[130:131]
	s_mov_b32 m0, s34
	s_nop 0
	global_load_lds_dwordx4 v[184:185], off
	v_lshl_add_u64 v[184:185], s[30:31], 0, v[134:135]
	s_add_i32 m0, s34, 0x2000
	s_nop 0
	global_load_lds_dwordx4 v[184:185], off
	s_waitcnt vmcnt(6)
	s_waitcnt lgkmcnt(0)
	s_barrier
	s_setprio 3
	v_mfma_f32_16x16x32_bf16 v[60:63], v[156:159], v[192:195], v[60:63]
	v_mfma_f32_16x16x32_bf16 v[56:59], v[164:167], v[192:195], v[56:59]
	v_mfma_f32_16x16x32_bf16 v[44:47], v[156:159], v[200:203], v[44:47]
	v_mfma_f32_16x16x32_bf16 v[40:43], v[164:167], v[200:203], v[40:43]
	v_mfma_f32_16x16x32_bf16 v[28:31], v[156:159], v[208:211], v[28:31]
	v_mfma_f32_16x16x32_bf16 v[24:27], v[164:167], v[208:211], v[24:27]
	v_mfma_f32_16x16x32_bf16 v[12:15], v[156:159], v[216:219], v[12:15]
	v_mfma_f32_16x16x32_bf16 v[8:11], v[164:167], v[216:219], v[8:11]
	v_mfma_f32_16x16x32_bf16 v[60:63], v[160:163], v[196:199], v[60:63]
	v_mfma_f32_16x16x32_bf16 v[56:59], v[168:171], v[196:199], v[56:59]
	v_mfma_f32_16x16x32_bf16 v[44:47], v[160:163], v[204:207], v[44:47]
	v_mfma_f32_16x16x32_bf16 v[40:43], v[168:171], v[204:207], v[40:43]
	v_mfma_f32_16x16x32_bf16 v[28:31], v[160:163], v[212:215], v[28:31]
	v_mfma_f32_16x16x32_bf16 v[24:27], v[168:171], v[212:215], v[24:27]
	v_mfma_f32_16x16x32_bf16 v[12:15], v[160:163], v[220:223], v[12:15]
	v_mfma_f32_16x16x32_bf16 v[8:11], v[168:171], v[220:223], v[8:11]
	s_setprio 0
	s_setprio 3
	v_mfma_f32_16x16x32_bf16 v[52:55], v[172:175], v[192:195], v[52:55]
	v_mfma_f32_16x16x32_bf16 v[48:51], v[180:183], v[192:195], v[48:51]
	v_mfma_f32_16x16x32_bf16 v[36:39], v[172:175], v[200:203], v[36:39]
	v_mfma_f32_16x16x32_bf16 v[32:35], v[180:183], v[200:203], v[32:35]
	v_mfma_f32_16x16x32_bf16 v[20:23], v[172:175], v[208:211], v[20:23]
	v_mfma_f32_16x16x32_bf16 v[16:19], v[180:183], v[208:211], v[16:19]
	v_mfma_f32_16x16x32_bf16 v[4:7], v[172:175], v[216:219], v[4:7]
	v_mfma_f32_16x16x32_bf16 v[0:3], v[180:183], v[216:219], v[0:3]
	v_mfma_f32_16x16x32_bf16 v[52:55], v[176:179], v[196:199], v[52:55]
	v_mfma_f32_16x16x32_bf16 v[48:51], v[188:191], v[196:199], v[48:51]
	v_mfma_f32_16x16x32_bf16 v[36:39], v[176:179], v[204:207], v[36:39]
	v_mfma_f32_16x16x32_bf16 v[32:35], v[188:191], v[204:207], v[32:35]
	v_mfma_f32_16x16x32_bf16 v[20:23], v[176:179], v[212:215], v[20:23]
	v_mfma_f32_16x16x32_bf16 v[16:19], v[188:191], v[212:215], v[16:19]
	v_mfma_f32_16x16x32_bf16 v[4:7], v[176:179], v[220:223], v[4:7]
	v_mfma_f32_16x16x32_bf16 v[0:3], v[188:191], v[220:223], v[0:3]
	s_setprio 0
	s_barrier
	s_add_i32 s48, s48, 2
	s_add_u32 s28, s28, 0x100
	s_addc_u32 s29, s29, 0
	s_cmpk_gt_u32 s48, 0x55
	s_cbranch_scc0 .LBB0_842

; #define PG8_STAGE(bufoff, gbase, voff) do { _Pragma("unroll") for (int _i = 0; _i < 2; ++_i) \
;         __builtin_amdgcn_global_load_lds((const unsigned*)((const char*)(gbase) + (voff)[_i]), (LAS unsigned*)(lds + (bufoff) + ldsw + _i * 8192), 16, 0, 0); } while (0)
; #define PG8_LDA(dst, b, h) do { _Pragma("unroll") for (int m = 0; m < 4; ++m) _Pragma("unroll") for (int k = 0; k < 2; ++k) dst[m][k] = *(const LAS bf16x8*)(lds + PG8_SA(b, h) + aoff + m * 2048 + k * 1024); } while (0)
; #define PG8_LDB(dst, b, h) do { _Pragma("unroll") for (int n = 0; n < 2; ++n) _Pragma("unroll") for (int k = 0; k < 2; ++k) dst[n][k] = *(const LAS bf16x8*)(lds + PG8_SB(b, h) + boff + n * 2048 + k * 1024); } while (0)
; #define PG8_MMA(ai, bj, At, Bt) do { __builtin_amdgcn_s_setprio(3); _Pragma("unroll") for (int m = 0; m < 4; ++m) _Pragma("unroll") for (int n = 0; n < 2; ++n) _Pragma("unroll") for (int k = 0; k < 2; ++k) \
;         acc[ai][bj][m][n] = __builtin_amdgcn_mfma_f32_16x16x32_bf16(Bt[n][k], At[m][k], acc[ai][bj][m][n], 0, 0, 0); __builtin_amdgcn_s_setprio(0); } while (0)
; #define PG8_WAIT_V(n) asm volatile("s_waitcnt vmcnt(" #n ")" ::: "memory")
; template <class Epi, class Sched>
; __device__ __forceinline__ void gemm_phase(LAS unsigned char* lds, const Gemm g, const Sched& S, const Epi& E, int tid_in) {
;     ...
;         const char* nA = has_next ? (const char*)g.A + (size_t)nxt.pm * tstep + nxt.koff : cA; const char* nB = has_next ? (const char*)g.Bt + (size_t)nxt.pn * tstep + nxt.koff : cB;
;         for (int t = 0; t < nt; t += 2) {
;             const bool last = (t == nt - 2);
;             const char* a1 = cA + (size_t)(t + 1) * kstep;
;             const char* a2 = last ? nA : cA + (size_t)(t + 2) * kstep; const char* b2 = last ? nB : cB + (size_t)(t + 2) * kstep;
;             const char* a3 = a2 + kstep; const char* b3 = b2 + kstep;
;             PG8_LDB(B0, 0, 0); PG8_LDB(B1, 0, 1); PG8_SCHED; PG8_LDA(At, 0, 0); PG8_STAGE(PG8_SA(1, 0), a1, voffA); PG8_STAGE(PG8_SA(1, 1), a1 + hstep, voffA);
;             PG8_WAIT_V(8); PG8_WAIT_L(0); PG8_BAR; PG8_MMA(0, 0, At, B0); PG8_MMA(0, 1, At, B1); PG8_BAR; PG8_SCHED;
;             PG8_LDA(At, 0, 1); PG8_STAGE(PG8_SB(0, 0), b2, voffB); PG8_STAGE(PG8_SB(0, 1), b2 + hstep, voffB);
;             PG8_WAIT_V(6); PG8_WAIT_L(0); PG8_BAR; PG8_MMA(1, 0, At, B0); PG8_MMA(1, 1, At, B1); PG8_BAR; PG8_SCHED;
.LBB0_988:
	ds_read_b128 v[4:7], v143
	ds_read_b128 v[8:11], v143 offset:1024
	ds_read_b128 v[12:15], v143 offset:2048
	ds_read_b128 v[16:19], v143 offset:3072
	ds_read_b128 v[20:23], v144
	ds_read_b128 v[24:27], v144 offset:1024
	ds_read_b128 v[28:31], v144 offset:2048
	ds_read_b128 v[32:35], v144 offset:3072
	s_ashr_i32 s35, s34, 31
	s_lshl_b64 s[36:37], s[34:35], 17
	s_add_u32 s36, s3, s36
	s_addc_u32 s37, s51, s37
	s_and_b64 s[38:39], s[4:5], exec
	s_cselect_b32 s49, s37, s43
	s_cselect_b32 s48, s36, s42
	s_ashr_i32 s31, s30, 31
	s_lshl_b64 s[38:39], s[30:31], 17
	s_add_u32 s38, s62, s38
	s_addc_u32 s39, s63, s39
	s_and_b64 s[46:47], s[4:5], exec
	s_cselect_b32 s47, s39, s45
	s_cselect_b32 s46, s38, s44
	v_lshl_add_u64 v[0:1], s[42:43], 0, v[134:135]
	s_mov_b32 m0, s71
	v_lshl_add_u64 v[2:3], v[0:1], 0, s[8:9]
	ds_read_b128 v[36:39], v145
	ds_read_b128 v[40:43], v145 offset:1024
	ds_read_b128 v[44:47], v145 offset:2048
	ds_read_b128 v[48:51], v145 offset:3072
	ds_read_b128 v[52:55], v145 offset:4096
	ds_read_b128 v[56:59], v145 offset:5120
	ds_read_b128 v[60:63], v145 offset:6144
	ds_read_b128 v[64:67], v145 offset:7168
	global_load_lds_dwordx4 v[2:3], off
	v_lshl_add_u64 v[2:3], s[42:43], 0, v[130:131]
	s_add_u32 s80, s42, 0x10080
	v_lshl_add_u64 v[68:69], v[2:3], 0, s[8:9]
	s_mov_b32 m0, s72
	s_addc_u32 s81, s43, 0
	global_load_lds_dwordx4 v[68:69], off
	v_lshl_add_u64 v[68:69], s[80:81], 0, v[134:135]
	s_mov_b32 m0, s73
	s_nop 0
	global_load_lds_dwordx4 v[68:69], off
	v_lshl_add_u64 v[68:69], s[80:81], 0, v[130:131]
	s_mov_b32 m0, s74
	s_nop 0
	global_load_lds_dwordx4 v[68:69], off
	s_waitcnt vmcnt(8)
	s_waitcnt lgkmcnt(0)
	s_barrier
	s_setprio 3
	v_mfma_f32_16x16x32_bf16 v[68:71], v[4:7], v[36:39], 0
	v_mfma_f32_16x16x32_bf16 v[72:75], v[12:15], v[36:39], 0
	v_mfma_f32_16x16x32_bf16 v[76:79], v[4:7], v[44:47], 0
	v_mfma_f32_16x16x32_bf16 v[80:83], v[12:15], v[44:47], 0
	v_mfma_f32_16x16x32_bf16 v[84:87], v[4:7], v[52:55], 0
	v_mfma_f32_16x16x32_bf16 v[88:91], v[12:15], v[52:55], 0
	v_mfma_f32_16x16x32_bf16 v[92:95], v[4:7], v[60:63], 0
	v_mfma_f32_16x16x32_bf16 v[96:99], v[12:15], v[60:63], 0
	v_mfma_f32_16x16x32_bf16 v[68:71], v[8:11], v[40:43], v[68:71]
	v_mfma_f32_16x16x32_bf16 v[72:75], v[16:19], v[40:43], v[72:75]
	v_mfma_f32_16x16x32_bf16 v[76:79], v[8:11], v[48:51], v[76:79]
	v_mfma_f32_16x16x32_bf16 v[80:83], v[16:19], v[48:51], v[80:83]
	v_mfma_f32_16x16x32_bf16 v[84:87], v[8:11], v[56:59], v[84:87]
	v_mfma_f32_16x16x32_bf16 v[88:91], v[16:19], v[56:59], v[88:91]
	v_mfma_f32_16x16x32_bf16 v[92:95], v[8:11], v[64:67], v[92:95]
	v_mfma_f32_16x16x32_bf16 v[96:99], v[16:19], v[64:67], v[96:99]
	s_setprio 0
	s_setprio 3
	v_mfma_f32_16x16x32_bf16 v[100:103], v[20:23], v[36:39], 0
	v_mfma_f32_16x16x32_bf16 v[36:39], v[28:31], v[36:39], 0
	v_mfma_f32_16x16x32_bf16 v[100:103], v[24:27], v[40:43], v[100:103]
	v_mfma_f32_16x16x32_bf16 v[36:39], v[32:35], v[40:43], v[36:39]
	v_mfma_f32_16x16x32_bf16 v[40:43], v[20:23], v[44:47], 0
	v_mfma_f32_16x16x32_bf16 v[44:47], v[28:31], v[44:47], 0
	v_mfma_f32_16x16x32_bf16 v[40:43], v[24:27], v[48:51], v[40:43]
	v_mfma_f32_16x16x32_bf16 v[44:47], v[32:35], v[48:51], v[44:47]
	v_mfma_f32_16x16x32_bf16 v[48:51], v[20:23], v[52:55], 0
	v_mfma_f32_16x16x32_bf16 v[52:55], v[28:31], v[52:55], 0
	v_mfma_f32_16x16x32_bf16 v[48:51], v[24:27], v[56:59], v[48:51]
	v_mfma_f32_16x16x32_bf16 v[52:55], v[32:35], v[56:59], v[52:55]
	v_mfma_f32_16x16x32_bf16 v[56:59], v[20:23], v[60:63], 0
	v_mfma_f32_16x16x32_bf16 v[60:63], v[28:31], v[60:63], 0
	v_mfma_f32_16x16x32_bf16 v[56:59], v[24:27], v[64:67], v[56:59]
	v_mfma_f32_16x16x32_bf16 v[60:63], v[32:35], v[64:67], v[60:63]
	s_setprio 0
	s_barrier
	s_add_i32 s82, s69, s2
	v_lshl_add_u64 v[216:217], s[44:45], 0, v[132:133]
	s_add_i32 s31, s82, 0x2000
	v_lshl_add_u64 v[150:151], v[216:217], 0, s[18:19]
	s_mov_b32 m0, s82
	v_lshl_add_u64 v[218:219], s[44:45], 0, v[128:129]
	s_add_u32 s80, s44, 0x10100
	ds_read_b128 v[64:67], v145 offset:16384
	ds_read_b128 v[104:107], v145 offset:17408
	ds_read_b128 v[108:111], v145 offset:18432
	ds_read_b128 v[112:115], v145 offset:19456
	ds_read_b128 v[116:119], v145 offset:20480
	ds_read_b128 v[120:123], v145 offset:21504
	ds_read_b128 v[124:127], v145 offset:22528
	ds_read_b128 v[146:149], v145 offset:23552
	global_load_lds_dwordx4 v[150:151], off
	v_lshl_add_u64 v[150:151], v[218:219], 0, s[18:19]
	s_mov_b32 m0, s31
	s_addc_u32 s81, s45, 0
	s_add_i32 s35, s70, s2
	global_load_lds_dwordx4 v[150:151], off
	v_lshl_add_u64 v[150:151], s[80:81], 0, v[132:133]
	s_mov_b32 m0, s35
	s_nop 0
	global_load_lds_dwordx4 v[150:151], off
	v_lshl_add_u64 v[150:151], s[80:81], 0, v[128:129]
	s_add_i32 s80, s35, 0x2000
	s_mov_b32 m0, s80
	s_nop 0
	global_load_lds_dwordx4 v[150:151], off
	s_waitcnt vmcnt(6)
	s_waitcnt lgkmcnt(0)
	s_barrier
; #define PG8_STAGE(bufoff, gbase, voff) do { _Pragma("unroll") for (int _i = 0; _i < 2; ++_i) \
;         __builtin_amdgcn_global_load_lds((const unsigned*)((const char*)(gbase) + (voff)[_i]), (LAS unsigned*)(lds + (bufoff) + ldsw + _i * 8192), 16, 0, 0); } while (0)
; #define PG8_LDA(dst, b, h) do { _Pragma("unroll") for (int m = 0; m < 4; ++m) _Pragma("unroll") for (int k = 0; k < 2; ++k) dst[m][k] = *(const LAS bf16x8*)(lds + PG8_SA(b, h) + aoff + m * 2048 + k * 1024); } while (0)
; #define PG8_LDB(dst, b, h) do { _Pragma("unroll") for (int n = 0; n < 2; ++n) _Pragma("unroll") for (int k = 0; k < 2; ++k) dst[n][k] = *(const LAS bf16x8*)(lds + PG8_SB(b, h) + boff + n * 2048 + k * 1024); } while (0)
; #define PG8_MMA(ai, bj, At, Bt) do { __builtin_amdgcn_s_setprio(3); _Pragma("unroll") for (int m = 0; m < 4; ++m) _Pragma("unroll") for (int n = 0; n < 2; ++n) _Pragma("unroll") for (int k = 0; k < 2; ++k) \
;         acc[ai][bj][m][n] = __builtin_amdgcn_mfma_f32_16x16x32_bf16(Bt[n][k], At[m][k], acc[ai][bj][m][n], 0, 0, 0); __builtin_amdgcn_s_setprio(0); } while (0)
; #define PG8_WAIT_V(n) asm volatile("s_waitcnt vmcnt(" #n ")" ::: "memory")
; #define PG8_WAIT_L(n) asm volatile("s_waitcnt lgkmcnt(" #n ")" ::: "memory")
; #define PG8_BAR __builtin_amdgcn_s_barrier()
; #define PG8_SCHED __builtin_amdgcn_sched_barrier(0)
; template <class Epi, class Sched>
; __device__ __forceinline__ void gemm_phase(LAS unsigned char* lds, const Gemm g, const Sched& S, const Epi& E, int tid_in) {
;     ...
;             PG8_WAIT_V(6); PG8_WAIT_L(0); PG8_BAR; PG8_MMA(1, 0, At, B0); PG8_MMA(1, 1, At, B1); PG8_BAR; PG8_SCHED;
;             PG8_LDB(B0, 1, 0); PG8_LDB(B1, 1, 1); PG8_SCHED; PG8_LDA(At, 1, 0); PG8_STAGE(PG8_SA(0, 0), a2, voffA); PG8_STAGE(PG8_SA(0, 1), a2 + hstep, voffA);
;             PG8_WAIT_V(8); PG8_WAIT_L(0); PG8_BAR; PG8_MMA(0, 0, At, B0); PG8_MMA(0, 1, At, B1); PG8_BAR; PG8_SCHED;
	s_setprio 3
	v_mfma_f32_16x16x32_bf16 v[150:153], v[4:7], v[64:67], 0
	v_mfma_f32_16x16x32_bf16 v[158:161], v[4:7], v[108:111], 0
	v_mfma_f32_16x16x32_bf16 v[166:169], v[4:7], v[116:119], 0
	v_mfma_f32_16x16x32_bf16 v[4:7], v[4:7], v[124:127], 0
	v_mfma_f32_16x16x32_bf16 v[150:153], v[8:11], v[104:107], v[150:153]
	v_mfma_f32_16x16x32_bf16 v[158:161], v[8:11], v[112:115], v[158:161]
	v_mfma_f32_16x16x32_bf16 v[166:169], v[8:11], v[120:123], v[166:169]
	v_mfma_f32_16x16x32_bf16 v[4:7], v[8:11], v[146:149], v[4:7]
	v_mfma_f32_16x16x32_bf16 v[8:11], v[12:15], v[124:127], 0
	v_mfma_f32_16x16x32_bf16 v[154:157], v[12:15], v[64:67], 0
	v_mfma_f32_16x16x32_bf16 v[162:165], v[12:15], v[108:111], 0
	v_mfma_f32_16x16x32_bf16 v[170:173], v[12:15], v[116:119], 0
	v_mfma_f32_16x16x32_bf16 v[8:11], v[16:19], v[146:149], v[8:11]
	v_mfma_f32_16x16x32_bf16 v[154:157], v[16:19], v[104:107], v[154:157]
	v_mfma_f32_16x16x32_bf16 v[162:165], v[16:19], v[112:115], v[162:165]
	v_mfma_f32_16x16x32_bf16 v[170:173], v[16:19], v[120:123], v[170:173]
	s_setprio 0
	s_setprio 3
	v_mfma_f32_16x16x32_bf16 v[12:15], v[20:23], v[64:67], 0
	v_mfma_f32_16x16x32_bf16 v[16:19], v[28:31], v[64:67], 0
	v_mfma_f32_16x16x32_bf16 v[12:15], v[24:27], v[104:107], v[12:15]
	v_mfma_f32_16x16x32_bf16 v[16:19], v[32:35], v[104:107], v[16:19]
	v_mfma_f32_16x16x32_bf16 v[64:67], v[20:23], v[108:111], 0
	v_mfma_f32_16x16x32_bf16 v[104:107], v[28:31], v[108:111], 0
	v_mfma_f32_16x16x32_bf16 v[108:111], v[20:23], v[116:119], 0
	v_mfma_f32_16x16x32_bf16 v[20:23], v[20:23], v[124:127], 0
	v_mfma_f32_16x16x32_bf16 v[64:67], v[24:27], v[112:115], v[64:67]
	v_mfma_f32_16x16x32_bf16 v[104:107], v[32:35], v[112:115], v[104:107]
	v_mfma_f32_16x16x32_bf16 v[108:111], v[24:27], v[120:123], v[108:111]
	v_mfma_f32_16x16x32_bf16 v[112:115], v[28:31], v[116:119], 0
	v_mfma_f32_16x16x32_bf16 v[20:23], v[24:27], v[146:149], v[20:23]
	v_mfma_f32_16x16x32_bf16 v[24:27], v[28:31], v[124:127], 0
	v_mfma_f32_16x16x32_bf16 v[112:115], v[32:35], v[120:123], v[112:115]
	v_mfma_f32_16x16x32_bf16 v[24:27], v[32:35], v[146:149], v[24:27]
	s_setprio 0
	s_barrier
	s_add_i32 s83, 0, 0x18000
	s_add_i32 s87, 0, 0x1c000
	v_add_u32_e32 v224, s83, v141
	v_add_u32_e32 v225, s87, v141
	ds_read_b128 v[28:31], v224
	ds_read_b128 v[32:35], v224 offset:1024
	ds_read_b128 v[116:119], v224 offset:2048
	ds_read_b128 v[120:123], v224 offset:3072
	ds_read_b128 v[124:127], v225
	ds_read_b128 v[146:149], v225 offset:1024
	ds_read_b128 v[174:177], v225 offset:2048
	ds_read_b128 v[178:181], v225 offset:3072
	s_mov_b32 m0, s41
	v_lshl_add_u64 v[220:221], v[0:1], 0, s[18:19]
	s_add_u32 s88, s42, 0x10100
	ds_read_b128 v[182:185], v145 offset:32768
	ds_read_b128 v[188:191], v145 offset:33792
	ds_read_b128 v[192:195], v145 offset:34816
	ds_read_b128 v[196:199], v145 offset:35840
	ds_read_b128 v[200:203], v145 offset:36864
	ds_read_b128 v[204:207], v145 offset:37888
	ds_read_b128 v[208:211], v145 offset:38912
	ds_read_b128 v[212:215], v145 offset:39936
	global_load_lds_dwordx4 v[220:221], off
	v_lshl_add_u64 v[220:221], v[2:3], 0, s[18:19]
	s_mov_b32 m0, s66
	s_addc_u32 s89, s43, 0
	global_load_lds_dwordx4 v[220:221], off
	v_lshl_add_u64 v[220:221], s[88:89], 0, v[134:135]
	s_mov_b32 m0, s67
	s_nop 0
	global_load_lds_dwordx4 v[220:221], off
	v_lshl_add_u64 v[220:221], s[88:89], 0, v[130:131]
	s_mov_b32 m0, s68
	s_nop 0
	global_load_lds_dwordx4 v[220:221], off
	s_waitcnt vmcnt(8)
	s_waitcnt lgkmcnt(0)
	s_barrier
	s_setprio 3
	v_mfma_f32_16x16x32_bf16 v[68:71], v[28:31], v[182:185], v[68:71]
	v_mfma_f32_16x16x32_bf16 v[72:75], v[116:119], v[182:185], v[72:75]
	v_mfma_f32_16x16x32_bf16 v[76:79], v[28:31], v[192:195], v[76:79]
	v_mfma_f32_16x16x32_bf16 v[80:83], v[116:119], v[192:195], v[80:83]
	v_mfma_f32_16x16x32_bf16 v[84:87], v[28:31], v[200:203], v[84:87]
	v_mfma_f32_16x16x32_bf16 v[88:91], v[116:119], v[200:203], v[88:91]
	v_mfma_f32_16x16x32_bf16 v[92:95], v[28:31], v[208:211], v[92:95]
	v_mfma_f32_16x16x32_bf16 v[96:99], v[116:119], v[208:211], v[96:99]
	v_mfma_f32_16x16x32_bf16 v[68:71], v[32:35], v[188:191], v[68:71]
	v_mfma_f32_16x16x32_bf16 v[72:75], v[120:123], v[188:191], v[72:75]
	v_mfma_f32_16x16x32_bf16 v[76:79], v[32:35], v[196:199], v[76:79]
	v_mfma_f32_16x16x32_bf16 v[80:83], v[120:123], v[196:199], v[80:83]
	v_mfma_f32_16x16x32_bf16 v[84:87], v[32:35], v[204:207], v[84:87]
	v_mfma_f32_16x16x32_bf16 v[88:91], v[120:123], v[204:207], v[88:91]
	v_mfma_f32_16x16x32_bf16 v[92:95], v[32:35], v[212:215], v[92:95]
	v_mfma_f32_16x16x32_bf16 v[96:99], v[120:123], v[212:215], v[96:99]
	s_setprio 0
	s_setprio 3
	v_mfma_f32_16x16x32_bf16 v[100:103], v[124:127], v[182:185], v[100:103]
	v_mfma_f32_16x16x32_bf16 v[36:39], v[174:177], v[182:185], v[36:39]
	v_mfma_f32_16x16x32_bf16 v[40:43], v[124:127], v[192:195], v[40:43]
	v_mfma_f32_16x16x32_bf16 v[44:47], v[174:177], v[192:195], v[44:47]
	v_mfma_f32_16x16x32_bf16 v[48:51], v[124:127], v[200:203], v[48:51]
	v_mfma_f32_16x16x32_bf16 v[52:55], v[174:177], v[200:203], v[52:55]
	v_mfma_f32_16x16x32_bf16 v[56:59], v[124:127], v[208:211], v[56:59]
	v_mfma_f32_16x16x32_bf16 v[60:63], v[174:177], v[208:211], v[60:63]
	v_mfma_f32_16x16x32_bf16 v[100:103], v[146:149], v[188:191], v[100:103]
	v_mfma_f32_16x16x32_bf16 v[36:39], v[178:181], v[188:191], v[36:39]
	v_mfma_f32_16x16x32_bf16 v[40:43], v[146:149], v[196:199], v[40:43]
	v_mfma_f32_16x16x32_bf16 v[44:47], v[178:181], v[196:199], v[44:47]
	v_mfma_f32_16x16x32_bf16 v[48:51], v[146:149], v[204:207], v[48:51]
	v_mfma_f32_16x16x32_bf16 v[52:55], v[178:181], v[204:207], v[52:55]
	v_mfma_f32_16x16x32_bf16 v[56:59], v[146:149], v[212:215], v[56:59]
	v_mfma_f32_16x16x32_bf16 v[60:63], v[178:181], v[212:215], v[60:63]
	s_setprio 0
	s_barrier
; #define PG8_STAGE(bufoff, gbase, voff) do { _Pragma("unroll") for (int _i = 0; _i < 2; ++_i) \
;         __builtin_amdgcn_global_load_lds((const unsigned*)((const char*)(gbase) + (voff)[_i]), (LAS unsigned*)(lds + (bufoff) + ldsw + _i * 8192), 16, 0, 0); } while (0)
; #define PG8_LDA(dst, b, h) do { _Pragma("unroll") for (int m = 0; m < 4; ++m) _Pragma("unroll") for (int k = 0; k < 2; ++k) dst[m][k] = *(const LAS bf16x8*)(lds + PG8_SA(b, h) + aoff + m * 2048 + k * 1024); } while (0)
; #define PG8_LDB(dst, b, h) do { _Pragma("unroll") for (int n = 0; n < 2; ++n) _Pragma("unroll") for (int k = 0; k < 2; ++k) dst[n][k] = *(const LAS bf16x8*)(lds + PG8_SB(b, h) + boff + n * 2048 + k * 1024); } while (0)
; #define PG8_MMA(ai, bj, At, Bt) do { __builtin_amdgcn_s_setprio(3); _Pragma("unroll") for (int m = 0; m < 4; ++m) _Pragma("unroll") for (int n = 0; n < 2; ++n) _Pragma("unroll") for (int k = 0; k < 2; ++k) \
;         acc[ai][bj][m][n] = __builtin_amdgcn_mfma_f32_16x16x32_bf16(Bt[n][k], At[m][k], acc[ai][bj][m][n], 0, 0, 0); __builtin_amdgcn_s_setprio(0); } while (0)
; #define PG8_WAIT_V(n) asm volatile("s_waitcnt vmcnt(" #n ")" ::: "memory")
; #define PG8_BAR __builtin_amdgcn_s_barrier()
; template <class Epi, class Sched>
; __device__ __forceinline__ void gemm_phase(LAS unsigned char* lds, const Gemm g, const Sched& S, const Epi& E, int tid_in) {
;     ...
;             PG8_LDB(B0, 0, 0); PG8_LDB(B1, 0, 1); PG8_SCHED; PG8_LDA(At, 0, 0); PG8_STAGE(PG8_SA(1, 0), a1, voffA); PG8_STAGE(PG8_SA(1, 1), a1 + hstep, voffA);
;             PG8_WAIT_V(8); PG8_WAIT_L(0); PG8_BAR; PG8_MMA(0, 0, At, B0); PG8_MMA(0, 1, At, B1); PG8_BAR; PG8_SCHED;
;             PG8_LDA(At, 0, 1); PG8_STAGE(PG8_SB(0, 0), b2, voffB); PG8_STAGE(PG8_SB(0, 1), b2 + hstep, voffB);
;             PG8_WAIT_V(6); PG8_WAIT_L(0); PG8_BAR; PG8_MMA(1, 0, At, B0); PG8_MMA(1, 1, At, B1); PG8_BAR; PG8_SCHED;
;             PG8_LDB(B0, 1, 0); PG8_LDB(B1, 1, 1); PG8_SCHED; PG8_LDA(At, 1, 0); PG8_STAGE(PG8_SA(0, 0), a2, voffA); PG8_STAGE(PG8_SA(0, 1), a2 + hstep, voffA);
;             PG8_WAIT_V(8); PG8_WAIT_L(0); PG8_BAR; PG8_MMA(0, 0, At, B0); PG8_MMA(0, 1, At, B1); PG8_BAR; PG8_SCHED;
;             PG8_LDA(At, 1, 1); PG8_STAGE(PG8_SB(1, 0), b3, voffB); PG8_STAGE(PG8_SB(1, 1), b3 + hstep, voffB);
;             PG8_WAIT_V(6); PG8_WAIT_L(0); PG8_BAR; PG8_MMA(1, 0, At, B0); PG8_MMA(1, 1, At, B1); PG8_BAR; PG8_SCHED;
	s_add_i32 s83, s83, s2
	s_add_i32 s81, s83, 0x2000
	v_lshl_add_u64 v[216:217], v[216:217], 0, s[20:21]
	s_mov_b32 m0, s83
	s_add_u32 s88, s44, 0x10180
	ds_read_b128 v[182:185], v145 offset:49152
	ds_read_b128 v[188:191], v145 offset:50176
	ds_read_b128 v[192:195], v145 offset:51200
	ds_read_b128 v[196:199], v145 offset:52224
	ds_read_b128 v[200:203], v145 offset:53248
	ds_read_b128 v[204:207], v145 offset:54272
	ds_read_b128 v[208:211], v145 offset:55296
	ds_read_b128 v[212:215], v145 offset:56320
	global_load_lds_dwordx4 v[216:217], off
	v_lshl_add_u64 v[216:217], v[218:219], 0, s[20:21]
	s_mov_b32 m0, s81
	s_addc_u32 s89, s45, 0
	s_add_i32 s44, s87, s2
	global_load_lds_dwordx4 v[216:217], off
	v_lshl_add_u64 v[216:217], s[88:89], 0, v[132:133]
	s_mov_b32 m0, s44
	s_add_i32 s45, s44, 0x2000
	global_load_lds_dwordx4 v[216:217], off
	v_lshl_add_u64 v[216:217], s[88:89], 0, v[128:129]
	s_mov_b32 m0, s45
	s_nop 0
	global_load_lds_dwordx4 v[216:217], off
	s_waitcnt vmcnt(6)
	s_waitcnt lgkmcnt(0)
	s_barrier
	s_setprio 3
	v_mfma_f32_16x16x32_bf16 v[4:7], v[28:31], v[208:211], v[4:7]
	v_mfma_f32_16x16x32_bf16 v[8:11], v[116:119], v[208:211], v[8:11]
	v_mfma_f32_16x16x32_bf16 v[150:153], v[28:31], v[182:185], v[150:153]
	v_mfma_f32_16x16x32_bf16 v[154:157], v[116:119], v[182:185], v[154:157]
	v_mfma_f32_16x16x32_bf16 v[158:161], v[28:31], v[192:195], v[158:161]
	v_mfma_f32_16x16x32_bf16 v[162:165], v[116:119], v[192:195], v[162:165]
	v_mfma_f32_16x16x32_bf16 v[166:169], v[28:31], v[200:203], v[166:169]
	v_mfma_f32_16x16x32_bf16 v[170:173], v[116:119], v[200:203], v[170:173]
	v_mfma_f32_16x16x32_bf16 v[4:7], v[32:35], v[212:215], v[4:7]
	v_mfma_f32_16x16x32_bf16 v[8:11], v[120:123], v[212:215], v[8:11]
	v_mfma_f32_16x16x32_bf16 v[150:153], v[32:35], v[188:191], v[150:153]
	v_mfma_f32_16x16x32_bf16 v[154:157], v[120:123], v[188:191], v[154:157]
	v_mfma_f32_16x16x32_bf16 v[158:161], v[32:35], v[196:199], v[158:161]
	v_mfma_f32_16x16x32_bf16 v[162:165], v[120:123], v[196:199], v[162:165]
	v_mfma_f32_16x16x32_bf16 v[166:169], v[32:35], v[204:207], v[166:169]
	v_mfma_f32_16x16x32_bf16 v[170:173], v[120:123], v[204:207], v[170:173]
	s_setprio 0
	s_setprio 3
	v_mfma_f32_16x16x32_bf16 v[12:15], v[124:127], v[182:185], v[12:15]
	v_mfma_f32_16x16x32_bf16 v[16:19], v[174:177], v[182:185], v[16:19]
	v_mfma_f32_16x16x32_bf16 v[28:31], v[124:127], v[192:195], v[64:67]
	v_mfma_f32_16x16x32_bf16 v[32:35], v[174:177], v[192:195], v[104:107]
	v_mfma_f32_16x16x32_bf16 v[64:67], v[124:127], v[200:203], v[108:111]
	v_mfma_f32_16x16x32_bf16 v[104:107], v[174:177], v[200:203], v[112:115]
	v_mfma_f32_16x16x32_bf16 v[20:23], v[124:127], v[208:211], v[20:23]
	v_mfma_f32_16x16x32_bf16 v[24:27], v[174:177], v[208:211], v[24:27]
	v_mfma_f32_16x16x32_bf16 v[12:15], v[146:149], v[188:191], v[12:15]
	v_mfma_f32_16x16x32_bf16 v[16:19], v[178:181], v[188:191], v[16:19]
	v_mfma_f32_16x16x32_bf16 v[28:31], v[146:149], v[196:199], v[28:31]
	v_mfma_f32_16x16x32_bf16 v[32:35], v[178:181], v[196:199], v[32:35]
	v_mfma_f32_16x16x32_bf16 v[64:67], v[146:149], v[204:207], v[64:67]
	v_mfma_f32_16x16x32_bf16 v[104:107], v[178:181], v[204:207], v[104:107]
	v_mfma_f32_16x16x32_bf16 v[20:23], v[146:149], v[212:215], v[20:23]
	v_mfma_f32_16x16x32_bf16 v[24:27], v[178:181], v[212:215], v[24:27]
	s_setprio 0
	s_barrier
	ds_read_b128 v[108:111], v143
	ds_read_b128 v[112:115], v143 offset:1024
	ds_read_b128 v[116:119], v143 offset:2048
	ds_read_b128 v[120:123], v143 offset:3072
	ds_read_b128 v[124:127], v144
	ds_read_b128 v[146:149], v144 offset:1024
	ds_read_b128 v[174:177], v144 offset:2048
	ds_read_b128 v[178:181], v144 offset:3072
	s_mov_b32 m0, s71
	v_lshl_add_u64 v[0:1], v[0:1], 0, s[20:21]
	s_add_u32 s42, s42, 0x10180
	ds_read_b128 v[182:185], v145
	ds_read_b128 v[188:191], v145 offset:1024
	ds_read_b128 v[192:195], v145 offset:2048
	ds_read_b128 v[196:199], v145 offset:3072
	ds_read_b128 v[200:203], v145 offset:4096
	ds_read_b128 v[204:207], v145 offset:5120
	ds_read_b128 v[208:211], v145 offset:6144
	ds_read_b128 v[212:215], v145 offset:7168
	global_load_lds_dwordx4 v[0:1], off
	v_lshl_add_u64 v[0:1], v[2:3], 0, s[20:21]
	s_mov_b32 m0, s72
	s_addc_u32 s43, s43, 0
	global_load_lds_dwordx4 v[0:1], off
	v_lshl_add_u64 v[0:1], s[42:43], 0, v[134:135]
	s_mov_b32 m0, s73
	s_nop 0
	global_load_lds_dwordx4 v[0:1], off
	v_lshl_add_u64 v[0:1], s[42:43], 0, v[130:131]
	s_mov_b32 m0, s74
	s_nop 0
	global_load_lds_dwordx4 v[0:1], off
	s_waitcnt vmcnt(8)
	s_waitcnt lgkmcnt(0)
	s_barrier
; #define PG8_STAGE(bufoff, gbase, voff) do { _Pragma("unroll") for (int _i = 0; _i < 2; ++_i) \
;         __builtin_amdgcn_global_load_lds((const unsigned*)((const char*)(gbase) + (voff)[_i]), (LAS unsigned*)(lds + (bufoff) + ldsw + _i * 8192), 16, 0, 0); } while (0)
; #define PG8_LDA(dst, b, h) do { _Pragma("unroll") for (int m = 0; m < 4; ++m) _Pragma("unroll") for (int k = 0; k < 2; ++k) dst[m][k] = *(const LAS bf16x8*)(lds + PG8_SA(b, h) + aoff + m * 2048 + k * 1024); } while (0)
; #define PG8_MMA(ai, bj, At, Bt) do { __builtin_amdgcn_s_setprio(3); _Pragma("unroll") for (int m = 0; m < 4; ++m) _Pragma("unroll") for (int n = 0; n < 2; ++n) _Pragma("unroll") for (int k = 0; k < 2; ++k) \
;         acc[ai][bj][m][n] = __builtin_amdgcn_mfma_f32_16x16x32_bf16(Bt[n][k], At[m][k], acc[ai][bj][m][n], 0, 0, 0); __builtin_amdgcn_s_setprio(0); } while (0)
; #define PG8_WAIT_V(n) asm volatile("s_waitcnt vmcnt(" #n ")" ::: "memory")
; #define PG8_WAIT_L(n) asm volatile("s_waitcnt lgkmcnt(" #n ")" ::: "memory")
; #define PG8_BAR __builtin_amdgcn_s_barrier()
; #define PG8_SCHED __builtin_amdgcn_sched_barrier(0)
; template <class Epi, class Sched>
; __device__ __forceinline__ void gemm_phase(LAS unsigned char* lds, const Gemm g, const Sched& S, const Epi& E, int tid_in) {
;     ...
;             PG8_WAIT_V(8); PG8_WAIT_L(0); PG8_BAR; PG8_MMA(0, 0, At, B0); PG8_MMA(0, 1, At, B1); PG8_BAR; PG8_SCHED;
;             PG8_LDA(At, 0, 1); PG8_STAGE(PG8_SB(0, 0), b2, voffB); PG8_STAGE(PG8_SB(0, 1), b2 + hstep, voffB);
;             PG8_WAIT_V(6); PG8_WAIT_L(0); PG8_BAR; PG8_MMA(1, 0, At, B0); PG8_MMA(1, 1, At, B1); PG8_BAR; PG8_SCHED;
	s_setprio 3
	v_mfma_f32_16x16x32_bf16 v[0:3], v[108:111], v[182:185], v[68:71]
	v_mfma_f32_16x16x32_bf16 v[68:71], v[116:119], v[182:185], v[72:75]
	v_mfma_f32_16x16x32_bf16 v[72:75], v[108:111], v[192:195], v[76:79]
	v_mfma_f32_16x16x32_bf16 v[76:79], v[116:119], v[192:195], v[80:83]
	v_mfma_f32_16x16x32_bf16 v[80:83], v[108:111], v[200:203], v[84:87]
	v_mfma_f32_16x16x32_bf16 v[84:87], v[116:119], v[200:203], v[88:91]
	v_mfma_f32_16x16x32_bf16 v[88:91], v[108:111], v[208:211], v[92:95]
	v_mfma_f32_16x16x32_bf16 v[92:95], v[116:119], v[208:211], v[96:99]
	v_mfma_f32_16x16x32_bf16 v[0:3], v[112:115], v[188:191], v[0:3]
	v_mfma_f32_16x16x32_bf16 v[68:71], v[120:123], v[188:191], v[68:71]
	v_mfma_f32_16x16x32_bf16 v[72:75], v[112:115], v[196:199], v[72:75]
	v_mfma_f32_16x16x32_bf16 v[76:79], v[120:123], v[196:199], v[76:79]
	v_mfma_f32_16x16x32_bf16 v[80:83], v[112:115], v[204:207], v[80:83]
	v_mfma_f32_16x16x32_bf16 v[84:87], v[120:123], v[204:207], v[84:87]
	v_mfma_f32_16x16x32_bf16 v[88:91], v[112:115], v[212:215], v[88:91]
	v_mfma_f32_16x16x32_bf16 v[96:99], v[120:123], v[212:215], v[92:95]
	s_setprio 0
	s_setprio 3
	v_mfma_f32_16x16x32_bf16 v[52:55], v[174:177], v[200:203], v[52:55]
	v_mfma_f32_16x16x32_bf16 v[92:95], v[124:127], v[182:185], v[100:103]
	v_mfma_f32_16x16x32_bf16 v[36:39], v[174:177], v[182:185], v[36:39]
	v_mfma_f32_16x16x32_bf16 v[40:43], v[124:127], v[192:195], v[40:43]
	v_mfma_f32_16x16x32_bf16 v[44:47], v[174:177], v[192:195], v[44:47]
	v_mfma_f32_16x16x32_bf16 v[48:51], v[124:127], v[200:203], v[48:51]
	v_mfma_f32_16x16x32_bf16 v[182:185], v[178:181], v[204:207], v[52:55]
	v_mfma_f32_16x16x32_bf16 v[52:55], v[124:127], v[208:211], v[56:59]
	v_mfma_f32_16x16x32_bf16 v[36:39], v[178:181], v[188:191], v[36:39]
	v_mfma_f32_16x16x32_bf16 v[40:43], v[146:149], v[196:199], v[40:43]
	v_mfma_f32_16x16x32_bf16 v[44:47], v[178:181], v[196:199], v[44:47]
	v_mfma_f32_16x16x32_bf16 v[48:51], v[146:149], v[204:207], v[48:51]
	v_mfma_f32_16x16x32_bf16 v[56:59], v[146:149], v[212:215], v[52:55]
	v_mfma_f32_16x16x32_bf16 v[52:55], v[174:177], v[208:211], v[60:63]
	v_mfma_f32_16x16x32_bf16 v[216:219], v[146:149], v[188:191], v[92:95]
	v_mfma_f32_16x16x32_bf16 v[188:191], v[178:181], v[212:215], v[52:55]
	s_setprio 0
	s_barrier
	s_mov_b32 m0, s82
	v_lshl_add_u64 v[252:253], s[46:47], 0, v[132:133]
	s_add_u32 s42, s46, 0x10000
	s_nop 0
	ds_read_b128 v[52:55], v145 offset:16384
	ds_read_b128 v[60:63], v145 offset:17408
	ds_read_b128 v[92:95], v145 offset:18432
	ds_read_b128 v[100:103], v145 offset:19456
	ds_read_b128 v[192:195], v145 offset:20480
	ds_read_b128 v[196:199], v145 offset:21504
	ds_read_b128 v[200:203], v145 offset:22528
	ds_read_b128 v[204:207], v145 offset:23552
	global_load_lds_dwordx4 v[252:253], off
	v_lshl_add_u64 v[186:187], s[46:47], 0, v[128:129]
	s_mov_b32 m0, s31
	s_addc_u32 s43, s47, 0
	global_load_lds_dwordx4 v[186:187], off
	v_lshl_add_u64 v[208:209], s[42:43], 0, v[132:133]
	s_mov_b32 m0, s35
	s_nop 0
	global_load_lds_dwordx4 v[208:209], off
	v_lshl_add_u64 v[208:209], s[42:43], 0, v[128:129]
	s_mov_b32 m0, s80
	s_nop 0
	global_load_lds_dwordx4 v[208:209], off
	s_waitcnt vmcnt(6)
	s_waitcnt lgkmcnt(0)
	s_barrier
	s_setprio 3
	v_mfma_f32_16x16x32_bf16 v[4:7], v[108:111], v[200:203], v[4:7]
	v_mfma_f32_16x16x32_bf16 v[8:11], v[116:119], v[200:203], v[8:11]
	v_mfma_f32_16x16x32_bf16 v[150:153], v[108:111], v[52:55], v[150:153]
	v_mfma_f32_16x16x32_bf16 v[154:157], v[116:119], v[52:55], v[154:157]
	v_mfma_f32_16x16x32_bf16 v[158:161], v[108:111], v[92:95], v[158:161]
	v_mfma_f32_16x16x32_bf16 v[162:165], v[116:119], v[92:95], v[162:165]
	v_mfma_f32_16x16x32_bf16 v[166:169], v[108:111], v[192:195], v[166:169]
	v_mfma_f32_16x16x32_bf16 v[170:173], v[116:119], v[192:195], v[170:173]
	v_mfma_f32_16x16x32_bf16 v[4:7], v[112:115], v[204:207], v[4:7]
	v_mfma_f32_16x16x32_bf16 v[8:11], v[120:123], v[204:207], v[8:11]
	v_mfma_f32_16x16x32_bf16 v[150:153], v[112:115], v[60:63], v[150:153]
	v_mfma_f32_16x16x32_bf16 v[154:157], v[120:123], v[60:63], v[154:157]
	v_mfma_f32_16x16x32_bf16 v[158:161], v[112:115], v[100:103], v[158:161]
	v_mfma_f32_16x16x32_bf16 v[162:165], v[120:123], v[100:103], v[162:165]
	v_mfma_f32_16x16x32_bf16 v[166:169], v[112:115], v[196:199], v[166:169]
	v_mfma_f32_16x16x32_bf16 v[170:173], v[120:123], v[196:199], v[170:173]
	s_setprio 0
	s_setprio 3
	v_mfma_f32_16x16x32_bf16 v[12:15], v[124:127], v[52:55], v[12:15]
	v_mfma_f32_16x16x32_bf16 v[208:211], v[146:149], v[60:63], v[12:15]
	v_mfma_f32_16x16x32_bf16 v[12:15], v[174:177], v[52:55], v[16:19]
	v_mfma_f32_16x16x32_bf16 v[16:19], v[178:181], v[60:63], v[12:15]
	v_mfma_f32_16x16x32_bf16 v[12:15], v[124:127], v[92:95], v[28:31]
	v_mfma_f32_16x16x32_bf16 v[212:215], v[146:149], v[100:103], v[12:15]
	v_mfma_f32_16x16x32_bf16 v[12:15], v[174:177], v[92:95], v[32:35]
	v_mfma_f32_16x16x32_bf16 v[32:35], v[178:181], v[100:103], v[12:15]
	v_mfma_f32_16x16x32_bf16 v[12:15], v[124:127], v[192:195], v[64:67]
	v_mfma_f32_16x16x32_bf16 v[220:223], v[146:149], v[196:199], v[12:15]
	v_mfma_f32_16x16x32_bf16 v[12:15], v[174:177], v[192:195], v[104:107]
	v_mfma_f32_16x16x32_bf16 v[192:195], v[178:181], v[196:199], v[12:15]
	v_mfma_f32_16x16x32_bf16 v[12:15], v[124:127], v[200:203], v[20:23]
	v_mfma_f32_16x16x32_bf16 v[146:149], v[146:149], v[204:207], v[12:15]
	v_mfma_f32_16x16x32_bf16 v[12:15], v[174:177], v[200:203], v[24:27]
	v_mfma_f32_16x16x32_bf16 v[174:177], v[178:181], v[204:207], v[12:15]
	s_setprio 0
	s_barrier
; #define PG8_STAGE(bufoff, gbase, voff) do { _Pragma("unroll") for (int _i = 0; _i < 2; ++_i) \
;         __builtin_amdgcn_global_load_lds((const unsigned*)((const char*)(gbase) + (voff)[_i]), (LAS unsigned*)(lds + (bufoff) + ldsw + _i * 8192), 16, 0, 0); } while (0)
; #define PG8_LDA(dst, b, h) do { _Pragma("unroll") for (int m = 0; m < 4; ++m) _Pragma("unroll") for (int k = 0; k < 2; ++k) dst[m][k] = *(const LAS bf16x8*)(lds + PG8_SA(b, h) + aoff + m * 2048 + k * 1024); } while (0)
; #define PG8_LDB(dst, b, h) do { _Pragma("unroll") for (int n = 0; n < 2; ++n) _Pragma("unroll") for (int k = 0; k < 2; ++k) dst[n][k] = *(const LAS bf16x8*)(lds + PG8_SB(b, h) + boff + n * 2048 + k * 1024); } while (0)
; #define PG8_MMA(ai, bj, At, Bt) do { __builtin_amdgcn_s_setprio(3); _Pragma("unroll") for (int m = 0; m < 4; ++m) _Pragma("unroll") for (int n = 0; n < 2; ++n) _Pragma("unroll") for (int k = 0; k < 2; ++k) \
;         acc[ai][bj][m][n] = __builtin_amdgcn_mfma_f32_16x16x32_bf16(Bt[n][k], At[m][k], acc[ai][bj][m][n], 0, 0, 0); __builtin_amdgcn_s_setprio(0); } while (0)
; #define PG8_WAIT_V(n) asm volatile("s_waitcnt vmcnt(" #n ")" ::: "memory")
; #define PG8_WAIT_L(n) asm volatile("s_waitcnt lgkmcnt(" #n ")" ::: "memory")
; #define PG8_BAR __builtin_amdgcn_s_barrier()
; #define PG8_SCHED __builtin_amdgcn_sched_barrier(0)
; template <class Epi, class Sched>
; __device__ __forceinline__ void gemm_phase(LAS unsigned char* lds, const Gemm g, const Sched& S, const Epi& E, int tid_in) {
;     ...
;             PG8_LDB(B0, 1, 0); PG8_LDB(B1, 1, 1); PG8_SCHED; PG8_LDA(At, 1, 0); PG8_STAGE(PG8_SA(0, 0), a2, voffA); PG8_STAGE(PG8_SA(0, 1), a2 + hstep, voffA);
;             PG8_WAIT_V(8); PG8_WAIT_L(0); PG8_BAR; PG8_MMA(0, 0, At, B0); PG8_MMA(0, 1, At, B1); PG8_BAR; PG8_SCHED;
;             PG8_LDA(At, 1, 1); PG8_STAGE(PG8_SB(1, 0), b3, voffB); PG8_STAGE(PG8_SB(1, 1), b3 + hstep, voffB);
;             PG8_WAIT_V(6); PG8_WAIT_L(0); PG8_BAR; PG8_MMA(1, 0, At, B0); PG8_MMA(1, 1, At, B1); PG8_BAR; PG8_SCHED;
;         }
;         if (wr == 0) PG8_BAR;
	s_nop 4
	ds_read_b128 v[12:15], v224
	ds_read_b128 v[24:27], v224 offset:1024
	ds_read_b128 v[64:67], v224 offset:2048
	ds_read_b128 v[178:181], v224 offset:3072
	ds_read_b128 v[196:199], v225
	ds_read_b128 v[200:203], v225 offset:1024
	ds_read_b128 v[204:207], v225 offset:2048
	ds_read_b128 v[224:227], v225 offset:3072
	s_mov_b32 m0, s41
	v_lshl_add_u64 v[52:53], s[48:49], 0, v[134:135]
	s_add_u32 s42, s48, 0x10000
	ds_read_b128 v[20:23], v145 offset:32768
	ds_read_b128 v[28:31], v145 offset:33792
	ds_read_b128 v[228:231], v145 offset:34816
	ds_read_b128 v[232:235], v145 offset:35840
	ds_read_b128 v[236:239], v145 offset:36864
	ds_read_b128 v[240:243], v145 offset:37888
	ds_read_b128 v[244:247], v145 offset:38912
	ds_read_b128 v[248:251], v145 offset:39936
	global_load_lds_dwordx4 v[52:53], off
	v_lshl_add_u64 v[52:53], s[48:49], 0, v[130:131]
	s_mov_b32 m0, s66
	s_addc_u32 s43, s49, 0
	global_load_lds_dwordx4 v[52:53], off
	v_lshl_add_u64 v[52:53], s[42:43], 0, v[134:135]
	s_mov_b32 m0, s67
	s_nop 0
	global_load_lds_dwordx4 v[52:53], off
	v_lshl_add_u64 v[52:53], s[42:43], 0, v[130:131]
	s_mov_b32 m0, s68
	s_nop 0
	global_load_lds_dwordx4 v[52:53], off
	s_waitcnt vmcnt(8)
	s_waitcnt lgkmcnt(0)
	s_barrier
	s_setprio 3
	v_mfma_f32_16x16x32_bf16 v[0:3], v[12:15], v[20:23], v[0:3]
	v_mfma_f32_16x16x32_bf16 v[124:127], v[24:27], v[28:31], v[0:3]
	v_mfma_f32_16x16x32_bf16 v[0:3], v[64:67], v[20:23], v[68:71]
	v_mfma_f32_16x16x32_bf16 v[116:119], v[178:181], v[28:31], v[0:3]
	v_mfma_f32_16x16x32_bf16 v[0:3], v[12:15], v[228:231], v[72:75]
	v_mfma_f32_16x16x32_bf16 v[108:111], v[24:27], v[232:235], v[0:3]
	v_mfma_f32_16x16x32_bf16 v[0:3], v[64:67], v[228:231], v[76:79]
	v_mfma_f32_16x16x32_bf16 v[100:103], v[178:181], v[232:235], v[0:3]
	v_mfma_f32_16x16x32_bf16 v[0:3], v[12:15], v[236:239], v[80:83]
	v_mfma_f32_16x16x32_bf16 v[92:95], v[24:27], v[240:243], v[0:3]
	v_mfma_f32_16x16x32_bf16 v[0:3], v[64:67], v[236:239], v[84:87]
	v_mfma_f32_16x16x32_bf16 v[84:87], v[178:181], v[240:243], v[0:3]
	v_mfma_f32_16x16x32_bf16 v[0:3], v[12:15], v[244:247], v[88:91]
	v_mfma_f32_16x16x32_bf16 v[60:63], v[24:27], v[248:251], v[0:3]
	v_mfma_f32_16x16x32_bf16 v[0:3], v[64:67], v[244:247], v[96:99]
	v_mfma_f32_16x16x32_bf16 v[52:55], v[178:181], v[248:251], v[0:3]
	s_setprio 0
	s_setprio 3
	v_mfma_f32_16x16x32_bf16 v[0:3], v[196:199], v[20:23], v[216:219]
	v_mfma_f32_16x16x32_bf16 v[120:123], v[200:203], v[28:31], v[0:3]
	v_mfma_f32_16x16x32_bf16 v[0:3], v[204:207], v[20:23], v[36:39]
	v_mfma_f32_16x16x32_bf16 v[112:115], v[224:227], v[28:31], v[0:3]
	v_mfma_f32_16x16x32_bf16 v[0:3], v[196:199], v[228:231], v[40:43]
	v_mfma_f32_16x16x32_bf16 v[104:107], v[200:203], v[232:235], v[0:3]
	v_mfma_f32_16x16x32_bf16 v[0:3], v[204:207], v[228:231], v[44:47]
	v_mfma_f32_16x16x32_bf16 v[96:99], v[224:227], v[232:235], v[0:3]
	v_mfma_f32_16x16x32_bf16 v[0:3], v[196:199], v[236:239], v[48:51]
	v_mfma_f32_16x16x32_bf16 v[88:91], v[200:203], v[240:243], v[0:3]
	v_mfma_f32_16x16x32_bf16 v[0:3], v[204:207], v[236:239], v[182:185]
	v_mfma_f32_16x16x32_bf16 v[80:83], v[224:227], v[240:243], v[0:3]
	v_mfma_f32_16x16x32_bf16 v[0:3], v[196:199], v[244:247], v[56:59]
	v_mfma_f32_16x16x32_bf16 v[56:59], v[200:203], v[248:251], v[0:3]
	v_mfma_f32_16x16x32_bf16 v[0:3], v[204:207], v[244:247], v[188:191]
	v_mfma_f32_16x16x32_bf16 v[48:51], v[224:227], v[248:251], v[0:3]
	s_setprio 0
	s_barrier
	s_mov_b32 m0, s83
	v_lshl_add_u64 v[20:21], v[252:253], 0, s[8:9]
	s_add_u32 s42, s46, 0x10080
	s_nop 1
	ds_read_b128 v[0:3], v145 offset:49152
	ds_read_b128 v[40:43], v145 offset:50176
	ds_read_b128 v[182:185], v145 offset:51200
	ds_read_b128 v[188:191], v145 offset:52224
	ds_read_b128 v[216:219], v145 offset:53248
	ds_read_b128 v[228:231], v145 offset:54272
	ds_read_b128 v[232:235], v145 offset:55296
	ds_read_b128 v[236:239], v145 offset:56320
	global_load_lds_dwordx4 v[20:21], off
	v_lshl_add_u64 v[20:21], v[186:187], 0, s[8:9]
	s_mov_b32 m0, s81
	s_addc_u32 s43, s47, 0
	global_load_lds_dwordx4 v[20:21], off
	v_lshl_add_u64 v[20:21], s[42:43], 0, v[132:133]
	s_mov_b32 m0, s44
	s_nop 0
	global_load_lds_dwordx4 v[20:21], off
	v_lshl_add_u64 v[20:21], s[42:43], 0, v[128:129]
	s_mov_b32 m0, s45
	s_nop 0
	global_load_lds_dwordx4 v[20:21], off
	s_waitcnt vmcnt(6)
	s_waitcnt lgkmcnt(0)
	s_barrier
	s_setprio 3
	v_mfma_f32_16x16x32_bf16 v[20:23], v[12:15], v[0:3], v[150:153]
	v_mfma_f32_16x16x32_bf16 v[76:79], v[24:27], v[40:43], v[20:23]
	v_mfma_f32_16x16x32_bf16 v[20:23], v[64:67], v[0:3], v[154:157]
	v_mfma_f32_16x16x32_bf16 v[68:71], v[178:181], v[40:43], v[20:23]
	v_mfma_f32_16x16x32_bf16 v[20:23], v[12:15], v[182:185], v[158:161]
	v_mfma_f32_16x16x32_bf16 v[44:47], v[24:27], v[188:191], v[20:23]
	v_mfma_f32_16x16x32_bf16 v[20:23], v[64:67], v[182:185], v[162:165]
	v_mfma_f32_16x16x32_bf16 v[36:39], v[178:181], v[188:191], v[20:23]
	v_mfma_f32_16x16x32_bf16 v[20:23], v[12:15], v[216:219], v[166:169]
	v_mfma_f32_16x16x32_bf16 v[4:7], v[12:15], v[232:235], v[4:7]
	v_mfma_f32_16x16x32_bf16 v[28:31], v[24:27], v[228:231], v[20:23]
	v_mfma_f32_16x16x32_bf16 v[20:23], v[64:67], v[216:219], v[170:173]
	v_mfma_f32_16x16x32_bf16 v[12:15], v[24:27], v[236:239], v[4:7]
	v_mfma_f32_16x16x32_bf16 v[4:7], v[64:67], v[232:235], v[8:11]
	v_mfma_f32_16x16x32_bf16 v[20:23], v[178:181], v[228:231], v[20:23]
	v_mfma_f32_16x16x32_bf16 v[4:7], v[178:181], v[236:239], v[4:7]
	s_setprio 0
	s_setprio 3
	v_mfma_f32_16x16x32_bf16 v[8:11], v[196:199], v[0:3], v[208:211]
	v_mfma_f32_16x16x32_bf16 v[0:3], v[204:207], v[0:3], v[16:19]
	v_mfma_f32_16x16x32_bf16 v[64:67], v[224:227], v[40:43], v[0:3]
	v_mfma_f32_16x16x32_bf16 v[0:3], v[196:199], v[182:185], v[212:215]
	v_mfma_f32_16x16x32_bf16 v[72:75], v[200:203], v[40:43], v[8:11]
	v_mfma_f32_16x16x32_bf16 v[40:43], v[200:203], v[188:191], v[0:3]
	v_mfma_f32_16x16x32_bf16 v[0:3], v[204:207], v[182:185], v[32:35]
	v_mfma_f32_16x16x32_bf16 v[32:35], v[224:227], v[188:191], v[0:3]
	v_mfma_f32_16x16x32_bf16 v[0:3], v[196:199], v[216:219], v[220:223]
	v_mfma_f32_16x16x32_bf16 v[24:27], v[200:203], v[228:231], v[0:3]
	v_mfma_f32_16x16x32_bf16 v[0:3], v[204:207], v[216:219], v[192:195]
	v_mfma_f32_16x16x32_bf16 v[16:19], v[224:227], v[228:231], v[0:3]
	v_mfma_f32_16x16x32_bf16 v[0:3], v[196:199], v[232:235], v[146:149]
	v_mfma_f32_16x16x32_bf16 v[8:11], v[200:203], v[236:239], v[0:3]
	v_mfma_f32_16x16x32_bf16 v[0:3], v[204:207], v[232:235], v[174:177]
	v_mfma_f32_16x16x32_bf16 v[0:3], v[224:227], v[236:239], v[0:3]
	s_setprio 0
	s_barrier
	s_andn2_b64 vcc, exec, s[14:15]
	s_cbranch_vccnz .LBB0_990
	s_barrier

; #define PG8_STAGE(bufoff, gbase, voff) do { _Pragma("unroll") for (int _i = 0; _i < 2; ++_i) \
;         __builtin_amdgcn_global_load_lds((const unsigned*)((const char*)(gbase) + (voff)[_i]), (LAS unsigned*)(lds + (bufoff) + ldsw + _i * 8192), 16, 0, 0); } while (0)
; #define PG8_LDA(dst, b, h) do { _Pragma("unroll") for (int m = 0; m < 4; ++m) _Pragma("unroll") for (int k = 0; k < 2; ++k) dst[m][k] = *(const LAS bf16x8*)(lds + PG8_SA(b, h) + aoff + m * 2048 + k * 1024); } while (0)
; #define PG8_LDB(dst, b, h) do { _Pragma("unroll") for (int n = 0; n < 2; ++n) _Pragma("unroll") for (int k = 0; k < 2; ++k) dst[n][k] = *(const LAS bf16x8*)(lds + PG8_SB(b, h) + boff + n * 2048 + k * 1024); } while (0)
; #define PG8_MMA(ai, bj, At, Bt) do { __builtin_amdgcn_s_setprio(3); _Pragma("unroll") for (int m = 0; m < 4; ++m) _Pragma("unroll") for (int n = 0; n < 2; ++n) _Pragma("unroll") for (int k = 0; k < 2; ++k) \
;         acc[ai][bj][m][n] = __builtin_amdgcn_mfma_f32_16x16x32_bf16(Bt[n][k], At[m][k], acc[ai][bj][m][n], 0, 0, 0); __builtin_amdgcn_s_setprio(0); } while (0)
; #define PG8_WAIT_V(n) asm volatile("s_waitcnt vmcnt(" #n ")" ::: "memory")
; template <class Epi, class Sched>
; __device__ __forceinline__ void gemm_phase(LAS unsigned char* lds, const Gemm g, const Sched& S, const Epi& E, int tid_in) {
;     ...
;         const char* nA = has_next ? (const char*)g.A + (size_t)nxt.pm * tstep + nxt.koff : cA; const char* nB = has_next ? (const char*)g.Bt + (size_t)nxt.pn * tstep + nxt.koff : cB;
;         for (int t = 0; t < nt; t += 2) {
;             const bool last = (t == nt - 2);
;             const char* a1 = cA + (size_t)(t + 1) * kstep;
;             const char* a2 = last ? nA : cA + (size_t)(t + 2) * kstep; const char* b2 = last ? nB : cB + (size_t)(t + 2) * kstep;
;             const char* a3 = a2 + kstep; const char* b3 = b2 + kstep;
;             PG8_LDB(B0, 0, 0); PG8_LDB(B1, 0, 1); PG8_SCHED; PG8_LDA(At, 0, 0); PG8_STAGE(PG8_SA(1, 0), a1, voffA); PG8_STAGE(PG8_SA(1, 1), a1 + hstep, voffA);
;             PG8_WAIT_V(8); PG8_WAIT_L(0); PG8_BAR; PG8_MMA(0, 0, At, B0); PG8_MMA(0, 1, At, B1); PG8_BAR; PG8_SCHED;
;             PG8_LDA(At, 0, 1); PG8_STAGE(PG8_SB(0, 0), b2, voffB); PG8_STAGE(PG8_SB(0, 1), b2 + hstep, voffB);
;             PG8_WAIT_V(6); PG8_WAIT_L(0); PG8_BAR; PG8_MMA(1, 0, At, B0); PG8_MMA(1, 1, At, B1); PG8_BAR; PG8_SCHED;
.LBB0_1008:
	s_ashr_i32 s23, s22, 31
	s_lshl_b64 s[24:25], s[22:23], 20
	s_add_u32 s24, s58, s24
	s_addc_u32 s25, s59, s25
	s_and_b64 s[26:27], s[4:5], exec
	s_cselect_b32 s23, s25, s31
	s_cselect_b32 s29, s24, s30
	s_ashr_i32 s21, s20, 31
	s_lshl_b64 s[26:27], s[20:21], 20
	s_add_u32 s26, s60, s26
	s_addc_u32 s27, s61, s27
	s_and_b64 s[36:37], s[4:5], exec
	s_cselect_b32 s21, s27, s35
	s_cselect_b32 s47, s26, s34
	s_add_u32 s48, s34, 0x100
	v_lshl_add_u64 v[144:145], s[30:31], 0, v[136:137]
	v_lshl_add_u64 v[146:147], s[30:31], 0, v[138:139]
	s_addc_u32 s49, s35, 0
	s_mov_b32 s51, -2
	s_mov_b64 s[34:35], 0
	s_waitcnt lgkmcnt(0)
	ds_read_b128 v[158:161], v153
	ds_read_b128 v[162:165], v153 offset:1024
	ds_read_b128 v[166:169], v153 offset:2048
	ds_read_b128 v[170:173], v153 offset:3072
	ds_read_b128 v[174:177], v154
	ds_read_b128 v[178:181], v154 offset:1024
	ds_read_b128 v[182:185], v154 offset:2048
	ds_read_b128 v[188:191], v154 offset:3072
	s_add_u32 s36, s30, s34
	s_addc_u32 s37, s31, s35
	s_add_u32 s38, s36, 0x100
	s_addc_u32 s39, s37, 0
	s_add_u32 s36, s48, s34
	s_addc_u32 s37, s49, s35
	s_cmpk_eq_i32 s34, 0xf00
	s_cselect_b32 s37, s21, s37
	s_cselect_b32 s36, s47, s36
	s_cselect_b32 s39, s23, s39
	s_cselect_b32 s38, s29, s38
	v_lshl_add_u64 v[148:149], v[146:147], 0, s[34:35]
	v_lshl_add_u64 v[186:187], v[148:149], 0, s[14:15]
	s_add_i32 m0, s3, 0x8000
	ds_read_b128 v[192:195], v155
	ds_read_b128 v[196:199], v155 offset:1024
	ds_read_b128 v[200:203], v155 offset:2048
	ds_read_b128 v[204:207], v155 offset:3072
	ds_read_b128 v[208:211], v155 offset:4096
	ds_read_b128 v[212:215], v155 offset:5120
	ds_read_b128 v[216:219], v155 offset:6144
	ds_read_b128 v[220:223], v155 offset:7168
	global_load_lds_dwordx4 v[186:187], off
	v_lshl_add_u64 v[186:187], v[144:145], 0, s[34:35]
	v_lshl_add_u64 v[224:225], v[186:187], 0, s[14:15]
	s_add_i32 m0, s3, 0xa000
	v_lshl_add_u64 v[148:149], v[148:149], 0, s[16:17]
	global_load_lds_dwordx4 v[224:225], off
	s_add_i32 m0, s3, 0xc000
	s_nop 0
	global_load_lds_dwordx4 v[148:149], off
	v_lshl_add_u64 v[148:149], v[186:187], 0, s[16:17]
	s_add_i32 m0, s3, 0xe000
	s_nop 0
	global_load_lds_dwordx4 v[148:149], off
	s_waitcnt vmcnt(8)
	s_waitcnt lgkmcnt(0)
	s_barrier
	s_setprio 3
	v_mfma_f32_16x16x32_bf16 v[124:127], v[158:161], v[192:195], 0
	v_mfma_f32_16x16x32_bf16 v[120:123], v[166:169], v[192:195], 0
	v_mfma_f32_16x16x32_bf16 v[108:111], v[158:161], v[200:203], 0
	v_mfma_f32_16x16x32_bf16 v[104:107], v[166:169], v[200:203], 0
	v_mfma_f32_16x16x32_bf16 v[92:95], v[158:161], v[208:211], 0
	v_mfma_f32_16x16x32_bf16 v[88:91], v[166:169], v[208:211], 0
	v_mfma_f32_16x16x32_bf16 v[76:79], v[158:161], v[216:219], 0
	v_mfma_f32_16x16x32_bf16 v[72:75], v[166:169], v[216:219], 0
	v_mfma_f32_16x16x32_bf16 v[124:127], v[162:165], v[196:199], v[124:127]
	v_mfma_f32_16x16x32_bf16 v[120:123], v[170:173], v[196:199], v[120:123]
	v_mfma_f32_16x16x32_bf16 v[108:111], v[162:165], v[204:207], v[108:111]
	v_mfma_f32_16x16x32_bf16 v[104:107], v[170:173], v[204:207], v[104:107]
	v_mfma_f32_16x16x32_bf16 v[92:95], v[162:165], v[212:215], v[92:95]
	v_mfma_f32_16x16x32_bf16 v[88:91], v[170:173], v[212:215], v[88:91]
	v_mfma_f32_16x16x32_bf16 v[76:79], v[162:165], v[220:223], v[76:79]
	v_mfma_f32_16x16x32_bf16 v[72:75], v[170:173], v[220:223], v[72:75]
	s_setprio 0
	s_setprio 3
	v_mfma_f32_16x16x32_bf16 v[116:119], v[174:177], v[192:195], 0
	v_mfma_f32_16x16x32_bf16 v[112:115], v[182:185], v[192:195], 0
	v_mfma_f32_16x16x32_bf16 v[100:103], v[174:177], v[200:203], 0
	v_mfma_f32_16x16x32_bf16 v[96:99], v[182:185], v[200:203], 0
	v_mfma_f32_16x16x32_bf16 v[84:87], v[174:177], v[208:211], 0
	v_mfma_f32_16x16x32_bf16 v[80:83], v[182:185], v[208:211], 0
	v_mfma_f32_16x16x32_bf16 v[68:71], v[174:177], v[216:219], 0
	v_mfma_f32_16x16x32_bf16 v[64:67], v[182:185], v[216:219], 0
	v_mfma_f32_16x16x32_bf16 v[116:119], v[178:181], v[196:199], v[116:119]
	v_mfma_f32_16x16x32_bf16 v[112:115], v[188:191], v[196:199], v[112:115]
	v_mfma_f32_16x16x32_bf16 v[100:103], v[178:181], v[204:207], v[100:103]
	v_mfma_f32_16x16x32_bf16 v[96:99], v[188:191], v[204:207], v[96:99]
	v_mfma_f32_16x16x32_bf16 v[84:87], v[178:181], v[212:215], v[84:87]
	v_mfma_f32_16x16x32_bf16 v[80:83], v[188:191], v[212:215], v[80:83]
	v_mfma_f32_16x16x32_bf16 v[68:71], v[178:181], v[220:223], v[68:71]
	v_mfma_f32_16x16x32_bf16 v[64:67], v[188:191], v[220:223], v[64:67]
	s_setprio 0
	s_barrier
	s_add_i32 s62, s44, s2
	v_lshl_add_u64 v[148:149], s[36:37], 0, v[130:131]
	s_mov_b32 m0, s62
	ds_read_b128 v[192:195], v155 offset:16384
	ds_read_b128 v[196:199], v155 offset:17408
	ds_read_b128 v[200:203], v155 offset:18432
	ds_read_b128 v[204:207], v155 offset:19456
	ds_read_b128 v[208:211], v155 offset:20480
	ds_read_b128 v[212:215], v155 offset:21504
	ds_read_b128 v[216:219], v155 offset:22528
	ds_read_b128 v[220:223], v155 offset:23552
	global_load_lds_dwordx4 v[148:149], off
	s_add_i32 m0, s62, 0x2000
	s_add_u32 s62, s36, 0x80000
	v_lshl_add_u64 v[186:187], s[36:37], 0, v[134:135]
	s_addc_u32 s63, s37, 0
	s_add_i32 s64, s45, s2
	global_load_lds_dwordx4 v[186:187], off
	v_lshl_add_u64 v[224:225], s[62:63], 0, v[130:131]
	s_mov_b32 m0, s64
	s_nop 0
	global_load_lds_dwordx4 v[224:225], off
	v_lshl_add_u64 v[224:225], s[62:63], 0, v[134:135]
	s_add_i32 m0, s64, 0x2000
	s_nop 0
	global_load_lds_dwordx4 v[224:225], off
	s_waitcnt vmcnt(6)
	s_waitcnt lgkmcnt(0)
	s_barrier
; #define PG8_STAGE(bufoff, gbase, voff) do { _Pragma("unroll") for (int _i = 0; _i < 2; ++_i) \
;         __builtin_amdgcn_global_load_lds((const unsigned*)((const char*)(gbase) + (voff)[_i]), (LAS unsigned*)(lds + (bufoff) + ldsw + _i * 8192), 16, 0, 0); } while (0)
; #define PG8_LDA(dst, b, h) do { _Pragma("unroll") for (int m = 0; m < 4; ++m) _Pragma("unroll") for (int k = 0; k < 2; ++k) dst[m][k] = *(const LAS bf16x8*)(lds + PG8_SA(b, h) + aoff + m * 2048 + k * 1024); } while (0)
; #define PG8_LDB(dst, b, h) do { _Pragma("unroll") for (int n = 0; n < 2; ++n) _Pragma("unroll") for (int k = 0; k < 2; ++k) dst[n][k] = *(const LAS bf16x8*)(lds + PG8_SB(b, h) + boff + n * 2048 + k * 1024); } while (0)
; #define PG8_MMA(ai, bj, At, Bt) do { __builtin_amdgcn_s_setprio(3); _Pragma("unroll") for (int m = 0; m < 4; ++m) _Pragma("unroll") for (int n = 0; n < 2; ++n) _Pragma("unroll") for (int k = 0; k < 2; ++k) \
;         acc[ai][bj][m][n] = __builtin_amdgcn_mfma_f32_16x16x32_bf16(Bt[n][k], At[m][k], acc[ai][bj][m][n], 0, 0, 0); __builtin_amdgcn_s_setprio(0); } while (0)
; #define PG8_WAIT_V(n) asm volatile("s_waitcnt vmcnt(" #n ")" ::: "memory")
; #define PG8_WAIT_L(n) asm volatile("s_waitcnt lgkmcnt(" #n ")" ::: "memory")
; #define PG8_BAR __builtin_amdgcn_s_barrier()
; #define PG8_SCHED __builtin_amdgcn_sched_barrier(0)
; template <class Epi, class Sched>
; __device__ __forceinline__ void gemm_phase(LAS unsigned char* lds, const Gemm g, const Sched& S, const Epi& E, int tid_in) {
;     ...
;             PG8_WAIT_V(6); PG8_WAIT_L(0); PG8_BAR; PG8_MMA(1, 0, At, B0); PG8_MMA(1, 1, At, B1); PG8_BAR; PG8_SCHED;
;             PG8_LDB(B0, 1, 0); PG8_LDB(B1, 1, 1); PG8_SCHED; PG8_LDA(At, 1, 0); PG8_STAGE(PG8_SA(0, 0), a2, voffA); PG8_STAGE(PG8_SA(0, 1), a2 + hstep, voffA);
;             PG8_WAIT_V(8); PG8_WAIT_L(0); PG8_BAR; PG8_MMA(0, 0, At, B0); PG8_MMA(0, 1, At, B1); PG8_BAR; PG8_SCHED;
	s_setprio 3
	v_mfma_f32_16x16x32_bf16 v[60:63], v[158:161], v[192:195], 0
	v_mfma_f32_16x16x32_bf16 v[56:59], v[166:169], v[192:195], 0
	v_mfma_f32_16x16x32_bf16 v[44:47], v[158:161], v[200:203], 0
	v_mfma_f32_16x16x32_bf16 v[40:43], v[166:169], v[200:203], 0
	v_mfma_f32_16x16x32_bf16 v[28:31], v[158:161], v[208:211], 0
	v_mfma_f32_16x16x32_bf16 v[24:27], v[166:169], v[208:211], 0
	v_mfma_f32_16x16x32_bf16 v[12:15], v[158:161], v[216:219], 0
	v_mfma_f32_16x16x32_bf16 v[8:11], v[166:169], v[216:219], 0
	v_mfma_f32_16x16x32_bf16 v[60:63], v[162:165], v[196:199], v[60:63]
	v_mfma_f32_16x16x32_bf16 v[56:59], v[170:173], v[196:199], v[56:59]
	v_mfma_f32_16x16x32_bf16 v[44:47], v[162:165], v[204:207], v[44:47]
	v_mfma_f32_16x16x32_bf16 v[40:43], v[170:173], v[204:207], v[40:43]
	v_mfma_f32_16x16x32_bf16 v[28:31], v[162:165], v[212:215], v[28:31]
	v_mfma_f32_16x16x32_bf16 v[24:27], v[170:173], v[212:215], v[24:27]
	v_mfma_f32_16x16x32_bf16 v[12:15], v[162:165], v[220:223], v[12:15]
	v_mfma_f32_16x16x32_bf16 v[8:11], v[170:173], v[220:223], v[8:11]
	s_setprio 0
	s_setprio 3
	v_mfma_f32_16x16x32_bf16 v[52:55], v[174:177], v[192:195], 0
	v_mfma_f32_16x16x32_bf16 v[48:51], v[182:185], v[192:195], 0
	v_mfma_f32_16x16x32_bf16 v[36:39], v[174:177], v[200:203], 0
	v_mfma_f32_16x16x32_bf16 v[32:35], v[182:185], v[200:203], 0
	v_mfma_f32_16x16x32_bf16 v[20:23], v[174:177], v[208:211], 0
	v_mfma_f32_16x16x32_bf16 v[16:19], v[182:185], v[208:211], 0
	v_mfma_f32_16x16x32_bf16 v[4:7], v[174:177], v[216:219], 0
	v_mfma_f32_16x16x32_bf16 v[0:3], v[182:185], v[216:219], 0
	v_mfma_f32_16x16x32_bf16 v[52:55], v[178:181], v[196:199], v[52:55]
	v_mfma_f32_16x16x32_bf16 v[48:51], v[188:191], v[196:199], v[48:51]
	v_mfma_f32_16x16x32_bf16 v[36:39], v[178:181], v[204:207], v[36:39]
	v_mfma_f32_16x16x32_bf16 v[32:35], v[188:191], v[204:207], v[32:35]
	v_mfma_f32_16x16x32_bf16 v[20:23], v[178:181], v[212:215], v[20:23]
	v_mfma_f32_16x16x32_bf16 v[16:19], v[188:191], v[212:215], v[16:19]
	v_mfma_f32_16x16x32_bf16 v[4:7], v[178:181], v[220:223], v[4:7]
	v_mfma_f32_16x16x32_bf16 v[0:3], v[188:191], v[220:223], v[0:3]
	s_setprio 0
	s_barrier
	s_add_i32 s62, 0, 0x18000
	v_add_u32_e32 v157, s62, v151
	s_add_i32 s63, 0, 0x1c000
	ds_read_b128 v[158:161], v157
	ds_read_b128 v[162:165], v157 offset:1024
	ds_read_b128 v[166:169], v157 offset:2048
	ds_read_b128 v[170:173], v157 offset:3072
	v_add_u32_e32 v157, s63, v151
	ds_read_b128 v[174:177], v157
	ds_read_b128 v[178:181], v157 offset:1024
	ds_read_b128 v[182:185], v157 offset:2048
	ds_read_b128 v[188:191], v157 offset:3072
	s_mov_b32 m0, s3
	v_lshl_add_u64 v[224:225], s[38:39], 0, v[128:129]
	ds_read_b128 v[192:195], v155 offset:32768
	ds_read_b128 v[196:199], v155 offset:33792
	ds_read_b128 v[200:203], v155 offset:34816
	ds_read_b128 v[204:207], v155 offset:35840
	ds_read_b128 v[208:211], v155 offset:36864
	ds_read_b128 v[212:215], v155 offset:37888
	ds_read_b128 v[216:219], v155 offset:38912
	ds_read_b128 v[220:223], v155 offset:39936
	global_load_lds_dwordx4 v[224:225], off
	v_lshl_add_u64 v[224:225], s[38:39], 0, v[132:133]
	s_add_u32 s38, s38, 0x80000
	s_mov_b32 m0, s40
	s_addc_u32 s39, s39, 0
	global_load_lds_dwordx4 v[224:225], off
	v_lshl_add_u64 v[224:225], s[38:39], 0, v[128:129]
	s_mov_b32 m0, s41
	s_nop 0
	global_load_lds_dwordx4 v[224:225], off
	v_lshl_add_u64 v[224:225], s[38:39], 0, v[132:133]
	s_mov_b32 m0, s42
	s_nop 0
	global_load_lds_dwordx4 v[224:225], off
	s_waitcnt vmcnt(8)
	s_waitcnt lgkmcnt(0)
	s_barrier
	s_setprio 3
	v_mfma_f32_16x16x32_bf16 v[124:127], v[158:161], v[192:195], v[124:127]
	v_mfma_f32_16x16x32_bf16 v[120:123], v[166:169], v[192:195], v[120:123]
	v_mfma_f32_16x16x32_bf16 v[108:111], v[158:161], v[200:203], v[108:111]
	v_mfma_f32_16x16x32_bf16 v[104:107], v[166:169], v[200:203], v[104:107]
	v_mfma_f32_16x16x32_bf16 v[92:95], v[158:161], v[208:211], v[92:95]
	v_mfma_f32_16x16x32_bf16 v[88:91], v[166:169], v[208:211], v[88:91]
	v_mfma_f32_16x16x32_bf16 v[76:79], v[158:161], v[216:219], v[76:79]
	v_mfma_f32_16x16x32_bf16 v[72:75], v[166:169], v[216:219], v[72:75]
	v_mfma_f32_16x16x32_bf16 v[124:127], v[162:165], v[196:199], v[124:127]
	v_mfma_f32_16x16x32_bf16 v[120:123], v[170:173], v[196:199], v[120:123]
	v_mfma_f32_16x16x32_bf16 v[108:111], v[162:165], v[204:207], v[108:111]
	v_mfma_f32_16x16x32_bf16 v[104:107], v[170:173], v[204:207], v[104:107]
	v_mfma_f32_16x16x32_bf16 v[92:95], v[162:165], v[212:215], v[92:95]
	v_mfma_f32_16x16x32_bf16 v[88:91], v[170:173], v[212:215], v[88:91]
	v_mfma_f32_16x16x32_bf16 v[76:79], v[162:165], v[220:223], v[76:79]
	v_mfma_f32_16x16x32_bf16 v[72:75], v[170:173], v[220:223], v[72:75]
	s_setprio 0
	s_setprio 3
	v_mfma_f32_16x16x32_bf16 v[116:119], v[174:177], v[192:195], v[116:119]
	v_mfma_f32_16x16x32_bf16 v[112:115], v[182:185], v[192:195], v[112:115]
	v_mfma_f32_16x16x32_bf16 v[100:103], v[174:177], v[200:203], v[100:103]
	v_mfma_f32_16x16x32_bf16 v[96:99], v[182:185], v[200:203], v[96:99]
	v_mfma_f32_16x16x32_bf16 v[84:87], v[174:177], v[208:211], v[84:87]
	v_mfma_f32_16x16x32_bf16 v[80:83], v[182:185], v[208:211], v[80:83]
	v_mfma_f32_16x16x32_bf16 v[68:71], v[174:177], v[216:219], v[68:71]
	v_mfma_f32_16x16x32_bf16 v[64:67], v[182:185], v[216:219], v[64:67]
	v_mfma_f32_16x16x32_bf16 v[116:119], v[178:181], v[196:199], v[116:119]
	v_mfma_f32_16x16x32_bf16 v[112:115], v[188:191], v[196:199], v[112:115]
	v_mfma_f32_16x16x32_bf16 v[100:103], v[178:181], v[204:207], v[100:103]
	v_mfma_f32_16x16x32_bf16 v[96:99], v[188:191], v[204:207], v[96:99]
	v_mfma_f32_16x16x32_bf16 v[84:87], v[178:181], v[212:215], v[84:87]
	v_mfma_f32_16x16x32_bf16 v[80:83], v[188:191], v[212:215], v[80:83]
	v_mfma_f32_16x16x32_bf16 v[68:71], v[178:181], v[220:223], v[68:71]
	v_mfma_f32_16x16x32_bf16 v[64:67], v[188:191], v[220:223], v[64:67]
	s_setprio 0
	s_barrier
; #define PG8_STAGE(bufoff, gbase, voff) do { _Pragma("unroll") for (int _i = 0; _i < 2; ++_i) \
;         __builtin_amdgcn_global_load_lds((const unsigned*)((const char*)(gbase) + (voff)[_i]), (LAS unsigned*)(lds + (bufoff) + ldsw + _i * 8192), 16, 0, 0); } while (0)
; #define PG8_LDA(dst, b, h) do { _Pragma("unroll") for (int m = 0; m < 4; ++m) _Pragma("unroll") for (int k = 0; k < 2; ++k) dst[m][k] = *(const LAS bf16x8*)(lds + PG8_SA(b, h) + aoff + m * 2048 + k * 1024); } while (0)
; #define PG8_LDB(dst, b, h) do { _Pragma("unroll") for (int n = 0; n < 2; ++n) _Pragma("unroll") for (int k = 0; k < 2; ++k) dst[n][k] = *(const LAS bf16x8*)(lds + PG8_SB(b, h) + boff + n * 2048 + k * 1024); } while (0)
; #define PG8_MMA(ai, bj, At, Bt) do { __builtin_amdgcn_s_setprio(3); _Pragma("unroll") for (int m = 0; m < 4; ++m) _Pragma("unroll") for (int n = 0; n < 2; ++n) _Pragma("unroll") for (int k = 0; k < 2; ++k) \
;         acc[ai][bj][m][n] = __builtin_amdgcn_mfma_f32_16x16x32_bf16(Bt[n][k], At[m][k], acc[ai][bj][m][n], 0, 0, 0); __builtin_amdgcn_s_setprio(0); } while (0)
; #define PG8_WAIT_V(n) asm volatile("s_waitcnt vmcnt(" #n ")" ::: "memory")
; #define PG8_BAR __builtin_amdgcn_s_barrier()
; template <class Epi, class Sched>
; __device__ __forceinline__ void gemm_phase(LAS unsigned char* lds, const Gemm g, const Sched& S, const Epi& E, int tid_in) {
;     ...
;             PG8_LDB(B0, 0, 0); PG8_LDB(B1, 0, 1); PG8_SCHED; PG8_LDA(At, 0, 0); PG8_STAGE(PG8_SA(1, 0), a1, voffA); PG8_STAGE(PG8_SA(1, 1), a1 + hstep, voffA);
;             PG8_WAIT_V(8); PG8_WAIT_L(0); PG8_BAR; PG8_MMA(0, 0, At, B0); PG8_MMA(0, 1, At, B1); PG8_BAR; PG8_SCHED;
;             PG8_LDA(At, 0, 1); PG8_STAGE(PG8_SB(0, 0), b2, voffB); PG8_STAGE(PG8_SB(0, 1), b2 + hstep, voffB);
;             PG8_WAIT_V(6); PG8_WAIT_L(0); PG8_BAR; PG8_MMA(1, 0, At, B0); PG8_MMA(1, 1, At, B1); PG8_BAR; PG8_SCHED;
;             PG8_LDB(B0, 1, 0); PG8_LDB(B1, 1, 1); PG8_SCHED; PG8_LDA(At, 1, 0); PG8_STAGE(PG8_SA(0, 0), a2, voffA); PG8_STAGE(PG8_SA(0, 1), a2 + hstep, voffA);
;             PG8_WAIT_V(8); PG8_WAIT_L(0); PG8_BAR; PG8_MMA(0, 0, At, B0); PG8_MMA(0, 1, At, B1); PG8_BAR; PG8_SCHED;
;             PG8_LDA(At, 1, 1); PG8_STAGE(PG8_SB(1, 0), b3, voffB); PG8_STAGE(PG8_SB(1, 1), b3 + hstep, voffB);
;             PG8_WAIT_V(6); PG8_WAIT_L(0); PG8_BAR; PG8_MMA(1, 0, At, B0); PG8_MMA(1, 1, At, B1); PG8_BAR; PG8_SCHED;
	s_add_i32 s38, s62, s2
	v_lshl_add_u64 v[148:149], v[148:149], 0, s[14:15]
	s_mov_b32 m0, s38
	ds_read_b128 v[192:195], v155 offset:49152
	ds_read_b128 v[196:199], v155 offset:50176
	ds_read_b128 v[200:203], v155 offset:51200
	ds_read_b128 v[204:207], v155 offset:52224
	ds_read_b128 v[208:211], v155 offset:53248
	ds_read_b128 v[212:215], v155 offset:54272
	ds_read_b128 v[216:219], v155 offset:55296
	ds_read_b128 v[220:223], v155 offset:56320
	global_load_lds_dwordx4 v[148:149], off
	s_add_i32 m0, s38, 0x2000
	s_add_u32 s36, s36, 0x80080
	v_lshl_add_u64 v[148:149], v[186:187], 0, s[14:15]
	s_addc_u32 s37, s37, 0
	s_add_i32 s38, s63, s2
	global_load_lds_dwordx4 v[148:149], off
	v_lshl_add_u64 v[148:149], s[36:37], 0, v[130:131]
	s_mov_b32 m0, s38
	s_nop 0
	global_load_lds_dwordx4 v[148:149], off
	v_lshl_add_u64 v[148:149], s[36:37], 0, v[134:135]
	s_add_i32 m0, s38, 0x2000
	s_nop 0
	global_load_lds_dwordx4 v[148:149], off
	s_waitcnt vmcnt(6)
	s_waitcnt lgkmcnt(0)
	s_barrier
	s_setprio 3
	v_mfma_f32_16x16x32_bf16 v[60:63], v[158:161], v[192:195], v[60:63]
	v_mfma_f32_16x16x32_bf16 v[56:59], v[166:169], v[192:195], v[56:59]
	v_mfma_f32_16x16x32_bf16 v[44:47], v[158:161], v[200:203], v[44:47]
	v_mfma_f32_16x16x32_bf16 v[40:43], v[166:169], v[200:203], v[40:43]
	v_mfma_f32_16x16x32_bf16 v[28:31], v[158:161], v[208:211], v[28:31]
	v_mfma_f32_16x16x32_bf16 v[24:27], v[166:169], v[208:211], v[24:27]
	v_mfma_f32_16x16x32_bf16 v[12:15], v[158:161], v[216:219], v[12:15]
	v_mfma_f32_16x16x32_bf16 v[8:11], v[166:169], v[216:219], v[8:11]
	v_mfma_f32_16x16x32_bf16 v[60:63], v[162:165], v[196:199], v[60:63]
	v_mfma_f32_16x16x32_bf16 v[56:59], v[170:173], v[196:199], v[56:59]
	v_mfma_f32_16x16x32_bf16 v[44:47], v[162:165], v[204:207], v[44:47]
	v_mfma_f32_16x16x32_bf16 v[40:43], v[170:173], v[204:207], v[40:43]
	v_mfma_f32_16x16x32_bf16 v[28:31], v[162:165], v[212:215], v[28:31]
	v_mfma_f32_16x16x32_bf16 v[24:27], v[170:173], v[212:215], v[24:27]
	v_mfma_f32_16x16x32_bf16 v[12:15], v[162:165], v[220:223], v[12:15]
	v_mfma_f32_16x16x32_bf16 v[8:11], v[170:173], v[220:223], v[8:11]
	s_setprio 0
	s_setprio 3
	v_mfma_f32_16x16x32_bf16 v[52:55], v[174:177], v[192:195], v[52:55]
	v_mfma_f32_16x16x32_bf16 v[48:51], v[182:185], v[192:195], v[48:51]
	v_mfma_f32_16x16x32_bf16 v[36:39], v[174:177], v[200:203], v[36:39]
	v_mfma_f32_16x16x32_bf16 v[32:35], v[182:185], v[200:203], v[32:35]
	v_mfma_f32_16x16x32_bf16 v[20:23], v[174:177], v[208:211], v[20:23]
	v_mfma_f32_16x16x32_bf16 v[16:19], v[182:185], v[208:211], v[16:19]
	v_mfma_f32_16x16x32_bf16 v[4:7], v[174:177], v[216:219], v[4:7]
	v_mfma_f32_16x16x32_bf16 v[0:3], v[182:185], v[216:219], v[0:3]
	v_mfma_f32_16x16x32_bf16 v[52:55], v[178:181], v[196:199], v[52:55]
	v_mfma_f32_16x16x32_bf16 v[48:51], v[188:191], v[196:199], v[48:51]
	v_mfma_f32_16x16x32_bf16 v[36:39], v[178:181], v[204:207], v[36:39]
	v_mfma_f32_16x16x32_bf16 v[32:35], v[188:191], v[204:207], v[32:35]
	v_mfma_f32_16x16x32_bf16 v[20:23], v[178:181], v[212:215], v[20:23]
	v_mfma_f32_16x16x32_bf16 v[16:19], v[188:191], v[212:215], v[16:19]
	v_mfma_f32_16x16x32_bf16 v[4:7], v[178:181], v[220:223], v[4:7]
	v_mfma_f32_16x16x32_bf16 v[0:3], v[188:191], v[220:223], v[0:3]
	s_setprio 0
	s_barrier
	s_add_i32 s51, s51, 2
	s_add_u32 s34, s34, 0x100
	s_addc_u32 s35, s35, 0
	s_cmp_gt_u32 s51, 29
	s_cbranch_scc0 .LBB0_1009
	s_branch .Lpeel_exit_4
.LBB0_1009:
	ds_read_b128 v[158:161], v153
	ds_read_b128 v[162:165], v153 offset:1024
	ds_read_b128 v[166:169], v153 offset:2048
	ds_read_b128 v[170:173], v153 offset:3072
	ds_read_b128 v[174:177], v154
	ds_read_b128 v[178:181], v154 offset:1024
	ds_read_b128 v[182:185], v154 offset:2048
	ds_read_b128 v[188:191], v154 offset:3072
	s_add_u32 s36, s30, s34
	s_addc_u32 s37, s31, s35
	s_add_u32 s38, s36, 0x100
	s_addc_u32 s39, s37, 0
	s_add_u32 s36, s48, s34
	s_addc_u32 s37, s49, s35
	s_cmpk_eq_i32 s34, 0xf00
	s_cselect_b32 s37, s21, s37
	s_cselect_b32 s36, s47, s36
	s_cselect_b32 s39, s23, s39
	s_cselect_b32 s38, s29, s38
	v_lshl_add_u64 v[148:149], v[146:147], 0, s[34:35]
	v_lshl_add_u64 v[186:187], v[148:149], 0, s[14:15]
	s_add_i32 m0, s3, 0x8000
	ds_read_b128 v[192:195], v155
	ds_read_b128 v[196:199], v155 offset:1024
	ds_read_b128 v[200:203], v155 offset:2048
	ds_read_b128 v[204:207], v155 offset:3072
	ds_read_b128 v[208:211], v155 offset:4096
	ds_read_b128 v[212:215], v155 offset:5120
	ds_read_b128 v[216:219], v155 offset:6144
	ds_read_b128 v[220:223], v155 offset:7168
	global_load_lds_dwordx4 v[186:187], off
	v_lshl_add_u64 v[186:187], v[144:145], 0, s[34:35]
	v_lshl_add_u64 v[224:225], v[186:187], 0, s[14:15]
	s_add_i32 m0, s3, 0xa000
	v_lshl_add_u64 v[148:149], v[148:149], 0, s[16:17]
	global_load_lds_dwordx4 v[224:225], off
	s_add_i32 m0, s3, 0xc000
	s_nop 0
	global_load_lds_dwordx4 v[148:149], off
	v_lshl_add_u64 v[148:149], v[186:187], 0, s[16:17]
	s_add_i32 m0, s3, 0xe000
	s_nop 0
	global_load_lds_dwordx4 v[148:149], off
	s_waitcnt vmcnt(8)
	s_waitcnt lgkmcnt(0)
	s_barrier
; #define PG8_STAGE(bufoff, gbase, voff) do { _Pragma("unroll") for (int _i = 0; _i < 2; ++_i) \
;         __builtin_amdgcn_global_load_lds((const unsigned*)((const char*)(gbase) + (voff)[_i]), (LAS unsigned*)(lds + (bufoff) + ldsw + _i * 8192), 16, 0, 0); } while (0)
; #define PG8_LDA(dst, b, h) do { _Pragma("unroll") for (int m = 0; m < 4; ++m) _Pragma("unroll") for (int k = 0; k < 2; ++k) dst[m][k] = *(const LAS bf16x8*)(lds + PG8_SA(b, h) + aoff + m * 2048 + k * 1024); } while (0)
; #define PG8_MMA(ai, bj, At, Bt) do { __builtin_amdgcn_s_setprio(3); _Pragma("unroll") for (int m = 0; m < 4; ++m) _Pragma("unroll") for (int n = 0; n < 2; ++n) _Pragma("unroll") for (int k = 0; k < 2; ++k) \
;         acc[ai][bj][m][n] = __builtin_amdgcn_mfma_f32_16x16x32_bf16(Bt[n][k], At[m][k], acc[ai][bj][m][n], 0, 0, 0); __builtin_amdgcn_s_setprio(0); } while (0)
; #define PG8_WAIT_V(n) asm volatile("s_waitcnt vmcnt(" #n ")" ::: "memory")
; #define PG8_WAIT_L(n) asm volatile("s_waitcnt lgkmcnt(" #n ")" ::: "memory")
; #define PG8_BAR __builtin_amdgcn_s_barrier()
; #define PG8_SCHED __builtin_amdgcn_sched_barrier(0)
; template <class Epi, class Sched>
; __device__ __forceinline__ void gemm_phase(LAS unsigned char* lds, const Gemm g, const Sched& S, const Epi& E, int tid_in) {
;     ...
;             PG8_WAIT_V(8); PG8_WAIT_L(0); PG8_BAR; PG8_MMA(0, 0, At, B0); PG8_MMA(0, 1, At, B1); PG8_BAR; PG8_SCHED;
;             PG8_LDA(At, 0, 1); PG8_STAGE(PG8_SB(0, 0), b2, voffB); PG8_STAGE(PG8_SB(0, 1), b2 + hstep, voffB);
;             PG8_WAIT_V(6); PG8_WAIT_L(0); PG8_BAR; PG8_MMA(1, 0, At, B0); PG8_MMA(1, 1, At, B1); PG8_BAR; PG8_SCHED;
	s_setprio 3
	v_mfma_f32_16x16x32_bf16 v[124:127], v[158:161], v[192:195], v[124:127]
	v_mfma_f32_16x16x32_bf16 v[120:123], v[166:169], v[192:195], v[120:123]
	v_mfma_f32_16x16x32_bf16 v[108:111], v[158:161], v[200:203], v[108:111]
	v_mfma_f32_16x16x32_bf16 v[104:107], v[166:169], v[200:203], v[104:107]
	v_mfma_f32_16x16x32_bf16 v[92:95], v[158:161], v[208:211], v[92:95]
	v_mfma_f32_16x16x32_bf16 v[88:91], v[166:169], v[208:211], v[88:91]
	v_mfma_f32_16x16x32_bf16 v[76:79], v[158:161], v[216:219], v[76:79]
	v_mfma_f32_16x16x32_bf16 v[72:75], v[166:169], v[216:219], v[72:75]
	v_mfma_f32_16x16x32_bf16 v[124:127], v[162:165], v[196:199], v[124:127]
	v_mfma_f32_16x16x32_bf16 v[120:123], v[170:173], v[196:199], v[120:123]
	v_mfma_f32_16x16x32_bf16 v[108:111], v[162:165], v[204:207], v[108:111]
	v_mfma_f32_16x16x32_bf16 v[104:107], v[170:173], v[204:207], v[104:107]
	v_mfma_f32_16x16x32_bf16 v[92:95], v[162:165], v[212:215], v[92:95]
	v_mfma_f32_16x16x32_bf16 v[88:91], v[170:173], v[212:215], v[88:91]
	v_mfma_f32_16x16x32_bf16 v[76:79], v[162:165], v[220:223], v[76:79]
	v_mfma_f32_16x16x32_bf16 v[72:75], v[170:173], v[220:223], v[72:75]
	s_setprio 0
	s_setprio 3
	v_mfma_f32_16x16x32_bf16 v[116:119], v[174:177], v[192:195], v[116:119]
	v_mfma_f32_16x16x32_bf16 v[112:115], v[182:185], v[192:195], v[112:115]
	v_mfma_f32_16x16x32_bf16 v[100:103], v[174:177], v[200:203], v[100:103]
	v_mfma_f32_16x16x32_bf16 v[96:99], v[182:185], v[200:203], v[96:99]
	v_mfma_f32_16x16x32_bf16 v[84:87], v[174:177], v[208:211], v[84:87]
	v_mfma_f32_16x16x32_bf16 v[80:83], v[182:185], v[208:211], v[80:83]
	v_mfma_f32_16x16x32_bf16 v[68:71], v[174:177], v[216:219], v[68:71]
	v_mfma_f32_16x16x32_bf16 v[64:67], v[182:185], v[216:219], v[64:67]
	v_mfma_f32_16x16x32_bf16 v[116:119], v[178:181], v[196:199], v[116:119]
	v_mfma_f32_16x16x32_bf16 v[112:115], v[188:191], v[196:199], v[112:115]
	v_mfma_f32_16x16x32_bf16 v[100:103], v[178:181], v[204:207], v[100:103]
	v_mfma_f32_16x16x32_bf16 v[96:99], v[188:191], v[204:207], v[96:99]
	v_mfma_f32_16x16x32_bf16 v[84:87], v[178:181], v[212:215], v[84:87]
	v_mfma_f32_16x16x32_bf16 v[80:83], v[188:191], v[212:215], v[80:83]
	v_mfma_f32_16x16x32_bf16 v[68:71], v[178:181], v[220:223], v[68:71]
	v_mfma_f32_16x16x32_bf16 v[64:67], v[188:191], v[220:223], v[64:67]
	s_setprio 0
	s_barrier
	s_add_i32 s62, s44, s2
	v_lshl_add_u64 v[148:149], s[36:37], 0, v[130:131]
	s_mov_b32 m0, s62
	ds_read_b128 v[192:195], v155 offset:16384
	ds_read_b128 v[196:199], v155 offset:17408
	ds_read_b128 v[200:203], v155 offset:18432
	ds_read_b128 v[204:207], v155 offset:19456
	ds_read_b128 v[208:211], v155 offset:20480
	ds_read_b128 v[212:215], v155 offset:21504
	ds_read_b128 v[216:219], v155 offset:22528
	ds_read_b128 v[220:223], v155 offset:23552
	global_load_lds_dwordx4 v[148:149], off
	s_add_i32 m0, s62, 0x2000
	s_add_u32 s62, s36, 0x80000
	v_lshl_add_u64 v[186:187], s[36:37], 0, v[134:135]
	s_addc_u32 s63, s37, 0
	s_add_i32 s64, s45, s2
	global_load_lds_dwordx4 v[186:187], off
	v_lshl_add_u64 v[224:225], s[62:63], 0, v[130:131]
	s_mov_b32 m0, s64
	s_nop 0
	global_load_lds_dwordx4 v[224:225], off
	v_lshl_add_u64 v[224:225], s[62:63], 0, v[134:135]
	s_add_i32 m0, s64, 0x2000
	s_nop 0
	global_load_lds_dwordx4 v[224:225], off
	s_waitcnt vmcnt(6)
	s_waitcnt lgkmcnt(0)
	s_barrier
	s_setprio 3
	v_mfma_f32_16x16x32_bf16 v[60:63], v[158:161], v[192:195], v[60:63]
	v_mfma_f32_16x16x32_bf16 v[56:59], v[166:169], v[192:195], v[56:59]
	v_mfma_f32_16x16x32_bf16 v[44:47], v[158:161], v[200:203], v[44:47]
	v_mfma_f32_16x16x32_bf16 v[40:43], v[166:169], v[200:203], v[40:43]
	v_mfma_f32_16x16x32_bf16 v[28:31], v[158:161], v[208:211], v[28:31]
	v_mfma_f32_16x16x32_bf16 v[24:27], v[166:169], v[208:211], v[24:27]
	v_mfma_f32_16x16x32_bf16 v[12:15], v[158:161], v[216:219], v[12:15]
	v_mfma_f32_16x16x32_bf16 v[8:11], v[166:169], v[216:219], v[8:11]
	v_mfma_f32_16x16x32_bf16 v[60:63], v[162:165], v[196:199], v[60:63]
	v_mfma_f32_16x16x32_bf16 v[56:59], v[170:173], v[196:199], v[56:59]
	v_mfma_f32_16x16x32_bf16 v[44:47], v[162:165], v[204:207], v[44:47]
	v_mfma_f32_16x16x32_bf16 v[40:43], v[170:173], v[204:207], v[40:43]
	v_mfma_f32_16x16x32_bf16 v[28:31], v[162:165], v[212:215], v[28:31]
	v_mfma_f32_16x16x32_bf16 v[24:27], v[170:173], v[212:215], v[24:27]
	v_mfma_f32_16x16x32_bf16 v[12:15], v[162:165], v[220:223], v[12:15]
	v_mfma_f32_16x16x32_bf16 v[8:11], v[170:173], v[220:223], v[8:11]
	s_setprio 0
	s_setprio 3
	v_mfma_f32_16x16x32_bf16 v[52:55], v[174:177], v[192:195], v[52:55]
	v_mfma_f32_16x16x32_bf16 v[48:51], v[182:185], v[192:195], v[48:51]
	v_mfma_f32_16x16x32_bf16 v[36:39], v[174:177], v[200:203], v[36:39]
	v_mfma_f32_16x16x32_bf16 v[32:35], v[182:185], v[200:203], v[32:35]
	v_mfma_f32_16x16x32_bf16 v[20:23], v[174:177], v[208:211], v[20:23]
	v_mfma_f32_16x16x32_bf16 v[16:19], v[182:185], v[208:211], v[16:19]
	v_mfma_f32_16x16x32_bf16 v[4:7], v[174:177], v[216:219], v[4:7]
	v_mfma_f32_16x16x32_bf16 v[0:3], v[182:185], v[216:219], v[0:3]
	v_mfma_f32_16x16x32_bf16 v[52:55], v[178:181], v[196:199], v[52:55]
	v_mfma_f32_16x16x32_bf16 v[48:51], v[188:191], v[196:199], v[48:51]
	v_mfma_f32_16x16x32_bf16 v[36:39], v[178:181], v[204:207], v[36:39]
	v_mfma_f32_16x16x32_bf16 v[32:35], v[188:191], v[204:207], v[32:35]
	v_mfma_f32_16x16x32_bf16 v[20:23], v[178:181], v[212:215], v[20:23]
	v_mfma_f32_16x16x32_bf16 v[16:19], v[188:191], v[212:215], v[16:19]
	v_mfma_f32_16x16x32_bf16 v[4:7], v[178:181], v[220:223], v[4:7]
	v_mfma_f32_16x16x32_bf16 v[0:3], v[188:191], v[220:223], v[0:3]
	s_setprio 0
	s_barrier
; #define PG8_STAGE(bufoff, gbase, voff) do { _Pragma("unroll") for (int _i = 0; _i < 2; ++_i) \
;         __builtin_amdgcn_global_load_lds((const unsigned*)((const char*)(gbase) + (voff)[_i]), (LAS unsigned*)(lds + (bufoff) + ldsw + _i * 8192), 16, 0, 0); } while (0)
; #define PG8_LDA(dst, b, h) do { _Pragma("unroll") for (int m = 0; m < 4; ++m) _Pragma("unroll") for (int k = 0; k < 2; ++k) dst[m][k] = *(const LAS bf16x8*)(lds + PG8_SA(b, h) + aoff + m * 2048 + k * 1024); } while (0)
; #define PG8_LDB(dst, b, h) do { _Pragma("unroll") for (int n = 0; n < 2; ++n) _Pragma("unroll") for (int k = 0; k < 2; ++k) dst[n][k] = *(const LAS bf16x8*)(lds + PG8_SB(b, h) + boff + n * 2048 + k * 1024); } while (0)
; #define PG8_MMA(ai, bj, At, Bt) do { __builtin_amdgcn_s_setprio(3); _Pragma("unroll") for (int m = 0; m < 4; ++m) _Pragma("unroll") for (int n = 0; n < 2; ++n) _Pragma("unroll") for (int k = 0; k < 2; ++k) \
;         acc[ai][bj][m][n] = __builtin_amdgcn_mfma_f32_16x16x32_bf16(Bt[n][k], At[m][k], acc[ai][bj][m][n], 0, 0, 0); __builtin_amdgcn_s_setprio(0); } while (0)
; #define PG8_WAIT_V(n) asm volatile("s_waitcnt vmcnt(" #n ")" ::: "memory")
; #define PG8_WAIT_L(n) asm volatile("s_waitcnt lgkmcnt(" #n ")" ::: "memory")
; #define PG8_BAR __builtin_amdgcn_s_barrier()
; #define PG8_SCHED __builtin_amdgcn_sched_barrier(0)
; template <class Epi, class Sched>
; __device__ __forceinline__ void gemm_phase(LAS unsigned char* lds, const Gemm g, const Sched& S, const Epi& E, int tid_in) {
;     ...
;             PG8_LDB(B0, 1, 0); PG8_LDB(B1, 1, 1); PG8_SCHED; PG8_LDA(At, 1, 0); PG8_STAGE(PG8_SA(0, 0), a2, voffA); PG8_STAGE(PG8_SA(0, 1), a2 + hstep, voffA);
;             PG8_WAIT_V(8); PG8_WAIT_L(0); PG8_BAR; PG8_MMA(0, 0, At, B0); PG8_MMA(0, 1, At, B1); PG8_BAR; PG8_SCHED;
;             PG8_LDA(At, 1, 1); PG8_STAGE(PG8_SB(1, 0), b3, voffB); PG8_STAGE(PG8_SB(1, 1), b3 + hstep, voffB);
;             PG8_WAIT_V(6); PG8_WAIT_L(0); PG8_BAR; PG8_MMA(1, 0, At, B0); PG8_MMA(1, 1, At, B1); PG8_BAR; PG8_SCHED;
	s_add_i32 s62, 0, 0x18000
	v_add_u32_e32 v157, s62, v151
	s_add_i32 s63, 0, 0x1c000
	ds_read_b128 v[158:161], v157
	ds_read_b128 v[162:165], v157 offset:1024
	ds_read_b128 v[166:169], v157 offset:2048
	ds_read_b128 v[170:173], v157 offset:3072
	v_add_u32_e32 v157, s63, v151
	ds_read_b128 v[174:177], v157
	ds_read_b128 v[178:181], v157 offset:1024
	ds_read_b128 v[182:185], v157 offset:2048
	ds_read_b128 v[188:191], v157 offset:3072
	s_mov_b32 m0, s3
	v_lshl_add_u64 v[224:225], s[38:39], 0, v[128:129]
	ds_read_b128 v[192:195], v155 offset:32768
	ds_read_b128 v[196:199], v155 offset:33792
	ds_read_b128 v[200:203], v155 offset:34816
	ds_read_b128 v[204:207], v155 offset:35840
	ds_read_b128 v[208:211], v155 offset:36864
	ds_read_b128 v[212:215], v155 offset:37888
	ds_read_b128 v[216:219], v155 offset:38912
	ds_read_b128 v[220:223], v155 offset:39936
	global_load_lds_dwordx4 v[224:225], off
	v_lshl_add_u64 v[224:225], s[38:39], 0, v[132:133]
	s_add_u32 s38, s38, 0x80000
	s_mov_b32 m0, s40
	s_addc_u32 s39, s39, 0
	global_load_lds_dwordx4 v[224:225], off
	v_lshl_add_u64 v[224:225], s[38:39], 0, v[128:129]
	s_mov_b32 m0, s41
	s_nop 0
	global_load_lds_dwordx4 v[224:225], off
	v_lshl_add_u64 v[224:225], s[38:39], 0, v[132:133]
	s_mov_b32 m0, s42
	s_nop 0
	global_load_lds_dwordx4 v[224:225], off
	s_waitcnt vmcnt(8)
	s_waitcnt lgkmcnt(0)
	s_barrier
	s_setprio 3
	v_mfma_f32_16x16x32_bf16 v[124:127], v[158:161], v[192:195], v[124:127]
	v_mfma_f32_16x16x32_bf16 v[120:123], v[166:169], v[192:195], v[120:123]
	v_mfma_f32_16x16x32_bf16 v[108:111], v[158:161], v[200:203], v[108:111]
	v_mfma_f32_16x16x32_bf16 v[104:107], v[166:169], v[200:203], v[104:107]
	v_mfma_f32_16x16x32_bf16 v[92:95], v[158:161], v[208:211], v[92:95]
	v_mfma_f32_16x16x32_bf16 v[88:91], v[166:169], v[208:211], v[88:91]
	v_mfma_f32_16x16x32_bf16 v[76:79], v[158:161], v[216:219], v[76:79]
	v_mfma_f32_16x16x32_bf16 v[72:75], v[166:169], v[216:219], v[72:75]
	v_mfma_f32_16x16x32_bf16 v[124:127], v[162:165], v[196:199], v[124:127]
	v_mfma_f32_16x16x32_bf16 v[120:123], v[170:173], v[196:199], v[120:123]
	v_mfma_f32_16x16x32_bf16 v[108:111], v[162:165], v[204:207], v[108:111]
	v_mfma_f32_16x16x32_bf16 v[104:107], v[170:173], v[204:207], v[104:107]
	v_mfma_f32_16x16x32_bf16 v[92:95], v[162:165], v[212:215], v[92:95]
	v_mfma_f32_16x16x32_bf16 v[88:91], v[170:173], v[212:215], v[88:91]
	v_mfma_f32_16x16x32_bf16 v[76:79], v[162:165], v[220:223], v[76:79]
	v_mfma_f32_16x16x32_bf16 v[72:75], v[170:173], v[220:223], v[72:75]
	s_setprio 0
	s_setprio 3
	v_mfma_f32_16x16x32_bf16 v[116:119], v[174:177], v[192:195], v[116:119]
	v_mfma_f32_16x16x32_bf16 v[112:115], v[182:185], v[192:195], v[112:115]
	v_mfma_f32_16x16x32_bf16 v[100:103], v[174:177], v[200:203], v[100:103]
	v_mfma_f32_16x16x32_bf16 v[96:99], v[182:185], v[200:203], v[96:99]
	v_mfma_f32_16x16x32_bf16 v[84:87], v[174:177], v[208:211], v[84:87]
	v_mfma_f32_16x16x32_bf16 v[80:83], v[182:185], v[208:211], v[80:83]
	v_mfma_f32_16x16x32_bf16 v[68:71], v[174:177], v[216:219], v[68:71]
	v_mfma_f32_16x16x32_bf16 v[64:67], v[182:185], v[216:219], v[64:67]
	v_mfma_f32_16x16x32_bf16 v[116:119], v[178:181], v[196:199], v[116:119]
	v_mfma_f32_16x16x32_bf16 v[112:115], v[188:191], v[196:199], v[112:115]
	v_mfma_f32_16x16x32_bf16 v[100:103], v[178:181], v[204:207], v[100:103]
	v_mfma_f32_16x16x32_bf16 v[96:99], v[188:191], v[204:207], v[96:99]
	v_mfma_f32_16x16x32_bf16 v[84:87], v[178:181], v[212:215], v[84:87]
	v_mfma_f32_16x16x32_bf16 v[80:83], v[188:191], v[212:215], v[80:83]
	v_mfma_f32_16x16x32_bf16 v[68:71], v[178:181], v[220:223], v[68:71]
	v_mfma_f32_16x16x32_bf16 v[64:67], v[188:191], v[220:223], v[64:67]
	s_setprio 0
	s_barrier
	s_add_i32 s38, s62, s2
	v_lshl_add_u64 v[148:149], v[148:149], 0, s[14:15]
	s_mov_b32 m0, s38
	ds_read_b128 v[192:195], v155 offset:49152
	ds_read_b128 v[196:199], v155 offset:50176
	ds_read_b128 v[200:203], v155 offset:51200
	ds_read_b128 v[204:207], v155 offset:52224
	ds_read_b128 v[208:211], v155 offset:53248
	ds_read_b128 v[212:215], v155 offset:54272
	ds_read_b128 v[216:219], v155 offset:55296
	ds_read_b128 v[220:223], v155 offset:56320
	global_load_lds_dwordx4 v[148:149], off
	s_add_i32 m0, s38, 0x2000
	s_add_u32 s36, s36, 0x80080
	v_lshl_add_u64 v[148:149], v[186:187], 0, s[14:15]
	s_addc_u32 s37, s37, 0
	s_add_i32 s38, s63, s2
	global_load_lds_dwordx4 v[148:149], off
	v_lshl_add_u64 v[148:149], s[36:37], 0, v[130:131]
	s_mov_b32 m0, s38
	s_nop 0
	global_load_lds_dwordx4 v[148:149], off
	v_lshl_add_u64 v[148:149], s[36:37], 0, v[134:135]
	s_add_i32 m0, s38, 0x2000
	s_nop 0
	global_load_lds_dwordx4 v[148:149], off
	s_waitcnt vmcnt(6)
	s_waitcnt lgkmcnt(0)
	s_barrier
	s_setprio 3
	v_mfma_f32_16x16x32_bf16 v[60:63], v[158:161], v[192:195], v[60:63]
	v_mfma_f32_16x16x32_bf16 v[56:59], v[166:169], v[192:195], v[56:59]
	v_mfma_f32_16x16x32_bf16 v[44:47], v[158:161], v[200:203], v[44:47]
	v_mfma_f32_16x16x32_bf16 v[40:43], v[166:169], v[200:203], v[40:43]
	v_mfma_f32_16x16x32_bf16 v[28:31], v[158:161], v[208:211], v[28:31]
	v_mfma_f32_16x16x32_bf16 v[24:27], v[166:169], v[208:211], v[24:27]
	v_mfma_f32_16x16x32_bf16 v[12:15], v[158:161], v[216:219], v[12:15]
	v_mfma_f32_16x16x32_bf16 v[8:11], v[166:169], v[216:219], v[8:11]
	v_mfma_f32_16x16x32_bf16 v[60:63], v[162:165], v[196:199], v[60:63]
	v_mfma_f32_16x16x32_bf16 v[56:59], v[170:173], v[196:199], v[56:59]
	v_mfma_f32_16x16x32_bf16 v[44:47], v[162:165], v[204:207], v[44:47]
	v_mfma_f32_16x16x32_bf16 v[40:43], v[170:173], v[204:207], v[40:43]
	v_mfma_f32_16x16x32_bf16 v[28:31], v[162:165], v[212:215], v[28:31]
	v_mfma_f32_16x16x32_bf16 v[24:27], v[170:173], v[212:215], v[24:27]
	v_mfma_f32_16x16x32_bf16 v[12:15], v[162:165], v[220:223], v[12:15]
	v_mfma_f32_16x16x32_bf16 v[8:11], v[170:173], v[220:223], v[8:11]
	s_setprio 0
	s_setprio 3
	v_mfma_f32_16x16x32_bf16 v[52:55], v[174:177], v[192:195], v[52:55]
	v_mfma_f32_16x16x32_bf16 v[48:51], v[182:185], v[192:195], v[48:51]
	v_mfma_f32_16x16x32_bf16 v[36:39], v[174:177], v[200:203], v[36:39]
	v_mfma_f32_16x16x32_bf16 v[32:35], v[182:185], v[200:203], v[32:35]
	v_mfma_f32_16x16x32_bf16 v[20:23], v[174:177], v[208:211], v[20:23]
	v_mfma_f32_16x16x32_bf16 v[16:19], v[182:185], v[208:211], v[16:19]
	v_mfma_f32_16x16x32_bf16 v[4:7], v[174:177], v[216:219], v[4:7]
	v_mfma_f32_16x16x32_bf16 v[0:3], v[182:185], v[216:219], v[0:3]
	v_mfma_f32_16x16x32_bf16 v[52:55], v[178:181], v[196:199], v[52:55]
	v_mfma_f32_16x16x32_bf16 v[48:51], v[188:191], v[196:199], v[48:51]
	v_mfma_f32_16x16x32_bf16 v[36:39], v[178:181], v[204:207], v[36:39]
	v_mfma_f32_16x16x32_bf16 v[32:35], v[188:191], v[204:207], v[32:35]
	v_mfma_f32_16x16x32_bf16 v[20:23], v[178:181], v[212:215], v[20:23]
	v_mfma_f32_16x16x32_bf16 v[16:19], v[188:191], v[212:215], v[16:19]
	v_mfma_f32_16x16x32_bf16 v[4:7], v[178:181], v[220:223], v[4:7]
	v_mfma_f32_16x16x32_bf16 v[0:3], v[188:191], v[220:223], v[0:3]
	s_setprio 0
	s_barrier
	s_add_i32 s51, s51, 2
	s_add_u32 s34, s34, 0x100
	s_addc_u32 s35, s35, 0
	s_cmp_gt_u32 s51, 29
	s_cbranch_scc0 .LBB0_1009
